# T21 pairing of the pg8 epilogues with whole-kernel liveness (gate epilogues now fully paired)
# speedup vs baseline: 1.0184x; 1.0016x over previous
.LBB0_648:
	ds_read_b128 v[2:5], v167
	ds_read_b128 v[6:9], v171
	ds_read_b128 v[10:13], v172
	ds_read_b128 v[14:17], v173
	s_add_u32 s30, s28, 0xfffe0080
	s_addc_u32 s31, s29, -1
	s_cmp_eq_u32 s68, 4
	s_cselect_b32 s35, s21, s31
	s_cselect_b32 s34, s62, s30
	s_cselect_b32 s31, s19, s65
	s_cselect_b32 s30, s63, s64
	v_lshl_add_u64 v[158:159], s[28:29], 0, v[152:153]
	s_add_i32 m0, s27, 0xc000
	ds_read_b128 v[186:189], v184
	ds_read_b128 v[190:193], v184 offset:1024
	ds_read_b128 v[194:197], v184 offset:2048
	ds_read_b128 v[198:201], v184 offset:3072
	ds_read_b128 v[202:205], v184 offset:4096
	ds_read_b128 v[206:209], v184 offset:5120
	ds_read_b128 v[210:213], v184 offset:6144
	ds_read_b128 v[214:217], v184 offset:7168
	global_load_lds_dwordx4 v[158:159], off
	v_lshl_add_u64 v[158:159], s[28:29], 0, v[150:151]
	s_add_i32 m0, s27, 0xe000
	s_nop 0
	global_load_lds_dwordx4 v[158:159], off
	s_waitcnt lgkmcnt(8)
	s_barrier
	s_waitcnt lgkmcnt(0)
	s_setprio 1
	s_waitcnt lgkmcnt(0)
	v_mfma_f32_16x16x128_f8f6f4 v[142:145], v[2:9], v[186:193], v[142:145]
	v_mfma_f32_16x16x128_f8f6f4 v[138:141], v[10:17], v[186:193], v[138:141]
	v_mfma_f32_16x16x128_f8f6f4 v[134:137], v[2:9], v[194:201], v[134:137]
	v_mfma_f32_16x16x128_f8f6f4 v[126:129], v[10:17], v[194:201], v[126:129]
	v_mfma_f32_16x16x128_f8f6f4 v[118:121], v[2:9], v[202:209], v[118:121]
	v_mfma_f32_16x16x128_f8f6f4 v[110:113], v[10:17], v[202:209], v[110:113]
	v_mfma_f32_16x16x128_f8f6f4 v[102:105], v[2:9], v[210:217], v[102:105]
	v_mfma_f32_16x16x128_f8f6f4 v[94:97], v[10:17], v[210:217], v[94:97]
	s_setprio 0
	s_barrier
	s_mov_b32 m0, s37
	v_lshl_add_u64 v[158:159], s[30:31], 0, v[148:149]
	ds_read_b128 v[220:223], v168
	ds_read_b128 v[224:227], v174
	ds_read_b128 v[228:231], v175
	ds_read_b128 v[232:235], v176
	global_load_lds_dwordx4 v[158:159], off
	v_lshl_add_u64 v[160:161], s[30:31], 0, v[146:147]
	s_mov_b32 m0, s38
	s_nop 0
	global_load_lds_dwordx4 v[160:161], off
	s_barrier
	s_waitcnt lgkmcnt(0)
	s_setprio 1
	s_waitcnt lgkmcnt(0)
	v_mfma_f32_16x16x128_f8f6f4 v[130:133], v[220:227], v[186:193], v[130:133]
	v_mfma_f32_16x16x128_f8f6f4 v[122:125], v[228:235], v[186:193], v[122:125]
	v_mfma_f32_16x16x128_f8f6f4 v[114:117], v[220:227], v[194:201], v[114:117]
	v_mfma_f32_16x16x128_f8f6f4 v[106:109], v[228:235], v[194:201], v[106:109]
	v_mfma_f32_16x16x128_f8f6f4 v[98:101], v[220:227], v[202:209], v[98:101]
	v_mfma_f32_16x16x128_f8f6f4 v[90:93], v[228:235], v[202:209], v[90:93]
	v_mfma_f32_16x16x128_f8f6f4 v[86:89], v[220:227], v[210:217], v[86:89]
	v_mfma_f32_16x16x128_f8f6f4 v[82:85], v[228:235], v[210:217], v[82:85]
	s_setprio 0
	s_mov_b32 m0, s27
	v_lshl_add_u64 v[162:163], s[34:35], 0, v[148:149]
	s_barrier
	ds_read_b128 v[186:189], v184 offset:16384
	ds_read_b128 v[190:193], v184 offset:17408
	ds_read_b128 v[194:197], v184 offset:18432
	ds_read_b128 v[198:201], v184 offset:19456
	ds_read_b128 v[202:205], v184 offset:20480
	ds_read_b128 v[206:209], v184 offset:21504
	ds_read_b128 v[210:213], v184 offset:22528
	ds_read_b128 v[214:217], v184 offset:23552
	global_load_lds_dwordx4 v[162:163], off
	v_lshl_add_u64 v[164:165], s[34:35], 0, v[146:147]
	s_mov_b32 m0, s39
	s_nop 0
	global_load_lds_dwordx4 v[164:165], off
	s_barrier
	s_waitcnt lgkmcnt(0)
	s_setprio 1
	s_waitcnt lgkmcnt(0)
	v_mfma_f32_16x16x128_f8f6f4 v[78:81], v[2:9], v[186:193], v[78:81]
	v_mfma_f32_16x16x128_f8f6f4 v[74:77], v[10:17], v[186:193], v[74:77]
	v_mfma_f32_16x16x128_f8f6f4 v[70:73], v[2:9], v[194:201], v[70:73]
	v_mfma_f32_16x16x128_f8f6f4 v[62:65], v[10:17], v[194:201], v[62:65]
	v_mfma_f32_16x16x128_f8f6f4 v[54:57], v[2:9], v[202:209], v[54:57]
	v_mfma_f32_16x16x128_f8f6f4 v[46:49], v[10:17], v[202:209], v[46:49]
	v_mfma_f32_16x16x128_f8f6f4 v[38:41], v[2:9], v[210:217], v[38:41]
	v_mfma_f32_16x16x128_f8f6f4 v[30:33], v[10:17], v[210:217], v[30:33]
	s_setprio 0
	s_barrier
	s_add_u32 s70, s30, 0x20000
	s_addc_u32 s71, s31, 0
	s_mov_b32 m0, s40
	v_lshl_add_u64 v[2:3], s[70:71], 0, v[148:149]
	global_load_lds_dwordx4 v[2:3], off
	v_lshl_add_u64 v[2:3], s[70:71], 0, v[146:147]
	s_mov_b32 m0, s41
	s_nop 0
	global_load_lds_dwordx4 v[2:3], off
	s_waitcnt vmcnt(6)
	s_barrier
	s_setprio 1
	v_mfma_f32_16x16x128_f8f6f4 v[66:69], v[220:227], v[186:193], v[66:69]
	v_mfma_f32_16x16x128_f8f6f4 v[58:61], v[228:235], v[186:193], v[58:61]
	v_mfma_f32_16x16x128_f8f6f4 v[50:53], v[220:227], v[194:201], v[50:53]
	v_mfma_f32_16x16x128_f8f6f4 v[42:45], v[228:235], v[194:201], v[42:45]
	v_mfma_f32_16x16x128_f8f6f4 v[34:37], v[220:227], v[202:209], v[34:37]
	v_mfma_f32_16x16x128_f8f6f4 v[26:29], v[228:235], v[202:209], v[26:29]
	v_mfma_f32_16x16x128_f8f6f4 v[22:25], v[220:227], v[210:217], v[22:25]
	v_mfma_f32_16x16x128_f8f6f4 v[18:21], v[228:235], v[210:217], v[18:21]
	s_setprio 0
	s_barrier
	ds_read_b128 v[2:5], v169
	ds_read_b128 v[6:9], v177
	ds_read_b128 v[10:13], v178
	ds_read_b128 v[14:17], v179
	s_add_u32 s34, s34, 0x20000
	s_addc_u32 s35, s35, 0
	s_mov_b32 m0, s42
	v_lshl_add_u64 v[220:221], s[34:35], 0, v[148:149]
	ds_read_b128 v[186:189], v184 offset:32768
	ds_read_b128 v[190:193], v184 offset:33792
	ds_read_b128 v[194:197], v184 offset:34816
	ds_read_b128 v[198:201], v184 offset:35840
	ds_read_b128 v[202:205], v184 offset:36864
	ds_read_b128 v[206:209], v184 offset:37888
	ds_read_b128 v[210:213], v184 offset:38912
	ds_read_b128 v[214:217], v184 offset:39936
	global_load_lds_dwordx4 v[220:221], off
	v_lshl_add_u64 v[220:221], s[34:35], 0, v[146:147]
	s_mov_b32 m0, s43
	s_nop 0
	global_load_lds_dwordx4 v[220:221], off
	s_waitcnt lgkmcnt(8)
	s_barrier
	s_waitcnt lgkmcnt(0)
	s_setprio 1
	s_waitcnt lgkmcnt(0)
	v_mfma_f32_16x16x128_f8f6f4 v[142:145], v[2:9], v[186:193], v[142:145]
	v_mfma_f32_16x16x128_f8f6f4 v[138:141], v[10:17], v[186:193], v[138:141]
	v_mfma_f32_16x16x128_f8f6f4 v[134:137], v[2:9], v[194:201], v[134:137]
	v_mfma_f32_16x16x128_f8f6f4 v[126:129], v[10:17], v[194:201], v[126:129]
	v_mfma_f32_16x16x128_f8f6f4 v[118:121], v[2:9], v[202:209], v[118:121]
	v_mfma_f32_16x16x128_f8f6f4 v[110:113], v[10:17], v[202:209], v[110:113]
	v_mfma_f32_16x16x128_f8f6f4 v[102:105], v[2:9], v[210:217], v[102:105]
	v_mfma_f32_16x16x128_f8f6f4 v[94:97], v[10:17], v[210:217], v[94:97]
	s_setprio 0
	s_barrier
	s_mov_b32 m0, s46
	v_lshl_add_u64 v[158:159], v[158:159], 0, s[14:15]
	ds_read_b128 v[220:223], v170
	ds_read_b128 v[224:227], v180
	ds_read_b128 v[228:231], v181
	ds_read_b128 v[232:235], v182
	global_load_lds_dwordx4 v[158:159], off
	v_lshl_add_u64 v[158:159], v[160:161], 0, s[14:15]
	s_mov_b32 m0, s47
	s_nop 0
	global_load_lds_dwordx4 v[158:159], off
	s_barrier
	s_waitcnt lgkmcnt(0)
	s_setprio 1
	s_waitcnt lgkmcnt(0)
	v_mfma_f32_16x16x128_f8f6f4 v[130:133], v[220:227], v[186:193], v[130:133]
	v_mfma_f32_16x16x128_f8f6f4 v[122:125], v[228:235], v[186:193], v[122:125]
	v_mfma_f32_16x16x128_f8f6f4 v[114:117], v[220:227], v[194:201], v[114:117]
	v_mfma_f32_16x16x128_f8f6f4 v[106:109], v[228:235], v[194:201], v[106:109]
	v_mfma_f32_16x16x128_f8f6f4 v[98:101], v[220:227], v[202:209], v[98:101]
	v_mfma_f32_16x16x128_f8f6f4 v[90:93], v[228:235], v[202:209], v[90:93]
	v_mfma_f32_16x16x128_f8f6f4 v[86:89], v[220:227], v[210:217], v[86:89]
	v_mfma_f32_16x16x128_f8f6f4 v[82:85], v[228:235], v[210:217], v[82:85]
	s_setprio 0
	s_mov_b32 m0, s48
	v_lshl_add_u64 v[158:159], v[162:163], 0, s[14:15]
	s_barrier
	ds_read_b128 v[186:189], v184 offset:49152
	ds_read_b128 v[190:193], v184 offset:50176
	ds_read_b128 v[194:197], v184 offset:51200
	ds_read_b128 v[198:201], v184 offset:52224
	ds_read_b128 v[202:205], v184 offset:53248
	ds_read_b128 v[206:209], v184 offset:54272
	ds_read_b128 v[210:213], v184 offset:55296
	ds_read_b128 v[214:217], v184 offset:56320
	global_load_lds_dwordx4 v[158:159], off
	v_lshl_add_u64 v[158:159], v[164:165], 0, s[14:15]
	s_mov_b32 m0, s49
	s_nop 0
	global_load_lds_dwordx4 v[158:159], off
	s_barrier
	s_waitcnt lgkmcnt(0)
	s_setprio 1
	s_waitcnt lgkmcnt(0)
	v_mfma_f32_16x16x128_f8f6f4 v[78:81], v[2:9], v[186:193], v[78:81]
	v_mfma_f32_16x16x128_f8f6f4 v[74:77], v[10:17], v[186:193], v[74:77]
	v_mfma_f32_16x16x128_f8f6f4 v[70:73], v[2:9], v[194:201], v[70:73]
	v_mfma_f32_16x16x128_f8f6f4 v[62:65], v[10:17], v[194:201], v[62:65]
	v_mfma_f32_16x16x128_f8f6f4 v[54:57], v[2:9], v[202:209], v[54:57]
	v_mfma_f32_16x16x128_f8f6f4 v[46:49], v[10:17], v[202:209], v[46:49]
	v_mfma_f32_16x16x128_f8f6f4 v[38:41], v[2:9], v[210:217], v[38:41]
	v_mfma_f32_16x16x128_f8f6f4 v[30:33], v[10:17], v[210:217], v[30:33]
	s_setprio 0
	s_barrier
	s_add_u32 s30, s30, 0x20080
	s_addc_u32 s31, s31, 0
	s_mov_b32 m0, s50
	v_lshl_add_u64 v[2:3], s[30:31], 0, v[148:149]
	global_load_lds_dwordx4 v[2:3], off
	v_lshl_add_u64 v[2:3], s[30:31], 0, v[146:147]
	s_mov_b32 m0, s51
	s_nop 0
	global_load_lds_dwordx4 v[2:3], off
	s_waitcnt vmcnt(6)
	s_barrier
	s_setprio 1
	v_mfma_f32_16x16x128_f8f6f4 v[66:69], v[220:227], v[186:193], v[66:69]
	v_mfma_f32_16x16x128_f8f6f4 v[58:61], v[228:235], v[186:193], v[58:61]
	v_mfma_f32_16x16x128_f8f6f4 v[50:53], v[220:227], v[194:201], v[50:53]
	v_mfma_f32_16x16x128_f8f6f4 v[42:45], v[228:235], v[194:201], v[42:45]
	v_mfma_f32_16x16x128_f8f6f4 v[34:37], v[220:227], v[202:209], v[34:37]
	v_mfma_f32_16x16x128_f8f6f4 v[26:29], v[228:235], v[202:209], v[26:29]
	v_mfma_f32_16x16x128_f8f6f4 v[22:25], v[220:227], v[210:217], v[22:25]
	v_mfma_f32_16x16x128_f8f6f4 v[18:21], v[228:235], v[210:217], v[18:21]
	s_setprio 0
	s_add_i32 s68, s68, 2
	s_add_u32 s64, s64, 0x100
	s_addc_u32 s65, s65, 0
	s_add_u32 s28, s28, 0x100
	s_addc_u32 s29, s29, 0
	s_cmp_gt_u32 s68, 5
	s_barrier
	s_cbranch_scc0 .LBB0_648
	v_bfe_u32 v160, v0, 4, 1
	v_mul_u32_u24_e32 v160, 24, v160
	v_mov_b32_e32 v161, 0
	v_lshl_or_b32 v4, s55, 8, v183
	v_pk_mul_f32 v[2:3], v[144:145], s[16:17] op_sel_hi:[1,0]
	v_pk_mul_f32 v[6:7], v[142:143], s[16:17] op_sel_hi:[1,0]
	v_lshl_add_u32 v12, s26, 8, v166
	v_cvt_pk_bf16_f32 v6, v6, v7
	v_cvt_pk_bf16_f32 v7, v2, v3
	v_mov_b64_e32 v[2:3], s[10:11]
	v_ashrrev_i32_e32 v5, 31, v4
	v_mad_i64_i32 v[8:9], s[28:29], v12, s53, v[2:3]
	v_lshlrev_b64 v[4:5], 1, v[4:5]
	v_lshl_add_u64 v[8:9], v[8:9], 0, v[4:5]
	s_nop 15
	s_nop 15
	v_mov_b32_e32 v192, v6
	v_mov_b32_e32 v193, v7
	v_pk_mul_f32 v[6:7], v[140:141], s[16:17] op_sel_hi:[1,0]
	v_pk_mul_f32 v[10:11], v[138:139], s[16:17] op_sel_hi:[1,0]
	s_and_b64 vcc, exec, s[6:7]
	v_cvt_pk_bf16_f32 v10, v10, v11
	v_cvt_pk_bf16_f32 v11, v6, v7
	v_mov_b32_e32 v194, v10
	v_mov_b32_e32 v195, v11
	v_lshl_add_u64 v[162:163], v[8:9], 0, v[160:161]
	s_nop 0
	v_permlane16_swap_b32 v192, v194
	v_permlane16_swap_b32 v193, v195
	global_store_dwordx4 v[162:163], v[192:195], off
	v_pk_mul_f32 v[6:7], v[132:133], s[16:17] op_sel_hi:[1,0]
	v_pk_mul_f32 v[10:11], v[130:131], s[16:17] op_sel_hi:[1,0]
	s_mov_b32 s55, s18
	v_cvt_pk_bf16_f32 v10, v10, v11
	v_cvt_pk_bf16_f32 v11, v6, v7
	v_mov_b32_e32 v196, v10
	v_mov_b32_e32 v197, v11
	v_pk_mul_f32 v[6:7], v[124:125], s[16:17] op_sel_hi:[1,0]
	v_pk_mul_f32 v[10:11], v[122:123], s[16:17] op_sel_hi:[1,0]
	s_mov_b32 s26, s20
	v_cvt_pk_bf16_f32 v10, v10, v11
	v_cvt_pk_bf16_f32 v11, v6, v7
	v_mov_b32_e32 v198, v10
	v_mov_b32_e32 v199, v11
	v_lshl_add_u64 v[162:163], v[8:9], 0, v[160:161]
	s_nop 0
	v_permlane16_swap_b32 v196, v198
	v_permlane16_swap_b32 v197, v199
	global_store_dwordx4 v[162:163], v[196:199], off offset:256
	v_or_b32_e32 v10, 16, v12
	v_pk_mul_f32 v[6:7], v[136:137], s[16:17] op_sel_hi:[1,0]
	v_pk_mul_f32 v[8:9], v[134:135], s[16:17] op_sel_hi:[1,0]
	s_mov_b64 s[30:31], s[22:23]
	v_cvt_pk_bf16_f32 v8, v8, v9
	v_cvt_pk_bf16_f32 v9, v6, v7
	v_mad_i64_i32 v[6:7], s[28:29], v10, s53, v[2:3]
	v_lshl_add_u64 v[6:7], v[6:7], 0, v[4:5]
	v_mov_b32_e32 v200, v8
	v_mov_b32_e32 v201, v9
	v_pk_mul_f32 v[8:9], v[128:129], s[16:17] op_sel_hi:[1,0]
	v_pk_mul_f32 v[10:11], v[126:127], s[16:17] op_sel_hi:[1,0]
	s_nop 0
	v_cvt_pk_bf16_f32 v10, v10, v11
	v_cvt_pk_bf16_f32 v11, v8, v9
	v_mov_b32_e32 v202, v10
	v_mov_b32_e32 v203, v11
	v_lshl_add_u64 v[162:163], v[6:7], 0, v[160:161]
	s_nop 0
	v_permlane16_swap_b32 v200, v202
	v_permlane16_swap_b32 v201, v203
	global_store_dwordx4 v[162:163], v[200:203], off
	v_pk_mul_f32 v[8:9], v[116:117], s[16:17] op_sel_hi:[1,0]
	v_pk_mul_f32 v[10:11], v[114:115], s[16:17] op_sel_hi:[1,0]
	s_nop 0
	v_cvt_pk_bf16_f32 v10, v10, v11
	v_cvt_pk_bf16_f32 v11, v8, v9
	v_mov_b32_e32 v204, v10
	v_mov_b32_e32 v205, v11
	v_pk_mul_f32 v[8:9], v[108:109], s[16:17] op_sel_hi:[1,0]
	v_pk_mul_f32 v[10:11], v[106:107], s[16:17] op_sel_hi:[1,0]
	s_nop 0
	v_cvt_pk_bf16_f32 v10, v10, v11
	v_cvt_pk_bf16_f32 v11, v8, v9
	v_mov_b32_e32 v206, v10
	v_mov_b32_e32 v207, v11
	v_lshl_add_u64 v[162:163], v[6:7], 0, v[160:161]
	s_nop 0
	v_permlane16_swap_b32 v204, v206
	v_permlane16_swap_b32 v205, v207
	global_store_dwordx4 v[162:163], v[204:207], off offset:256
	v_or_b32_e32 v10, 32, v12
	v_pk_mul_f32 v[6:7], v[120:121], s[16:17] op_sel_hi:[1,0]
	v_pk_mul_f32 v[8:9], v[118:119], s[16:17] op_sel_hi:[1,0]
	s_nop 0
	v_cvt_pk_bf16_f32 v8, v8, v9
	v_cvt_pk_bf16_f32 v9, v6, v7
	v_mad_i64_i32 v[6:7], s[28:29], v10, s53, v[2:3]
	v_lshl_add_u64 v[6:7], v[6:7], 0, v[4:5]
	v_mov_b32_e32 v208, v8
	v_mov_b32_e32 v209, v9
	v_pk_mul_f32 v[8:9], v[112:113], s[16:17] op_sel_hi:[1,0]
	v_pk_mul_f32 v[10:11], v[110:111], s[16:17] op_sel_hi:[1,0]
	s_nop 0
	v_cvt_pk_bf16_f32 v10, v10, v11
	v_cvt_pk_bf16_f32 v11, v8, v9
	v_mov_b32_e32 v210, v10
	v_mov_b32_e32 v211, v11
	v_lshl_add_u64 v[162:163], v[6:7], 0, v[160:161]
	s_nop 0
	v_permlane16_swap_b32 v208, v210
	v_permlane16_swap_b32 v209, v211
	global_store_dwordx4 v[162:163], v[208:211], off
	v_pk_mul_f32 v[8:9], v[100:101], s[16:17] op_sel_hi:[1,0]
	v_pk_mul_f32 v[10:11], v[98:99], s[16:17] op_sel_hi:[1,0]
	s_nop 0
	v_cvt_pk_bf16_f32 v10, v10, v11
	v_cvt_pk_bf16_f32 v11, v8, v9
	v_mov_b32_e32 v212, v10
	v_mov_b32_e32 v213, v11
	v_pk_mul_f32 v[8:9], v[92:93], s[16:17] op_sel_hi:[1,0]
	v_pk_mul_f32 v[10:11], v[90:91], s[16:17] op_sel_hi:[1,0]
	s_nop 0
	v_cvt_pk_bf16_f32 v10, v10, v11
	v_cvt_pk_bf16_f32 v11, v8, v9
	v_mov_b32_e32 v214, v10
	v_mov_b32_e32 v215, v11
	v_lshl_add_u64 v[162:163], v[6:7], 0, v[160:161]
	s_nop 0
	v_permlane16_swap_b32 v212, v214
	v_permlane16_swap_b32 v213, v215
	global_store_dwordx4 v[162:163], v[212:215], off offset:256
	v_or_b32_e32 v10, 48, v12
	v_pk_mul_f32 v[6:7], v[104:105], s[16:17] op_sel_hi:[1,0]
	v_pk_mul_f32 v[8:9], v[102:103], s[16:17] op_sel_hi:[1,0]
	s_nop 0
	v_cvt_pk_bf16_f32 v8, v8, v9
	v_cvt_pk_bf16_f32 v9, v6, v7
	v_mad_i64_i32 v[6:7], s[28:29], v10, s53, v[2:3]
	v_lshl_add_u64 v[6:7], v[6:7], 0, v[4:5]
	v_mov_b32_e32 v220, v8
	v_mov_b32_e32 v221, v9
	v_pk_mul_f32 v[8:9], v[96:97], s[16:17] op_sel_hi:[1,0]
	v_pk_mul_f32 v[10:11], v[94:95], s[16:17] op_sel_hi:[1,0]
	s_nop 0
	v_cvt_pk_bf16_f32 v10, v10, v11
	v_cvt_pk_bf16_f32 v11, v8, v9
	v_mov_b32_e32 v222, v10
	v_mov_b32_e32 v223, v11
	v_lshl_add_u64 v[162:163], v[6:7], 0, v[160:161]
	s_nop 0
	v_permlane16_swap_b32 v220, v222
	v_permlane16_swap_b32 v221, v223
	global_store_dwordx4 v[162:163], v[220:223], off
	v_pk_mul_f32 v[8:9], v[88:89], s[16:17] op_sel_hi:[1,0]
	v_pk_mul_f32 v[10:11], v[86:87], s[16:17] op_sel_hi:[1,0]
	s_nop 0
	v_cvt_pk_bf16_f32 v10, v10, v11
	v_cvt_pk_bf16_f32 v11, v8, v9
	v_mov_b32_e32 v224, v10
	v_mov_b32_e32 v225, v11
	v_pk_mul_f32 v[8:9], v[84:85], s[16:17] op_sel_hi:[1,0]
	v_pk_mul_f32 v[10:11], v[82:83], s[16:17] op_sel_hi:[1,0]
	s_nop 0
	v_cvt_pk_bf16_f32 v10, v10, v11
	v_cvt_pk_bf16_f32 v11, v8, v9
	v_mov_b32_e32 v226, v10
	v_mov_b32_e32 v227, v11
	v_lshl_add_u64 v[162:163], v[6:7], 0, v[160:161]
	s_nop 0
	v_permlane16_swap_b32 v224, v226
	v_permlane16_swap_b32 v225, v227
	global_store_dwordx4 v[162:163], v[224:227], off offset:256
	v_add_u32_e32 v10, 0x80, v12
	v_pk_mul_f32 v[6:7], v[80:81], s[16:17] op_sel_hi:[1,0]
	v_pk_mul_f32 v[8:9], v[78:79], s[16:17] op_sel_hi:[1,0]
	s_nop 0
	v_cvt_pk_bf16_f32 v8, v8, v9
	v_cvt_pk_bf16_f32 v9, v6, v7
	v_mad_i64_i32 v[6:7], s[28:29], v10, s53, v[2:3]
	v_lshl_add_u64 v[6:7], v[6:7], 0, v[4:5]
	v_mov_b32_e32 v232, v8
	v_mov_b32_e32 v233, v9
	v_pk_mul_f32 v[8:9], v[76:77], s[16:17] op_sel_hi:[1,0]
	v_pk_mul_f32 v[10:11], v[74:75], s[16:17] op_sel_hi:[1,0]
	s_nop 0
	v_cvt_pk_bf16_f32 v10, v10, v11
	v_cvt_pk_bf16_f32 v11, v8, v9
	v_mov_b32_e32 v234, v10
	v_mov_b32_e32 v235, v11
	v_lshl_add_u64 v[162:163], v[6:7], 0, v[160:161]
	s_nop 0
	v_permlane16_swap_b32 v232, v234
	v_permlane16_swap_b32 v233, v235
	global_store_dwordx4 v[162:163], v[232:235], off
	v_pk_mul_f32 v[8:9], v[68:69], s[16:17] op_sel_hi:[1,0]
	v_pk_mul_f32 v[10:11], v[66:67], s[16:17] op_sel_hi:[1,0]
	s_nop 0
	v_cvt_pk_bf16_f32 v10, v10, v11
	v_cvt_pk_bf16_f32 v11, v8, v9
	v_mov_b32_e32 v236, v10
	v_mov_b32_e32 v237, v11
	v_pk_mul_f32 v[8:9], v[60:61], s[16:17] op_sel_hi:[1,0]
	v_pk_mul_f32 v[10:11], v[58:59], s[16:17] op_sel_hi:[1,0]
	s_nop 0
	v_cvt_pk_bf16_f32 v10, v10, v11
	v_cvt_pk_bf16_f32 v11, v8, v9
	v_mov_b32_e32 v238, v10
	v_mov_b32_e32 v239, v11
	v_lshl_add_u64 v[162:163], v[6:7], 0, v[160:161]
	s_nop 0
	v_permlane16_swap_b32 v236, v238
	v_permlane16_swap_b32 v237, v239
	global_store_dwordx4 v[162:163], v[236:239], off offset:256
	v_add_u32_e32 v10, 0x90, v12
	v_pk_mul_f32 v[6:7], v[72:73], s[16:17] op_sel_hi:[1,0]
	v_pk_mul_f32 v[8:9], v[70:71], s[16:17] op_sel_hi:[1,0]
	s_nop 0
	v_cvt_pk_bf16_f32 v8, v8, v9
	v_cvt_pk_bf16_f32 v9, v6, v7
	v_mad_i64_i32 v[6:7], s[28:29], v10, s53, v[2:3]
	v_lshl_add_u64 v[6:7], v[6:7], 0, v[4:5]
	v_mov_b32_e32 v240, v8
	v_mov_b32_e32 v241, v9
	v_pk_mul_f32 v[8:9], v[64:65], s[16:17] op_sel_hi:[1,0]
	v_pk_mul_f32 v[10:11], v[62:63], s[16:17] op_sel_hi:[1,0]
	s_nop 0
	v_cvt_pk_bf16_f32 v10, v10, v11
	v_cvt_pk_bf16_f32 v11, v8, v9
	v_mov_b32_e32 v242, v10
	v_mov_b32_e32 v243, v11
	v_lshl_add_u64 v[162:163], v[6:7], 0, v[160:161]
	s_nop 0
	v_permlane16_swap_b32 v240, v242
	v_permlane16_swap_b32 v241, v243
	global_store_dwordx4 v[162:163], v[240:243], off
	v_pk_mul_f32 v[8:9], v[52:53], s[16:17] op_sel_hi:[1,0]
	v_pk_mul_f32 v[10:11], v[50:51], s[16:17] op_sel_hi:[1,0]
	s_nop 0
	v_cvt_pk_bf16_f32 v10, v10, v11
	v_cvt_pk_bf16_f32 v11, v8, v9
	v_mov_b32_e32 v192, v10
	v_mov_b32_e32 v193, v11
	v_pk_mul_f32 v[8:9], v[44:45], s[16:17] op_sel_hi:[1,0]
	v_pk_mul_f32 v[10:11], v[42:43], s[16:17] op_sel_hi:[1,0]
	s_nop 0
	v_cvt_pk_bf16_f32 v10, v10, v11
	v_cvt_pk_bf16_f32 v11, v8, v9
	v_mov_b32_e32 v194, v10
	v_mov_b32_e32 v195, v11
	v_lshl_add_u64 v[162:163], v[6:7], 0, v[160:161]
	s_nop 0
	v_permlane16_swap_b32 v192, v194
	v_permlane16_swap_b32 v193, v195
	global_store_dwordx4 v[162:163], v[192:195], off offset:256
	v_add_u32_e32 v10, 0xa0, v12
	v_pk_mul_f32 v[6:7], v[56:57], s[16:17] op_sel_hi:[1,0]
	v_pk_mul_f32 v[8:9], v[54:55], s[16:17] op_sel_hi:[1,0]
	s_nop 0
	v_cvt_pk_bf16_f32 v8, v8, v9
	v_cvt_pk_bf16_f32 v9, v6, v7
	v_mad_i64_i32 v[6:7], s[28:29], v10, s53, v[2:3]
	v_lshl_add_u64 v[6:7], v[6:7], 0, v[4:5]
	v_mov_b32_e32 v196, v8
	v_mov_b32_e32 v197, v9
	v_pk_mul_f32 v[8:9], v[48:49], s[16:17] op_sel_hi:[1,0]
	v_pk_mul_f32 v[10:11], v[46:47], s[16:17] op_sel_hi:[1,0]
	s_nop 0
	v_cvt_pk_bf16_f32 v10, v10, v11
	v_cvt_pk_bf16_f32 v11, v8, v9
	v_mov_b32_e32 v198, v10
	v_mov_b32_e32 v199, v11
	v_lshl_add_u64 v[162:163], v[6:7], 0, v[160:161]
	s_nop 0
	v_permlane16_swap_b32 v196, v198
	v_permlane16_swap_b32 v197, v199
	global_store_dwordx4 v[162:163], v[196:199], off
	v_pk_mul_f32 v[8:9], v[36:37], s[16:17] op_sel_hi:[1,0]
	v_pk_mul_f32 v[10:11], v[34:35], s[16:17] op_sel_hi:[1,0]
	s_nop 0
	v_cvt_pk_bf16_f32 v10, v10, v11
	v_cvt_pk_bf16_f32 v11, v8, v9
	v_mov_b32_e32 v200, v10
	v_mov_b32_e32 v201, v11
	v_pk_mul_f32 v[8:9], v[28:29], s[16:17] op_sel_hi:[1,0]
	v_pk_mul_f32 v[10:11], v[26:27], s[16:17] op_sel_hi:[1,0]
	s_nop 0
	v_cvt_pk_bf16_f32 v10, v10, v11
	v_cvt_pk_bf16_f32 v11, v8, v9
	v_mov_b32_e32 v202, v10
	v_mov_b32_e32 v203, v11
	v_lshl_add_u64 v[162:163], v[6:7], 0, v[160:161]
	s_nop 0
	v_permlane16_swap_b32 v200, v202
	v_permlane16_swap_b32 v201, v203
	global_store_dwordx4 v[162:163], v[200:203], off offset:256
	v_add_u32_e32 v10, 0xb0, v12
	v_pk_mul_f32 v[6:7], v[40:41], s[16:17] op_sel_hi:[1,0]
	v_pk_mul_f32 v[8:9], v[38:39], s[16:17] op_sel_hi:[1,0]
	v_mad_i64_i32 v[2:3], s[28:29], v10, s53, v[2:3]
	v_cvt_pk_bf16_f32 v8, v8, v9
	v_cvt_pk_bf16_f32 v9, v6, v7
	v_lshl_add_u64 v[2:3], v[2:3], 0, v[4:5]
	v_pk_mul_f32 v[4:5], v[32:33], s[16:17] op_sel_hi:[1,0]
	v_pk_mul_f32 v[6:7], v[30:31], s[16:17] op_sel_hi:[1,0]
	s_mov_b64 s[28:29], s[24:25]
	v_cvt_pk_bf16_f32 v6, v6, v7
	v_cvt_pk_bf16_f32 v7, v4, v5
	v_mov_b32_e32 v206, v6
	v_mov_b32_e32 v207, v7
	v_pk_mul_f32 v[4:5], v[24:25], s[16:17] op_sel_hi:[1,0]
	v_pk_mul_f32 v[6:7], v[22:23], s[16:17] op_sel_hi:[1,0]
	v_mov_b32_e32 v204, v8
	v_mov_b32_e32 v205, v9
	v_lshl_add_u64 v[162:163], v[2:3], 0, v[160:161]
	s_nop 0
	v_permlane16_swap_b32 v204, v206
	v_permlane16_swap_b32 v205, v207
	global_store_dwordx4 v[162:163], v[204:207], off
	v_cvt_pk_bf16_f32 v6, v6, v7
	v_cvt_pk_bf16_f32 v7, v4, v5
	v_mov_b32_e32 v208, v6
	v_mov_b32_e32 v209, v7
	v_pk_mul_f32 v[4:5], v[20:21], s[16:17] op_sel_hi:[1,0]
	v_pk_mul_f32 v[6:7], v[18:19], s[16:17] op_sel_hi:[1,0]
	s_nop 0
	v_cvt_pk_bf16_f32 v6, v6, v7
	v_cvt_pk_bf16_f32 v7, v4, v5
	v_mov_b32_e32 v210, v6
	v_mov_b32_e32 v211, v7
	v_lshl_add_u64 v[162:163], v[2:3], 0, v[160:161]
	s_nop 0
	v_permlane16_swap_b32 v208, v210
	v_permlane16_swap_b32 v209, v211
	global_store_dwordx4 v[162:163], v[208:211], off offset:256
	s_cbranch_vccz .LBB0_645
	s_waitcnt vmcnt(0)
	s_cmpk_gt_u32 s3, 0xff
	v_readlane_b32 s2, v252, 8
	s_cbranch_scc1 .LBB0_652
	s_barrier

.LBB0_1551:
	ds_read_b128 v[2:5], v167
	ds_read_b128 v[6:9], v171
	ds_read_b128 v[10:13], v172
	ds_read_b128 v[14:17], v173
	s_add_u32 s40, s38, 0xfffe0080
	s_addc_u32 s41, s39, -1
	s_cmp_eq_u32 s77, 4
	s_cselect_b32 s43, s29, s41
	s_cselect_b32 s42, s73, s40
	s_cselect_b32 s41, s27, s76
	s_cselect_b32 s40, s74, s75
	v_lshl_add_u64 v[158:159], s[38:39], 0, v[152:153]
	s_add_i32 m0, s37, 0xc000
	ds_read_b128 v[186:189], v184
	ds_read_b128 v[190:193], v184 offset:1024
	ds_read_b128 v[194:197], v184 offset:2048
	ds_read_b128 v[198:201], v184 offset:3072
	ds_read_b128 v[202:205], v184 offset:4096
	ds_read_b128 v[206:209], v184 offset:5120
	ds_read_b128 v[210:213], v184 offset:6144
	ds_read_b128 v[214:217], v184 offset:7168
	global_load_lds_dwordx4 v[158:159], off
	v_lshl_add_u64 v[158:159], s[38:39], 0, v[150:151]
	s_add_i32 m0, s37, 0xe000
	s_nop 0
	global_load_lds_dwordx4 v[158:159], off
	s_waitcnt lgkmcnt(8)
	s_barrier
	s_waitcnt lgkmcnt(0)
	s_setprio 1
	s_waitcnt lgkmcnt(0)
	v_mfma_f32_16x16x128_f8f6f4 v[142:145], v[2:9], v[186:193], v[142:145]
	v_mfma_f32_16x16x128_f8f6f4 v[138:141], v[10:17], v[186:193], v[138:141]
	v_mfma_f32_16x16x128_f8f6f4 v[126:129], v[2:9], v[194:201], v[126:129]
	v_mfma_f32_16x16x128_f8f6f4 v[122:125], v[10:17], v[194:201], v[122:125]
	v_mfma_f32_16x16x128_f8f6f4 v[110:113], v[2:9], v[202:209], v[110:113]
	v_mfma_f32_16x16x128_f8f6f4 v[106:109], v[10:17], v[202:209], v[106:109]
	v_mfma_f32_16x16x128_f8f6f4 v[94:97], v[2:9], v[210:217], v[94:97]
	v_mfma_f32_16x16x128_f8f6f4 v[90:93], v[10:17], v[210:217], v[90:93]
	s_setprio 0
	s_barrier
	s_mov_b32 m0, s45
	v_lshl_add_u64 v[158:159], s[40:41], 0, v[148:149]
	ds_read_b128 v[220:223], v168
	ds_read_b128 v[224:227], v174
	ds_read_b128 v[228:231], v175
	ds_read_b128 v[232:235], v176
	global_load_lds_dwordx4 v[158:159], off
	v_lshl_add_u64 v[160:161], s[40:41], 0, v[146:147]
	s_mov_b32 m0, s46
	s_nop 0
	global_load_lds_dwordx4 v[160:161], off
	s_barrier
	s_waitcnt lgkmcnt(0)
	s_setprio 1
	s_waitcnt lgkmcnt(0)
	v_mfma_f32_16x16x128_f8f6f4 v[134:137], v[220:227], v[186:193], v[134:137]
	v_mfma_f32_16x16x128_f8f6f4 v[130:133], v[228:235], v[186:193], v[130:133]
	v_mfma_f32_16x16x128_f8f6f4 v[118:121], v[220:227], v[194:201], v[118:121]
	v_mfma_f32_16x16x128_f8f6f4 v[114:117], v[228:235], v[194:201], v[114:117]
	v_mfma_f32_16x16x128_f8f6f4 v[102:105], v[220:227], v[202:209], v[102:105]
	v_mfma_f32_16x16x128_f8f6f4 v[98:101], v[228:235], v[202:209], v[98:101]
	v_mfma_f32_16x16x128_f8f6f4 v[86:89], v[220:227], v[210:217], v[86:89]
	v_mfma_f32_16x16x128_f8f6f4 v[82:85], v[228:235], v[210:217], v[82:85]
	s_setprio 0
	s_mov_b32 m0, s37
	v_lshl_add_u64 v[162:163], s[42:43], 0, v[148:149]
	s_barrier
	ds_read_b128 v[186:189], v184 offset:16384
	ds_read_b128 v[190:193], v184 offset:17408
	ds_read_b128 v[194:197], v184 offset:18432
	ds_read_b128 v[198:201], v184 offset:19456
	ds_read_b128 v[202:205], v184 offset:20480
	ds_read_b128 v[206:209], v184 offset:21504
	ds_read_b128 v[210:213], v184 offset:22528
	ds_read_b128 v[214:217], v184 offset:23552
	global_load_lds_dwordx4 v[162:163], off
	v_lshl_add_u64 v[164:165], s[42:43], 0, v[146:147]
	s_mov_b32 m0, s47
	s_nop 0
	global_load_lds_dwordx4 v[164:165], off
	s_barrier
	s_waitcnt lgkmcnt(0)
	s_setprio 1
	s_waitcnt lgkmcnt(0)
	v_mfma_f32_16x16x128_f8f6f4 v[78:81], v[2:9], v[186:193], v[78:81]
	v_mfma_f32_16x16x128_f8f6f4 v[74:77], v[10:17], v[186:193], v[74:77]
	v_mfma_f32_16x16x128_f8f6f4 v[62:65], v[2:9], v[194:201], v[62:65]
	v_mfma_f32_16x16x128_f8f6f4 v[58:61], v[10:17], v[194:201], v[58:61]
	v_mfma_f32_16x16x128_f8f6f4 v[46:49], v[2:9], v[202:209], v[46:49]
	v_mfma_f32_16x16x128_f8f6f4 v[42:45], v[10:17], v[202:209], v[42:45]
	v_mfma_f32_16x16x128_f8f6f4 v[30:33], v[2:9], v[210:217], v[30:33]
	v_mfma_f32_16x16x128_f8f6f4 v[26:29], v[10:17], v[210:217], v[26:29]
	s_setprio 0
	s_barrier
	s_add_u32 s66, s40, 0x20000
	s_addc_u32 s67, s41, 0
	s_mov_b32 m0, s48
	v_lshl_add_u64 v[2:3], s[66:67], 0, v[148:149]
	global_load_lds_dwordx4 v[2:3], off
	v_lshl_add_u64 v[2:3], s[66:67], 0, v[146:147]
	s_mov_b32 m0, s49
	s_nop 0
	global_load_lds_dwordx4 v[2:3], off
	s_waitcnt vmcnt(6)
	s_barrier
	s_setprio 1
	v_mfma_f32_16x16x128_f8f6f4 v[70:73], v[220:227], v[186:193], v[70:73]
	v_mfma_f32_16x16x128_f8f6f4 v[66:69], v[228:235], v[186:193], v[66:69]
	v_mfma_f32_16x16x128_f8f6f4 v[54:57], v[220:227], v[194:201], v[54:57]
	v_mfma_f32_16x16x128_f8f6f4 v[50:53], v[228:235], v[194:201], v[50:53]
	v_mfma_f32_16x16x128_f8f6f4 v[38:41], v[220:227], v[202:209], v[38:41]
	v_mfma_f32_16x16x128_f8f6f4 v[34:37], v[228:235], v[202:209], v[34:37]
	v_mfma_f32_16x16x128_f8f6f4 v[22:25], v[220:227], v[210:217], v[22:25]
	v_mfma_f32_16x16x128_f8f6f4 v[18:21], v[228:235], v[210:217], v[18:21]
	s_setprio 0
	s_barrier
	ds_read_b128 v[2:5], v169
	ds_read_b128 v[6:9], v177
	ds_read_b128 v[10:13], v178
	ds_read_b128 v[14:17], v179
	s_add_u32 s42, s42, 0x20000
	s_addc_u32 s43, s43, 0
	s_mov_b32 m0, s50
	v_lshl_add_u64 v[220:221], s[42:43], 0, v[148:149]
	ds_read_b128 v[186:189], v184 offset:32768
	ds_read_b128 v[190:193], v184 offset:33792
	ds_read_b128 v[194:197], v184 offset:34816
	ds_read_b128 v[198:201], v184 offset:35840
	ds_read_b128 v[202:205], v184 offset:36864
	ds_read_b128 v[206:209], v184 offset:37888
	ds_read_b128 v[210:213], v184 offset:38912
	ds_read_b128 v[214:217], v184 offset:39936
	global_load_lds_dwordx4 v[220:221], off
	v_lshl_add_u64 v[220:221], s[42:43], 0, v[146:147]
	s_mov_b32 m0, s51
	s_nop 0
	global_load_lds_dwordx4 v[220:221], off
	s_waitcnt lgkmcnt(8)
	s_barrier
	s_waitcnt lgkmcnt(0)
	s_setprio 1
	s_waitcnt lgkmcnt(0)
	v_mfma_f32_16x16x128_f8f6f4 v[142:145], v[2:9], v[186:193], v[142:145]
	v_mfma_f32_16x16x128_f8f6f4 v[138:141], v[10:17], v[186:193], v[138:141]
	v_mfma_f32_16x16x128_f8f6f4 v[126:129], v[2:9], v[194:201], v[126:129]
	v_mfma_f32_16x16x128_f8f6f4 v[122:125], v[10:17], v[194:201], v[122:125]
	v_mfma_f32_16x16x128_f8f6f4 v[110:113], v[2:9], v[202:209], v[110:113]
	v_mfma_f32_16x16x128_f8f6f4 v[106:109], v[10:17], v[202:209], v[106:109]
	v_mfma_f32_16x16x128_f8f6f4 v[94:97], v[2:9], v[210:217], v[94:97]
	v_mfma_f32_16x16x128_f8f6f4 v[90:93], v[10:17], v[210:217], v[90:93]
	s_setprio 0
	s_barrier
	s_mov_b32 m0, s53
	v_lshl_add_u64 v[158:159], v[158:159], 0, s[20:21]
	ds_read_b128 v[220:223], v170
	ds_read_b128 v[224:227], v180
	ds_read_b128 v[228:231], v181
	ds_read_b128 v[232:235], v182
	global_load_lds_dwordx4 v[158:159], off
	v_lshl_add_u64 v[158:159], v[160:161], 0, s[20:21]
	s_mov_b32 m0, s55
	s_nop 0
	global_load_lds_dwordx4 v[158:159], off
	s_barrier
	s_waitcnt lgkmcnt(0)
	s_setprio 1
	s_waitcnt lgkmcnt(0)
	v_mfma_f32_16x16x128_f8f6f4 v[134:137], v[220:227], v[186:193], v[134:137]
	v_mfma_f32_16x16x128_f8f6f4 v[130:133], v[228:235], v[186:193], v[130:133]
	v_mfma_f32_16x16x128_f8f6f4 v[118:121], v[220:227], v[194:201], v[118:121]
	v_mfma_f32_16x16x128_f8f6f4 v[114:117], v[228:235], v[194:201], v[114:117]
	v_mfma_f32_16x16x128_f8f6f4 v[102:105], v[220:227], v[202:209], v[102:105]
	v_mfma_f32_16x16x128_f8f6f4 v[98:101], v[228:235], v[202:209], v[98:101]
	v_mfma_f32_16x16x128_f8f6f4 v[86:89], v[220:227], v[210:217], v[86:89]
	v_mfma_f32_16x16x128_f8f6f4 v[82:85], v[228:235], v[210:217], v[82:85]
	s_setprio 0
	s_mov_b32 m0, s64
	v_lshl_add_u64 v[158:159], v[162:163], 0, s[20:21]
	s_barrier
	ds_read_b128 v[186:189], v184 offset:49152
	ds_read_b128 v[190:193], v184 offset:50176
	ds_read_b128 v[194:197], v184 offset:51200
	ds_read_b128 v[198:201], v184 offset:52224
	ds_read_b128 v[202:205], v184 offset:53248
	ds_read_b128 v[206:209], v184 offset:54272
	ds_read_b128 v[210:213], v184 offset:55296
	ds_read_b128 v[214:217], v184 offset:56320
	global_load_lds_dwordx4 v[158:159], off
	v_lshl_add_u64 v[158:159], v[164:165], 0, s[20:21]
	s_mov_b32 m0, s65
	s_nop 0
	global_load_lds_dwordx4 v[158:159], off
	s_barrier
	s_waitcnt lgkmcnt(0)
	s_setprio 1
	s_waitcnt lgkmcnt(0)
	v_mfma_f32_16x16x128_f8f6f4 v[78:81], v[2:9], v[186:193], v[78:81]
	v_mfma_f32_16x16x128_f8f6f4 v[74:77], v[10:17], v[186:193], v[74:77]
	v_mfma_f32_16x16x128_f8f6f4 v[62:65], v[2:9], v[194:201], v[62:65]
	v_mfma_f32_16x16x128_f8f6f4 v[58:61], v[10:17], v[194:201], v[58:61]
	v_mfma_f32_16x16x128_f8f6f4 v[46:49], v[2:9], v[202:209], v[46:49]
	v_mfma_f32_16x16x128_f8f6f4 v[42:45], v[10:17], v[202:209], v[42:45]
	v_mfma_f32_16x16x128_f8f6f4 v[30:33], v[2:9], v[210:217], v[30:33]
	v_mfma_f32_16x16x128_f8f6f4 v[26:29], v[10:17], v[210:217], v[26:29]
	s_setprio 0
	s_barrier
	s_add_u32 s40, s40, 0x20080
	s_addc_u32 s41, s41, 0
	s_mov_b32 m0, s68
	v_lshl_add_u64 v[2:3], s[40:41], 0, v[148:149]
	global_load_lds_dwordx4 v[2:3], off
	v_lshl_add_u64 v[2:3], s[40:41], 0, v[146:147]
	s_mov_b32 m0, s69
	s_nop 0
	global_load_lds_dwordx4 v[2:3], off
	s_waitcnt vmcnt(6)
	s_barrier
	s_setprio 1
	v_mfma_f32_16x16x128_f8f6f4 v[70:73], v[220:227], v[186:193], v[70:73]
	v_mfma_f32_16x16x128_f8f6f4 v[66:69], v[228:235], v[186:193], v[66:69]
	v_mfma_f32_16x16x128_f8f6f4 v[54:57], v[220:227], v[194:201], v[54:57]
	v_mfma_f32_16x16x128_f8f6f4 v[50:53], v[228:235], v[194:201], v[50:53]
	v_mfma_f32_16x16x128_f8f6f4 v[38:41], v[220:227], v[202:209], v[38:41]
	v_mfma_f32_16x16x128_f8f6f4 v[34:37], v[228:235], v[202:209], v[34:37]
	v_mfma_f32_16x16x128_f8f6f4 v[22:25], v[220:227], v[210:217], v[22:25]
	v_mfma_f32_16x16x128_f8f6f4 v[18:21], v[228:235], v[210:217], v[18:21]
	s_setprio 0
	s_add_i32 s77, s77, 2
	s_add_u32 s75, s75, 0x100
	s_addc_u32 s76, s76, 0
	s_add_u32 s38, s38, 0x100
	s_addc_u32 s39, s39, 0
	s_cmp_gt_u32 s77, 5
	s_barrier
	s_cbranch_scc0 .LBB0_1551
	v_bfe_u32 v192, v0, 4, 1
	v_mul_u32_u24_e32 v192, 24, v192
	v_mov_b32_e32 v193, 0
	v_lshl_or_b32 v10, s72, 8, v183
	v_ashrrev_i32_e32 v11, 31, v10
	s_nop 15
	s_nop 15
	v_lshl_add_u64 v[14:15], v[10:11], 2, s[16:17]
	global_load_dwordx4 v[158:161], v[14:15], off
	global_load_dwordx4 v[162:165], v[14:15], off offset:64
	global_load_dwordx4 v[6:9], v[14:15], off offset:512
	global_load_dwordx4 v[2:5], v[14:15], off offset:576
	v_lshl_add_u32 v16, s36, 8, v166
	v_mov_b64_e32 v[12:13], s[14:15]
	v_mad_i64_i32 v[186:187], s[38:39], v16, s71, v[12:13]
	v_lshlrev_b64 v[10:11], 1, v[10:11]
	v_lshl_add_u64 v[186:187], v[186:187], 0, v[10:11]
	s_and_b64 vcc, exec, s[10:11]
	s_mov_b32 s72, s26
	s_mov_b32 s36, s28
	s_mov_b64 s[40:41], s[30:31]
	s_waitcnt vmcnt(0)
	v_pk_fma_f32 v[144:145], v[144:145], s[22:23], v[160:161] op_sel_hi:[1,0,1]
	v_pk_fma_f32 v[142:143], v[142:143], s[22:23], v[158:159] op_sel_hi:[1,0,1]
	v_pk_fma_f32 v[140:141], v[140:141], s[22:23], v[164:165] op_sel_hi:[1,0,1]
	v_pk_fma_f32 v[138:139], v[138:139], s[22:23], v[162:163] op_sel_hi:[1,0,1]
	v_pk_fma_f32 v[136:137], v[136:137], s[22:23], v[8:9] op_sel_hi:[1,0,1]
	v_pk_fma_f32 v[134:135], v[134:135], s[22:23], v[6:7] op_sel_hi:[1,0,1]
	v_mul_f32_e32 v17, 0xbfb8aa3b, v142
	v_mul_f32_e32 v142, 0xbfb8aa3b, v143
	v_mul_f32_e32 v143, 0xbfb8aa3b, v144
	v_mul_f32_e32 v144, 0xbfb8aa3b, v145
	v_mul_f32_e32 v138, 0xbfb8aa3b, v138
	v_mul_f32_e32 v139, 0xbfb8aa3b, v139
	v_mul_f32_e32 v140, 0xbfb8aa3b, v140
	v_mul_f32_e32 v141, 0xbfb8aa3b, v141
	v_mul_f32_e32 v134, 0xbfb8aa3b, v134
	v_mul_f32_e32 v135, 0xbfb8aa3b, v135
	v_mul_f32_e32 v136, 0xbfb8aa3b, v136
	v_mul_f32_e32 v137, 0xbfb8aa3b, v137
	v_exp_f32_e32 v17, v17
	v_exp_f32_e32 v142, v142
	v_exp_f32_e32 v143, v143
	v_exp_f32_e32 v144, v144
	v_exp_f32_e32 v138, v138
	v_exp_f32_e32 v139, v139
	v_exp_f32_e32 v140, v140
	v_exp_f32_e32 v141, v141
	v_exp_f32_e32 v134, v134
	v_exp_f32_e32 v135, v135
	v_exp_f32_e32 v136, v136
	v_exp_f32_e32 v137, v137
	v_pk_fma_f32 v[130:131], v[130:131], s[22:23], v[2:3] op_sel_hi:[1,0,1]
	v_pk_fma_f32 v[132:133], v[132:133], s[22:23], v[4:5] op_sel_hi:[1,0,1]
	v_mul_f32_e32 v130, 0xbfb8aa3b, v130
	v_mul_f32_e32 v131, 0xbfb8aa3b, v131
	v_mul_f32_e32 v132, 0xbfb8aa3b, v132
	v_mul_f32_e32 v133, 0xbfb8aa3b, v133
	v_exp_f32_e32 v130, v130
	v_exp_f32_e32 v131, v131
	v_add_f32_e32 v17, 1.0, v17
	v_add_f32_e32 v142, 1.0, v142
	v_add_f32_e32 v143, 1.0, v143
	v_add_f32_e32 v144, 1.0, v144
	v_exp_f32_e32 v132, v132
	v_exp_f32_e32 v133, v133
	v_add_f32_e32 v138, 1.0, v138
	v_add_f32_e32 v139, 1.0, v139
	v_add_f32_e32 v140, 1.0, v140
	v_add_f32_e32 v141, 1.0, v141
	v_add_f32_e32 v134, 1.0, v134
	v_add_f32_e32 v135, 1.0, v135
	v_add_f32_e32 v136, 1.0, v136
	v_add_f32_e32 v137, 1.0, v137
	v_rcp_f32_e32 v17, v17
	v_rcp_f32_e32 v142, v142
	v_rcp_f32_e32 v143, v143
	v_rcp_f32_e32 v144, v144
	v_rcp_f32_e32 v138, v138
	v_rcp_f32_e32 v139, v139
	v_rcp_f32_e32 v140, v140
	v_rcp_f32_e32 v141, v141
	v_rcp_f32_e32 v134, v134
	v_rcp_f32_e32 v135, v135
	v_rcp_f32_e32 v136, v136
	v_rcp_f32_e32 v137, v137
	v_add_f32_e32 v130, 1.0, v130
	v_add_f32_e32 v131, 1.0, v131
	v_pk_fma_f32 v[126:127], v[126:127], s[22:23], v[158:159] op_sel_hi:[1,0,1]
	v_add_f32_e32 v132, 1.0, v132
	v_add_f32_e32 v133, 1.0, v133
	v_rcp_f32_e32 v145, v130
	v_rcp_f32_e32 v185, v131
	v_cvt_pk_bf16_f32 v130, v17, v142
	v_cvt_pk_bf16_f32 v131, v143, v144
	v_mul_f32_e32 v17, 0xbfb8aa3b, v126
	v_mul_f32_e32 v126, 0xbfb8aa3b, v127
	v_rcp_f32_e32 v188, v132
	v_rcp_f32_e32 v189, v133
	v_cvt_pk_bf16_f32 v132, v138, v139
	v_cvt_pk_bf16_f32 v133, v140, v141
	v_cvt_pk_bf16_f32 v134, v134, v135
	v_cvt_pk_bf16_f32 v135, v136, v137
	v_mov_b32_e32 v196, v130
	v_mov_b32_e32 v197, v131
	v_mov_b32_e32 v198, v132
	v_mov_b32_e32 v199, v133
	v_lshl_add_u64 v[194:195], v[186:187], 0, v[192:193]
	s_nop 0
	v_permlane16_swap_b32 v196, v198
	v_permlane16_swap_b32 v197, v199
	global_store_dwordx4 v[194:195], v[196:199], off
	v_mov_b32_e32 v200, v134
	v_mov_b32_e32 v201, v135
	v_exp_f32_e32 v130, v126
	v_pk_fma_f32 v[126:127], v[128:129], s[22:23], v[160:161] op_sel_hi:[1,0,1]
	v_exp_f32_e32 v17, v17
	v_mul_f32_e32 v126, 0xbfb8aa3b, v126
	v_exp_f32_e32 v126, v126
	v_mul_f32_e32 v127, 0xbfb8aa3b, v127
	v_exp_f32_e32 v127, v127
	v_add_f32_e32 v17, 1.0, v17
	v_add_f32_e32 v128, 1.0, v130
	v_add_f32_e32 v126, 1.0, v126
	v_rcp_f32_e32 v17, v17
	v_rcp_f32_e32 v128, v128
	v_rcp_f32_e32 v129, v126
	v_add_f32_e32 v126, 1.0, v127
	v_rcp_f32_e32 v127, v126
	v_pk_fma_f32 v[122:123], v[122:123], s[22:23], v[162:163] op_sel_hi:[1,0,1]
	v_or_b32_e32 v130, 16, v16
	v_cvt_pk_bf16_f32 v126, v17, v128
	v_mul_f32_e32 v17, 0xbfb8aa3b, v122
	v_mul_f32_e32 v122, 0xbfb8aa3b, v123
	v_cvt_pk_bf16_f32 v127, v129, v127
	v_mad_i64_i32 v[128:129], s[38:39], v130, s71, v[12:13]
	v_exp_f32_e32 v17, v17
	v_exp_f32_e32 v130, v122
	v_pk_fma_f32 v[122:123], v[124:125], s[22:23], v[164:165] op_sel_hi:[1,0,1]
	v_pk_fma_f32 v[6:7], v[118:119], s[22:23], v[6:7] op_sel_hi:[1,0,1]
	v_add_f32_e32 v17, 1.0, v17
	v_add_f32_e32 v124, 1.0, v130
	v_rcp_f32_e32 v17, v17
	v_rcp_f32_e32 v124, v124
	v_mul_f32_e32 v6, 0xbfb8aa3b, v6
	v_pk_fma_f32 v[2:3], v[114:115], s[22:23], v[2:3] op_sel_hi:[1,0,1]
	v_mul_f32_e32 v122, 0xbfb8aa3b, v122
	v_cvt_pk_bf16_f32 v124, v17, v124
	v_exp_f32_e32 v17, v6
	v_mul_f32_e32 v6, 0xbfb8aa3b, v7
	v_exp_f32_e32 v118, v6
	v_pk_fma_f32 v[6:7], v[120:121], s[22:23], v[8:9] op_sel_hi:[1,0,1]
	v_add_f32_e32 v8, 1.0, v17
	v_rcp_f32_e32 v8, v8
	v_add_f32_e32 v9, 1.0, v118
	v_rcp_f32_e32 v9, v9
	v_mul_f32_e32 v6, 0xbfb8aa3b, v6
	v_exp_f32_e32 v17, v6
	v_mul_f32_e32 v6, 0xbfb8aa3b, v7
	v_mul_f32_e32 v2, 0xbfb8aa3b, v2
	v_exp_f32_e32 v7, v6
	v_cvt_pk_bf16_f32 v6, v8, v9
	v_exp_f32_e32 v9, v2
	v_mul_f32_e32 v2, 0xbfb8aa3b, v3
	v_add_f32_e32 v8, 1.0, v17
	v_exp_f32_e32 v17, v2
	v_pk_fma_f32 v[2:3], v[116:117], s[22:23], v[4:5] op_sel_hi:[1,0,1]
	v_exp_f32_e32 v122, v122
	v_mul_f32_e32 v2, 0xbfb8aa3b, v2
	v_mul_f32_e32 v123, 0xbfb8aa3b, v123
	v_exp_f32_e32 v2, v2
	v_mul_f32_e32 v3, 0xbfb8aa3b, v3
	v_exp_f32_e32 v123, v123
	v_exp_f32_e32 v3, v3
	v_add_f32_e32 v122, 1.0, v122
	v_add_f32_e32 v2, 1.0, v2
	v_rcp_f32_e32 v125, v122
	v_add_f32_e32 v122, 1.0, v123
	v_add_f32_e32 v7, 1.0, v7
	v_add_f32_e32 v4, 1.0, v9
	v_add_f32_e32 v5, 1.0, v17
	v_rcp_f32_e32 v9, v2
	v_add_f32_e32 v2, 1.0, v3
	v_rcp_f32_e32 v130, v122
	v_rcp_f32_e32 v8, v8
	v_rcp_f32_e32 v7, v7
	v_rcp_f32_e32 v4, v4
	v_rcp_f32_e32 v5, v5
	v_rcp_f32_e32 v3, v2
	v_cvt_pk_bf16_f32 v136, v145, v185
	v_cvt_pk_bf16_f32 v137, v188, v189
	v_lshl_add_u64 v[122:123], v[128:129], 0, v[10:11]
	v_cvt_pk_bf16_f32 v125, v125, v130
	v_cvt_pk_bf16_f32 v7, v8, v7
	v_cvt_pk_bf16_f32 v2, v4, v5
	v_cvt_pk_bf16_f32 v3, v9, v3
	v_mov_b32_e32 v202, v136
	v_mov_b32_e32 v203, v137
	v_lshl_add_u64 v[194:195], v[186:187], 0, v[192:193]
	s_nop 0
	v_permlane16_swap_b32 v200, v202
	v_permlane16_swap_b32 v201, v203
	global_store_dwordx4 v[194:195], v[200:203], off offset:256
	v_mov_b32_e32 v204, v126
	v_mov_b32_e32 v205, v127
	v_mov_b32_e32 v206, v124
	v_mov_b32_e32 v207, v125
	v_lshl_add_u64 v[194:195], v[122:123], 0, v[192:193]
	s_nop 0
	v_permlane16_swap_b32 v204, v206
	v_permlane16_swap_b32 v205, v207
	global_store_dwordx4 v[194:195], v[204:207], off
	v_mov_b32_e32 v208, v6
	v_mov_b32_e32 v209, v7
	v_mov_b32_e32 v210, v2
	v_mov_b32_e32 v211, v3
	v_lshl_add_u64 v[194:195], v[122:123], 0, v[192:193]
	s_nop 0
	v_permlane16_swap_b32 v208, v210
	v_permlane16_swap_b32 v209, v211
	global_store_dwordx4 v[194:195], v[208:211], off offset:256
	global_load_dwordx4 v[6:9], v[14:15], off
	s_nop 0
	global_load_dwordx4 v[114:117], v[14:15], off offset:64
	global_load_dwordx4 v[118:121], v[14:15], off offset:512
	global_load_dwordx4 v[2:5], v[14:15], off offset:576
	s_waitcnt vmcnt(0)
	v_pk_fma_f32 v[110:111], v[110:111], s[22:23], v[6:7] op_sel_hi:[1,0,1]
	s_nop 0
	v_mul_f32_e32 v17, 0xbfb8aa3b, v110
	v_mul_f32_e32 v110, 0xbfb8aa3b, v111
	v_exp_f32_e32 v122, v110
	v_pk_fma_f32 v[110:111], v[112:113], s[22:23], v[8:9] op_sel_hi:[1,0,1]
	v_exp_f32_e32 v17, v17
	v_mul_f32_e32 v110, 0xbfb8aa3b, v110
	v_exp_f32_e32 v110, v110
	v_mul_f32_e32 v111, 0xbfb8aa3b, v111
	v_exp_f32_e32 v111, v111
	v_add_f32_e32 v17, 1.0, v17
	v_add_f32_e32 v112, 1.0, v122
	v_add_f32_e32 v110, 1.0, v110
	v_rcp_f32_e32 v17, v17
	v_rcp_f32_e32 v112, v112
	v_rcp_f32_e32 v113, v110
	v_add_f32_e32 v110, 1.0, v111
	v_rcp_f32_e32 v111, v110
	v_pk_fma_f32 v[106:107], v[106:107], s[22:23], v[114:115] op_sel_hi:[1,0,1]
	v_or_b32_e32 v122, 32, v16
	v_cvt_pk_bf16_f32 v110, v17, v112
	v_mul_f32_e32 v17, 0xbfb8aa3b, v106
	v_mul_f32_e32 v106, 0xbfb8aa3b, v107
	v_cvt_pk_bf16_f32 v111, v113, v111
	v_mad_i64_i32 v[112:113], s[38:39], v122, s71, v[12:13]
	v_exp_f32_e32 v122, v106
	v_pk_fma_f32 v[106:107], v[108:109], s[22:23], v[116:117] op_sel_hi:[1,0,1]
	v_exp_f32_e32 v17, v17
	v_mul_f32_e32 v106, 0xbfb8aa3b, v106
	v_exp_f32_e32 v106, v106
	v_mul_f32_e32 v107, 0xbfb8aa3b, v107
	v_exp_f32_e32 v107, v107
	v_add_f32_e32 v17, 1.0, v17
	v_add_f32_e32 v106, 1.0, v106
	v_add_f32_e32 v108, 1.0, v122
	v_rcp_f32_e32 v109, v106
	v_add_f32_e32 v106, 1.0, v107
	v_rcp_f32_e32 v17, v17
	v_rcp_f32_e32 v108, v108
	v_rcp_f32_e32 v122, v106
	v_pk_fma_f32 v[102:103], v[102:103], s[22:23], v[118:119] op_sel_hi:[1,0,1]
	v_lshl_add_u64 v[106:107], v[112:113], 0, v[10:11]
	v_cvt_pk_bf16_f32 v108, v17, v108
	v_cvt_pk_bf16_f32 v109, v109, v122
	v_mul_f32_e32 v17, 0xbfb8aa3b, v102
	v_mul_f32_e32 v102, 0xbfb8aa3b, v103
	v_mov_b32_e32 v214, v108
	v_mov_b32_e32 v215, v109
	v_exp_f32_e32 v17, v17
	v_exp_f32_e32 v108, v102
	v_pk_fma_f32 v[102:103], v[104:105], s[22:23], v[120:121] op_sel_hi:[1,0,1]
	v_pk_fma_f32 v[6:7], v[94:95], s[22:23], v[6:7] op_sel_hi:[1,0,1]
	v_mul_f32_e32 v102, 0xbfb8aa3b, v102
	v_add_f32_e32 v17, 1.0, v17
	v_add_f32_e32 v104, 1.0, v108
	v_exp_f32_e32 v105, v102
	v_mul_f32_e32 v102, 0xbfb8aa3b, v103
	v_rcp_f32_e32 v17, v17
	v_rcp_f32_e32 v104, v104
	v_exp_f32_e32 v103, v102
	v_mul_f32_e32 v6, 0xbfb8aa3b, v6
	v_pk_fma_f32 v[90:91], v[90:91], s[22:23], v[114:115] op_sel_hi:[1,0,1]
	v_cvt_pk_bf16_f32 v102, v17, v104
	v_add_f32_e32 v17, 1.0, v105
	v_add_f32_e32 v103, 1.0, v103
	v_rcp_f32_e32 v17, v17
	v_rcp_f32_e32 v103, v103
	v_pk_fma_f32 v[98:99], v[98:99], s[22:23], v[2:3] op_sel_hi:[1,0,1]
	v_pk_fma_f32 v[2:3], v[82:83], s[22:23], v[2:3] op_sel_hi:[1,0,1]
	v_mul_f32_e32 v98, 0xbfb8aa3b, v98
	v_cvt_pk_bf16_f32 v103, v17, v103
	v_exp_f32_e32 v17, v6
	v_mul_f32_e32 v6, 0xbfb8aa3b, v7
	v_exp_f32_e32 v94, v6
	v_pk_fma_f32 v[6:7], v[96:97], s[22:23], v[8:9] op_sel_hi:[1,0,1]
	v_add_f32_e32 v8, 1.0, v17
	v_mul_f32_e32 v6, 0xbfb8aa3b, v6
	v_exp_f32_e32 v6, v6
	v_mul_f32_e32 v7, 0xbfb8aa3b, v7
	v_exp_f32_e32 v7, v7
	v_add_f32_e32 v9, 1.0, v94
	v_add_f32_e32 v6, 1.0, v6
	v_rcp_f32_e32 v17, v6
	v_add_f32_e32 v6, 1.0, v7
	v_rcp_f32_e32 v7, v6
	v_rcp_f32_e32 v8, v8
	v_rcp_f32_e32 v9, v9
	v_or_b32_e32 v94, 48, v16
	v_cvt_pk_bf16_f32 v7, v17, v7
	v_mul_f32_e32 v17, 0xbfb8aa3b, v90
	v_mul_f32_e32 v90, 0xbfb8aa3b, v91
	v_cvt_pk_bf16_f32 v6, v8, v9
	v_mad_i64_i32 v[8:9], s[38:39], v94, s71, v[12:13]
	v_exp_f32_e32 v94, v90
	v_pk_fma_f32 v[90:91], v[92:93], s[22:23], v[116:117] op_sel_hi:[1,0,1]
	v_exp_f32_e32 v17, v17
	v_mul_f32_e32 v90, 0xbfb8aa3b, v90
	v_mul_f32_e32 v91, 0xbfb8aa3b, v91
	v_exp_f32_e32 v90, v90
	v_exp_f32_e32 v91, v91
	v_add_f32_e32 v17, 1.0, v17
	v_add_f32_e32 v92, 1.0, v94
	v_add_f32_e32 v90, 1.0, v90
	v_add_f32_e32 v91, 1.0, v91
	v_rcp_f32_e32 v17, v17
	v_rcp_f32_e32 v92, v92
	v_rcp_f32_e32 v90, v90
	v_rcp_f32_e32 v91, v91
	v_lshl_add_u64 v[8:9], v[8:9], 0, v[10:11]
	v_mov_b32_e32 v220, v6
	v_mov_b32_e32 v221, v7
	v_cvt_pk_bf16_f32 v6, v17, v92
	v_cvt_pk_bf16_f32 v7, v90, v91
	v_mov_b32_e32 v222, v6
	v_mov_b32_e32 v223, v7
	v_lshl_add_u64 v[194:195], v[8:9], 0, v[192:193]
	s_nop 0
	v_permlane16_swap_b32 v220, v222
	v_permlane16_swap_b32 v221, v223
	global_store_dwordx4 v[194:195], v[220:223], off
	v_pk_fma_f32 v[6:7], v[86:87], s[22:23], v[118:119] op_sel_hi:[1,0,1]
	v_mul_f32_e32 v2, 0xbfb8aa3b, v2
	v_mul_f32_e32 v6, 0xbfb8aa3b, v6
	v_exp_f32_e32 v17, v6
	v_mul_f32_e32 v6, 0xbfb8aa3b, v7
	v_exp_f32_e32 v86, v6
	v_exp_f32_e32 v104, v98
	v_mul_f32_e32 v98, 0xbfb8aa3b, v99
	v_exp_f32_e32 v82, v2
	v_mul_f32_e32 v2, 0xbfb8aa3b, v3
	v_exp_f32_e32 v105, v98
	v_pk_fma_f32 v[98:99], v[100:101], s[22:23], v[4:5] op_sel_hi:[1,0,1]
	v_pk_fma_f32 v[6:7], v[88:89], s[22:23], v[120:121] op_sel_hi:[1,0,1]
	v_exp_f32_e32 v83, v2
	v_pk_fma_f32 v[2:3], v[84:85], s[22:23], v[4:5] op_sel_hi:[1,0,1]
	v_mul_f32_e32 v98, 0xbfb8aa3b, v98
	v_mul_f32_e32 v6, 0xbfb8aa3b, v6
	v_mul_f32_e32 v2, 0xbfb8aa3b, v2
	v_exp_f32_e32 v98, v98
	v_mul_f32_e32 v99, 0xbfb8aa3b, v99
	v_add_f32_e32 v17, 1.0, v17
	v_add_f32_e32 v86, 1.0, v86
	v_exp_f32_e32 v87, v6
	v_mul_f32_e32 v6, 0xbfb8aa3b, v7
	v_exp_f32_e32 v2, v2
	v_mul_f32_e32 v3, 0xbfb8aa3b, v3
	v_exp_f32_e32 v99, v99
	v_rcp_f32_e32 v17, v17
	v_rcp_f32_e32 v86, v86
	v_exp_f32_e32 v7, v6
	v_exp_f32_e32 v3, v3
	v_add_f32_e32 v98, 1.0, v98
	v_add_f32_e32 v2, 1.0, v2
	v_add_f32_e32 v100, 1.0, v104
	v_add_f32_e32 v101, 1.0, v105
	v_rcp_f32_e32 v104, v98
	v_add_f32_e32 v98, 1.0, v99
	v_cvt_pk_bf16_f32 v6, v17, v86
	v_add_f32_e32 v17, 1.0, v87
	v_add_f32_e32 v7, 1.0, v7
	v_add_f32_e32 v4, 1.0, v82
	v_add_f32_e32 v5, 1.0, v83
	v_rcp_f32_e32 v82, v2
	v_add_f32_e32 v2, 1.0, v3
	v_rcp_f32_e32 v100, v100
	v_rcp_f32_e32 v101, v101
	v_rcp_f32_e32 v99, v98
	v_rcp_f32_e32 v17, v17
	v_rcp_f32_e32 v7, v7
	v_rcp_f32_e32 v4, v4
	v_rcp_f32_e32 v5, v5
	v_rcp_f32_e32 v3, v2
	v_cvt_pk_bf16_f32 v98, v100, v101
	v_cvt_pk_bf16_f32 v99, v104, v99
	v_cvt_pk_bf16_f32 v7, v17, v7
	v_cvt_pk_bf16_f32 v2, v4, v5
	v_cvt_pk_bf16_f32 v3, v82, v3
	v_mov_b32_e32 v212, v110
	v_mov_b32_e32 v213, v111
	v_lshl_add_u64 v[194:195], v[106:107], 0, v[192:193]
	s_nop 0
	v_permlane16_swap_b32 v212, v214
	v_permlane16_swap_b32 v213, v215
	global_store_dwordx4 v[194:195], v[212:215], off
	v_mov_b32_e32 v224, v102
	v_mov_b32_e32 v225, v103
	v_mov_b32_e32 v226, v98
	v_mov_b32_e32 v227, v99
	v_lshl_add_u64 v[194:195], v[106:107], 0, v[192:193]
	s_nop 0
	v_permlane16_swap_b32 v224, v226
	v_permlane16_swap_b32 v225, v227
	global_store_dwordx4 v[194:195], v[224:227], off offset:256
	v_mov_b32_e32 v232, v6
	v_mov_b32_e32 v233, v7
	v_mov_b32_e32 v234, v2
	v_mov_b32_e32 v235, v3
	v_lshl_add_u64 v[194:195], v[8:9], 0, v[192:193]
	s_nop 0
	v_permlane16_swap_b32 v232, v234
	v_permlane16_swap_b32 v233, v235
	global_store_dwordx4 v[194:195], v[232:235], off offset:256
	global_load_dwordx4 v[6:9], v[14:15], off
	s_nop 0
	global_load_dwordx4 v[82:85], v[14:15], off offset:64
	global_load_dwordx4 v[86:89], v[14:15], off offset:512
	global_load_dwordx4 v[2:5], v[14:15], off offset:576
	s_waitcnt vmcnt(0)
	v_pk_fma_f32 v[78:79], v[78:79], s[22:23], v[6:7] op_sel_hi:[1,0,1]
	s_nop 0
	v_mul_f32_e32 v17, 0xbfb8aa3b, v78
	v_mul_f32_e32 v78, 0xbfb8aa3b, v79
	v_exp_f32_e32 v90, v78
	v_pk_fma_f32 v[78:79], v[80:81], s[22:23], v[8:9] op_sel_hi:[1,0,1]
	v_exp_f32_e32 v17, v17
	v_mul_f32_e32 v78, 0xbfb8aa3b, v78
	v_exp_f32_e32 v78, v78
	v_mul_f32_e32 v79, 0xbfb8aa3b, v79
	v_exp_f32_e32 v79, v79
	v_add_f32_e32 v17, 1.0, v17
	v_add_f32_e32 v80, 1.0, v90
	v_add_f32_e32 v78, 1.0, v78
	v_rcp_f32_e32 v17, v17
	v_rcp_f32_e32 v80, v80
	v_rcp_f32_e32 v81, v78
	v_add_f32_e32 v78, 1.0, v79
	v_rcp_f32_e32 v79, v78
	v_pk_fma_f32 v[74:75], v[74:75], s[22:23], v[82:83] op_sel_hi:[1,0,1]
	v_add_u32_e32 v90, 0x80, v16
	v_cvt_pk_bf16_f32 v78, v17, v80
	v_mul_f32_e32 v17, 0xbfb8aa3b, v74
	v_mul_f32_e32 v74, 0xbfb8aa3b, v75
	v_cvt_pk_bf16_f32 v79, v81, v79
	v_mad_i64_i32 v[80:81], s[38:39], v90, s71, v[12:13]
	v_exp_f32_e32 v90, v74
	v_pk_fma_f32 v[74:75], v[76:77], s[22:23], v[84:85] op_sel_hi:[1,0,1]
	v_exp_f32_e32 v17, v17
	v_mul_f32_e32 v74, 0xbfb8aa3b, v74
	v_exp_f32_e32 v74, v74
	v_mul_f32_e32 v75, 0xbfb8aa3b, v75
	v_exp_f32_e32 v75, v75
	v_add_f32_e32 v17, 1.0, v17
	v_add_f32_e32 v74, 1.0, v74
	v_add_f32_e32 v76, 1.0, v90
	v_rcp_f32_e32 v77, v74
	v_add_f32_e32 v74, 1.0, v75
	v_rcp_f32_e32 v17, v17
	v_rcp_f32_e32 v76, v76
	v_rcp_f32_e32 v90, v74
	v_pk_fma_f32 v[70:71], v[70:71], s[22:23], v[86:87] op_sel_hi:[1,0,1]
	v_lshl_add_u64 v[74:75], v[80:81], 0, v[10:11]
	v_cvt_pk_bf16_f32 v76, v17, v76
	v_cvt_pk_bf16_f32 v77, v77, v90
	v_mul_f32_e32 v17, 0xbfb8aa3b, v70
	v_mul_f32_e32 v70, 0xbfb8aa3b, v71
	v_mov_b32_e32 v238, v76
	v_mov_b32_e32 v239, v77
	v_exp_f32_e32 v17, v17
	v_exp_f32_e32 v76, v70
	v_pk_fma_f32 v[70:71], v[72:73], s[22:23], v[88:89] op_sel_hi:[1,0,1]
	v_pk_fma_f32 v[6:7], v[62:63], s[22:23], v[6:7] op_sel_hi:[1,0,1]
	v_mul_f32_e32 v70, 0xbfb8aa3b, v70
	v_add_f32_e32 v17, 1.0, v17
	v_add_f32_e32 v72, 1.0, v76
	v_exp_f32_e32 v73, v70
	v_mul_f32_e32 v70, 0xbfb8aa3b, v71
	v_rcp_f32_e32 v17, v17
	v_rcp_f32_e32 v72, v72
	v_exp_f32_e32 v71, v70
	v_mul_f32_e32 v6, 0xbfb8aa3b, v6
	v_pk_fma_f32 v[58:59], v[58:59], s[22:23], v[82:83] op_sel_hi:[1,0,1]
	v_cvt_pk_bf16_f32 v70, v17, v72
	v_add_f32_e32 v17, 1.0, v73
	v_add_f32_e32 v71, 1.0, v71
	v_rcp_f32_e32 v17, v17
	v_rcp_f32_e32 v71, v71
	v_pk_fma_f32 v[66:67], v[66:67], s[22:23], v[2:3] op_sel_hi:[1,0,1]
	v_pk_fma_f32 v[2:3], v[50:51], s[22:23], v[2:3] op_sel_hi:[1,0,1]
	v_mul_f32_e32 v66, 0xbfb8aa3b, v66
	v_cvt_pk_bf16_f32 v71, v17, v71
	v_exp_f32_e32 v17, v6
	v_mul_f32_e32 v6, 0xbfb8aa3b, v7
	v_exp_f32_e32 v62, v6
	v_pk_fma_f32 v[6:7], v[64:65], s[22:23], v[8:9] op_sel_hi:[1,0,1]
	v_add_f32_e32 v8, 1.0, v17
	v_mul_f32_e32 v6, 0xbfb8aa3b, v6
	v_exp_f32_e32 v6, v6
	v_mul_f32_e32 v7, 0xbfb8aa3b, v7
	v_exp_f32_e32 v7, v7
	v_add_f32_e32 v9, 1.0, v62
	v_add_f32_e32 v6, 1.0, v6
	v_rcp_f32_e32 v17, v6
	v_add_f32_e32 v6, 1.0, v7
	v_rcp_f32_e32 v7, v6
	v_rcp_f32_e32 v8, v8
	v_rcp_f32_e32 v9, v9
	v_add_u32_e32 v62, 0x90, v16
	v_cvt_pk_bf16_f32 v7, v17, v7
	v_mul_f32_e32 v17, 0xbfb8aa3b, v58
	v_mul_f32_e32 v58, 0xbfb8aa3b, v59
	v_cvt_pk_bf16_f32 v6, v8, v9
	v_mad_i64_i32 v[8:9], s[38:39], v62, s71, v[12:13]
	v_exp_f32_e32 v62, v58
	v_pk_fma_f32 v[58:59], v[60:61], s[22:23], v[84:85] op_sel_hi:[1,0,1]
	v_exp_f32_e32 v17, v17
	v_mul_f32_e32 v58, 0xbfb8aa3b, v58
	v_mul_f32_e32 v59, 0xbfb8aa3b, v59
	v_exp_f32_e32 v58, v58
	v_exp_f32_e32 v59, v59
	v_add_f32_e32 v17, 1.0, v17
	v_add_f32_e32 v60, 1.0, v62
	v_add_f32_e32 v58, 1.0, v58
	v_add_f32_e32 v59, 1.0, v59
	v_rcp_f32_e32 v17, v17
	v_rcp_f32_e32 v60, v60
	v_rcp_f32_e32 v58, v58
	v_rcp_f32_e32 v59, v59
	v_lshl_add_u64 v[8:9], v[8:9], 0, v[10:11]
	v_mov_b32_e32 v240, v6
	v_mov_b32_e32 v241, v7
	v_cvt_pk_bf16_f32 v6, v17, v60
	v_cvt_pk_bf16_f32 v7, v58, v59
	v_mov_b32_e32 v242, v6
	v_mov_b32_e32 v243, v7
	v_lshl_add_u64 v[194:195], v[8:9], 0, v[192:193]
	s_nop 0
	v_permlane16_swap_b32 v240, v242
	v_permlane16_swap_b32 v241, v243
	global_store_dwordx4 v[194:195], v[240:243], off
	v_pk_fma_f32 v[6:7], v[54:55], s[22:23], v[86:87] op_sel_hi:[1,0,1]
	v_mul_f32_e32 v2, 0xbfb8aa3b, v2
	v_mul_f32_e32 v6, 0xbfb8aa3b, v6
	v_exp_f32_e32 v17, v6
	v_mul_f32_e32 v6, 0xbfb8aa3b, v7
	v_exp_f32_e32 v54, v6
	v_exp_f32_e32 v72, v66
	v_mul_f32_e32 v66, 0xbfb8aa3b, v67
	v_exp_f32_e32 v50, v2
	v_mul_f32_e32 v2, 0xbfb8aa3b, v3
	v_exp_f32_e32 v73, v66
	v_pk_fma_f32 v[66:67], v[68:69], s[22:23], v[4:5] op_sel_hi:[1,0,1]
	v_pk_fma_f32 v[6:7], v[56:57], s[22:23], v[88:89] op_sel_hi:[1,0,1]
	v_exp_f32_e32 v51, v2
	v_pk_fma_f32 v[2:3], v[52:53], s[22:23], v[4:5] op_sel_hi:[1,0,1]
	v_mul_f32_e32 v66, 0xbfb8aa3b, v66
	v_mul_f32_e32 v6, 0xbfb8aa3b, v6
	v_mul_f32_e32 v2, 0xbfb8aa3b, v2
	v_exp_f32_e32 v66, v66
	v_mul_f32_e32 v67, 0xbfb8aa3b, v67
	v_add_f32_e32 v17, 1.0, v17
	v_add_f32_e32 v54, 1.0, v54
	v_exp_f32_e32 v55, v6
	v_mul_f32_e32 v6, 0xbfb8aa3b, v7
	v_exp_f32_e32 v2, v2
	v_mul_f32_e32 v3, 0xbfb8aa3b, v3
	v_exp_f32_e32 v67, v67
	v_rcp_f32_e32 v17, v17
	v_rcp_f32_e32 v54, v54
	v_exp_f32_e32 v7, v6
	v_exp_f32_e32 v3, v3
	v_add_f32_e32 v66, 1.0, v66
	v_add_f32_e32 v2, 1.0, v2
	v_add_f32_e32 v68, 1.0, v72
	v_add_f32_e32 v69, 1.0, v73
	v_rcp_f32_e32 v72, v66
	v_add_f32_e32 v66, 1.0, v67
	v_cvt_pk_bf16_f32 v6, v17, v54
	v_add_f32_e32 v17, 1.0, v55
	v_add_f32_e32 v7, 1.0, v7
	v_add_f32_e32 v4, 1.0, v50
	v_add_f32_e32 v5, 1.0, v51
	v_rcp_f32_e32 v50, v2
	v_add_f32_e32 v2, 1.0, v3
	v_rcp_f32_e32 v68, v68
	v_rcp_f32_e32 v69, v69
	v_rcp_f32_e32 v67, v66
	v_rcp_f32_e32 v17, v17
	v_rcp_f32_e32 v7, v7
	v_rcp_f32_e32 v4, v4
	v_rcp_f32_e32 v5, v5
	v_rcp_f32_e32 v3, v2
	v_cvt_pk_bf16_f32 v66, v68, v69
	v_cvt_pk_bf16_f32 v67, v72, v67
	v_cvt_pk_bf16_f32 v7, v17, v7
	v_cvt_pk_bf16_f32 v2, v4, v5
	v_cvt_pk_bf16_f32 v3, v50, v3
	v_mov_b32_e32 v236, v78
	v_mov_b32_e32 v237, v79
	v_lshl_add_u64 v[194:195], v[74:75], 0, v[192:193]
	s_nop 0
	v_permlane16_swap_b32 v236, v238
	v_permlane16_swap_b32 v237, v239
	global_store_dwordx4 v[194:195], v[236:239], off
	v_mov_b32_e32 v244, v70
	v_mov_b32_e32 v245, v71
	v_mov_b32_e32 v246, v66
	v_mov_b32_e32 v247, v67
	v_lshl_add_u64 v[194:195], v[74:75], 0, v[192:193]
	s_nop 0
	v_permlane16_swap_b32 v244, v246
	v_permlane16_swap_b32 v245, v247
	global_store_dwordx4 v[194:195], v[244:247], off offset:256
	v_mov_b32_e32 v196, v6
	v_mov_b32_e32 v197, v7
	v_mov_b32_e32 v198, v2
	v_mov_b32_e32 v199, v3
	v_lshl_add_u64 v[194:195], v[8:9], 0, v[192:193]
	s_nop 0
	v_permlane16_swap_b32 v196, v198
	v_permlane16_swap_b32 v197, v199
	global_store_dwordx4 v[194:195], v[196:199], off offset:256
	global_load_dwordx4 v[6:9], v[14:15], off
	s_nop 0
	global_load_dwordx4 v[50:53], v[14:15], off offset:64
	global_load_dwordx4 v[54:57], v[14:15], off offset:512
	global_load_dwordx4 v[2:5], v[14:15], off offset:576
	s_waitcnt vmcnt(0)
	v_pk_fma_f32 v[14:15], v[46:47], s[22:23], v[6:7] op_sel_hi:[1,0,1]
	s_nop 0
	v_mul_f32_e32 v14, 0xbfb8aa3b, v14
	v_exp_f32_e32 v17, v14
	v_mul_f32_e32 v14, 0xbfb8aa3b, v15
	v_exp_f32_e32 v46, v14
	v_pk_fma_f32 v[14:15], v[48:49], s[22:23], v[8:9] op_sel_hi:[1,0,1]
	v_add_f32_e32 v17, 1.0, v17
	v_mul_f32_e32 v14, 0xbfb8aa3b, v14
	v_exp_f32_e32 v14, v14
	v_mul_f32_e32 v15, 0xbfb8aa3b, v15
	v_exp_f32_e32 v15, v15
	v_add_f32_e32 v46, 1.0, v46
	v_add_f32_e32 v14, 1.0, v14
	v_rcp_f32_e32 v17, v17
	v_rcp_f32_e32 v46, v46
	v_rcp_f32_e32 v47, v14
	v_add_f32_e32 v14, 1.0, v15
	v_rcp_f32_e32 v15, v14
	v_pk_fma_f32 v[42:43], v[42:43], s[22:23], v[50:51] op_sel_hi:[1,0,1]
	v_add_u32_e32 v48, 0xa0, v16
	v_cvt_pk_bf16_f32 v14, v17, v46
	v_mul_f32_e32 v17, 0xbfb8aa3b, v42
	v_mul_f32_e32 v42, 0xbfb8aa3b, v43
	v_cvt_pk_bf16_f32 v15, v47, v15
	v_mad_i64_i32 v[46:47], s[38:39], v48, s71, v[12:13]
	v_exp_f32_e32 v48, v42
	v_pk_fma_f32 v[42:43], v[44:45], s[22:23], v[52:53] op_sel_hi:[1,0,1]
	v_exp_f32_e32 v17, v17
	v_mul_f32_e32 v42, 0xbfb8aa3b, v42
	v_exp_f32_e32 v42, v42
	v_mul_f32_e32 v43, 0xbfb8aa3b, v43
	v_exp_f32_e32 v43, v43
	v_add_f32_e32 v17, 1.0, v17
	v_add_f32_e32 v42, 1.0, v42
	v_add_f32_e32 v44, 1.0, v48
	v_rcp_f32_e32 v45, v42
	v_add_f32_e32 v42, 1.0, v43
	v_rcp_f32_e32 v17, v17
	v_rcp_f32_e32 v44, v44
	v_rcp_f32_e32 v48, v42
	v_lshl_add_u64 v[42:43], v[46:47], 0, v[10:11]
	v_mov_b32_e32 v200, v14
	v_mov_b32_e32 v201, v15
	v_cvt_pk_bf16_f32 v14, v17, v44
	v_cvt_pk_bf16_f32 v15, v45, v48
	v_mov_b32_e32 v202, v14
	v_mov_b32_e32 v203, v15
	v_lshl_add_u64 v[194:195], v[42:43], 0, v[192:193]
	s_nop 0
	v_permlane16_swap_b32 v200, v202
	v_permlane16_swap_b32 v201, v203
	global_store_dwordx4 v[194:195], v[200:203], off
	v_pk_fma_f32 v[14:15], v[38:39], s[22:23], v[54:55] op_sel_hi:[1,0,1]
	v_pk_fma_f32 v[34:35], v[34:35], s[22:23], v[2:3] op_sel_hi:[1,0,1]
	v_mul_f32_e32 v14, 0xbfb8aa3b, v14
	v_exp_f32_e32 v17, v14
	v_mul_f32_e32 v14, 0xbfb8aa3b, v15
	v_exp_f32_e32 v38, v14
	v_pk_fma_f32 v[14:15], v[40:41], s[22:23], v[56:57] op_sel_hi:[1,0,1]
	v_add_f32_e32 v17, 1.0, v17
	v_mul_f32_e32 v14, 0xbfb8aa3b, v14
	v_add_f32_e32 v38, 1.0, v38
	v_exp_f32_e32 v39, v14
	v_mul_f32_e32 v14, 0xbfb8aa3b, v15
	v_rcp_f32_e32 v17, v17
	v_rcp_f32_e32 v38, v38
	v_exp_f32_e32 v15, v14
	v_mul_f32_e32 v34, 0xbfb8aa3b, v34
	v_pk_fma_f32 v[6:7], v[30:31], s[22:23], v[6:7] op_sel_hi:[1,0,1]
	v_cvt_pk_bf16_f32 v14, v17, v38
	v_add_f32_e32 v17, 1.0, v39
	v_add_f32_e32 v15, 1.0, v15
	v_rcp_f32_e32 v17, v17
	v_rcp_f32_e32 v15, v15
	v_exp_f32_e32 v38, v34
	v_mul_f32_e32 v34, 0xbfb8aa3b, v35
	v_exp_f32_e32 v39, v34
	v_pk_fma_f32 v[34:35], v[36:37], s[22:23], v[4:5] op_sel_hi:[1,0,1]
	v_mul_f32_e32 v6, 0xbfb8aa3b, v6
	v_mul_f32_e32 v34, 0xbfb8aa3b, v34
	v_mul_f32_e32 v35, 0xbfb8aa3b, v35
	v_exp_f32_e32 v34, v34
	v_exp_f32_e32 v35, v35
	v_cvt_pk_bf16_f32 v15, v17, v15
	v_exp_f32_e32 v17, v6
	v_mul_f32_e32 v6, 0xbfb8aa3b, v7
	v_exp_f32_e32 v30, v6
	v_pk_fma_f32 v[6:7], v[32:33], s[22:23], v[8:9] op_sel_hi:[1,0,1]
	v_add_f32_e32 v36, 1.0, v38
	v_add_f32_e32 v37, 1.0, v39
	v_add_f32_e32 v34, 1.0, v34
	v_add_f32_e32 v35, 1.0, v35
	v_mul_f32_e32 v6, 0xbfb8aa3b, v6
	v_rcp_f32_e32 v36, v36
	v_rcp_f32_e32 v37, v37
	v_rcp_f32_e32 v34, v34
	v_rcp_f32_e32 v35, v35
	v_exp_f32_e32 v6, v6
	v_mul_f32_e32 v7, 0xbfb8aa3b, v7
	v_add_f32_e32 v8, 1.0, v17
	v_add_f32_e32 v9, 1.0, v30
	v_exp_f32_e32 v7, v7
	v_rcp_f32_e32 v8, v8
	v_rcp_f32_e32 v9, v9
	v_mov_b32_e32 v204, v14
	v_mov_b32_e32 v205, v15
	v_cvt_pk_bf16_f32 v14, v36, v37
	v_cvt_pk_bf16_f32 v15, v34, v35
	v_add_f32_e32 v6, 1.0, v6
	v_rcp_f32_e32 v17, v6
	v_add_f32_e32 v6, 1.0, v7
	v_mov_b32_e32 v206, v14
	v_mov_b32_e32 v207, v15
	v_lshl_add_u64 v[194:195], v[42:43], 0, v[192:193]
	s_nop 0
	v_permlane16_swap_b32 v204, v206
	v_permlane16_swap_b32 v205, v207
	global_store_dwordx4 v[194:195], v[204:207], off offset:256
	v_add_u32_e32 v14, 0xb0, v16
	v_rcp_f32_e32 v7, v6
	v_cvt_pk_bf16_f32 v6, v8, v9
	v_mad_i64_i32 v[8:9], s[38:39], v14, s71, v[12:13]
	v_pk_fma_f32 v[12:13], v[26:27], s[22:23], v[50:51] op_sel_hi:[1,0,1]
	v_cvt_pk_bf16_f32 v7, v17, v7
	v_mul_f32_e32 v12, 0xbfb8aa3b, v12
	v_exp_f32_e32 v14, v12
	v_mul_f32_e32 v12, 0xbfb8aa3b, v13
	v_exp_f32_e32 v15, v12
	v_pk_fma_f32 v[12:13], v[28:29], s[22:23], v[52:53] op_sel_hi:[1,0,1]
	v_add_f32_e32 v14, 1.0, v14
	v_mul_f32_e32 v12, 0xbfb8aa3b, v12
	v_mul_f32_e32 v13, 0xbfb8aa3b, v13
	v_exp_f32_e32 v12, v12
	v_exp_f32_e32 v13, v13
	v_add_f32_e32 v15, 1.0, v15
	v_rcp_f32_e32 v14, v14
	v_add_f32_e32 v12, 1.0, v12
	v_add_f32_e32 v13, 1.0, v13
	v_rcp_f32_e32 v15, v15
	v_rcp_f32_e32 v12, v12
	v_rcp_f32_e32 v13, v13
	v_lshl_add_u64 v[8:9], v[8:9], 0, v[10:11]
	v_mov_b32_e32 v208, v6
	v_mov_b32_e32 v209, v7
	v_cvt_pk_bf16_f32 v6, v14, v15
	v_cvt_pk_bf16_f32 v7, v12, v13
	v_mov_b32_e32 v210, v6
	v_mov_b32_e32 v211, v7
	v_lshl_add_u64 v[194:195], v[8:9], 0, v[192:193]
	s_nop 0
	v_permlane16_swap_b32 v208, v210
	v_permlane16_swap_b32 v209, v211
	global_store_dwordx4 v[194:195], v[208:211], off
	v_pk_fma_f32 v[6:7], v[22:23], s[22:23], v[54:55] op_sel_hi:[1,0,1]
	v_pk_fma_f32 v[2:3], v[18:19], s[22:23], v[2:3] op_sel_hi:[1,0,1]
	v_mul_f32_e32 v6, 0xbfb8aa3b, v6
	v_exp_f32_e32 v10, v6
	v_mul_f32_e32 v6, 0xbfb8aa3b, v7
	v_exp_f32_e32 v11, v6
	v_pk_fma_f32 v[6:7], v[24:25], s[22:23], v[56:57] op_sel_hi:[1,0,1]
	v_add_f32_e32 v10, 1.0, v10
	v_rcp_f32_e32 v10, v10
	v_add_f32_e32 v11, 1.0, v11
	v_rcp_f32_e32 v11, v11
	v_mul_f32_e32 v6, 0xbfb8aa3b, v6
	v_exp_f32_e32 v12, v6
	v_mul_f32_e32 v6, 0xbfb8aa3b, v7
	v_mul_f32_e32 v2, 0xbfb8aa3b, v2
	v_exp_f32_e32 v7, v6
	v_cvt_pk_bf16_f32 v6, v10, v11
	v_exp_f32_e32 v11, v2
	v_mul_f32_e32 v2, 0xbfb8aa3b, v3
	v_add_f32_e32 v10, 1.0, v12
	v_exp_f32_e32 v12, v2
	v_pk_fma_f32 v[2:3], v[20:21], s[22:23], v[4:5] op_sel_hi:[1,0,1]
	v_add_f32_e32 v7, 1.0, v7
	v_mul_f32_e32 v2, 0xbfb8aa3b, v2
	v_exp_f32_e32 v2, v2
	v_mul_f32_e32 v3, 0xbfb8aa3b, v3
	v_exp_f32_e32 v3, v3
	v_add_f32_e32 v4, 1.0, v11
	v_add_f32_e32 v2, 1.0, v2
	v_add_f32_e32 v5, 1.0, v12
	v_rcp_f32_e32 v11, v2
	v_add_f32_e32 v2, 1.0, v3
	v_rcp_f32_e32 v10, v10
	v_rcp_f32_e32 v7, v7
	v_rcp_f32_e32 v4, v4
	v_rcp_f32_e32 v5, v5
	v_rcp_f32_e32 v3, v2
	v_cvt_pk_bf16_f32 v7, v10, v7
	s_mov_b64 s[38:39], s[34:35]
	v_cvt_pk_bf16_f32 v2, v4, v5
	v_cvt_pk_bf16_f32 v3, v11, v3
	v_mov_b32_e32 v212, v6
	v_mov_b32_e32 v213, v7
	v_mov_b32_e32 v214, v2
	v_mov_b32_e32 v215, v3
	v_lshl_add_u64 v[194:195], v[8:9], 0, v[192:193]
	s_nop 0
	v_permlane16_swap_b32 v212, v214
	v_permlane16_swap_b32 v213, v215
	global_store_dwordx4 v[194:195], v[212:215], off offset:256
	s_cbranch_vccz .LBB0_1548
	s_waitcnt vmcnt(0)
	s_cmpk_gt_u32 s3, 0xff
	s_cbranch_scc1 .LBB0_1555
	s_barrier

.LBB0_3123:
	ds_read_b128 v[2:5], v167
	ds_read_b128 v[6:9], v171
	ds_read_b128 v[10:13], v172
	ds_read_b128 v[14:17], v173
	s_add_u32 s40, s38, 0x100
	s_addc_u32 s41, s39, 0
	s_cmp_eq_u32 s86, 18
	s_cselect_b32 s45, s15, s41
	s_cselect_b32 s44, s14, s40
	s_cselect_b32 s43, s17, s85
	s_cselect_b32 s42, s16, s84
	v_lshl_add_u64 v[158:159], s[38:39], 0, v[152:153]
	s_add_i32 m0, s47, 0xc000
	ds_read_b128 v[186:189], v184
	ds_read_b128 v[190:193], v184 offset:1024
	ds_read_b128 v[194:197], v184 offset:2048
	ds_read_b128 v[198:201], v184 offset:3072
	ds_read_b128 v[202:205], v184 offset:4096
	ds_read_b128 v[206:209], v184 offset:5120
	ds_read_b128 v[210:213], v184 offset:6144
	ds_read_b128 v[214:217], v184 offset:7168
	global_load_lds_dwordx4 v[158:159], off
	v_lshl_add_u64 v[158:159], s[38:39], 0, v[150:151]
	s_add_i32 m0, s47, 0xe000
	s_nop 0
	global_load_lds_dwordx4 v[158:159], off
	s_waitcnt lgkmcnt(8)
	s_barrier
	s_waitcnt lgkmcnt(0)
	s_setprio 1
	s_waitcnt lgkmcnt(0)
	v_mfma_f32_16x16x128_f8f6f4 v[142:145], v[2:9], v[186:193], v[142:145]
	v_mfma_f32_16x16x128_f8f6f4 v[138:141], v[10:17], v[186:193], v[138:141]
	v_mfma_f32_16x16x128_f8f6f4 v[134:137], v[2:9], v[194:201], v[134:137]
	v_mfma_f32_16x16x128_f8f6f4 v[130:133], v[10:17], v[194:201], v[130:133]
	v_mfma_f32_16x16x128_f8f6f4 v[110:113], v[2:9], v[202:209], v[110:113]
	v_mfma_f32_16x16x128_f8f6f4 v[106:109], v[10:17], v[202:209], v[106:109]
	v_mfma_f32_16x16x128_f8f6f4 v[102:105], v[2:9], v[210:217], v[102:105]
	v_mfma_f32_16x16x128_f8f6f4 v[98:101], v[10:17], v[210:217], v[98:101]
	s_setprio 0
	s_barrier
	s_mov_b32 m0, s48
	v_lshl_add_u64 v[158:159], s[42:43], 0, v[146:147]
	ds_read_b128 v[220:223], v168
	ds_read_b128 v[224:227], v174
	ds_read_b128 v[228:231], v175
	ds_read_b128 v[232:235], v176
	global_load_lds_dwordx4 v[158:159], off
	v_lshl_add_u64 v[160:161], s[42:43], 0, v[148:149]
	s_mov_b32 m0, s49
	s_nop 0
	global_load_lds_dwordx4 v[160:161], off
	s_barrier
	s_waitcnt lgkmcnt(0)
	s_setprio 1
	s_waitcnt lgkmcnt(0)
	v_mfma_f32_16x16x128_f8f6f4 v[126:129], v[220:227], v[186:193], v[126:129]
	v_mfma_f32_16x16x128_f8f6f4 v[122:125], v[228:235], v[186:193], v[122:125]
	v_mfma_f32_16x16x128_f8f6f4 v[118:121], v[220:227], v[194:201], v[118:121]
	v_mfma_f32_16x16x128_f8f6f4 v[114:117], v[228:235], v[194:201], v[114:117]
	v_mfma_f32_16x16x128_f8f6f4 v[94:97], v[220:227], v[202:209], v[94:97]
	v_mfma_f32_16x16x128_f8f6f4 v[90:93], v[228:235], v[202:209], v[90:93]
	v_mfma_f32_16x16x128_f8f6f4 v[86:89], v[220:227], v[210:217], v[86:89]
	v_mfma_f32_16x16x128_f8f6f4 v[82:85], v[228:235], v[210:217], v[82:85]
	s_setprio 0
	s_mov_b32 m0, s47
	v_lshl_add_u64 v[162:163], s[44:45], 0, v[146:147]
	s_barrier
	ds_read_b128 v[186:189], v184 offset:16384
	ds_read_b128 v[190:193], v184 offset:17408
	ds_read_b128 v[194:197], v184 offset:18432
	ds_read_b128 v[198:201], v184 offset:19456
	ds_read_b128 v[202:205], v184 offset:20480
	ds_read_b128 v[206:209], v184 offset:21504
	ds_read_b128 v[210:213], v184 offset:22528
	ds_read_b128 v[214:217], v184 offset:23552
	global_load_lds_dwordx4 v[162:163], off
	v_lshl_add_u64 v[164:165], s[44:45], 0, v[148:149]
	s_mov_b32 m0, s52
	s_nop 0
	global_load_lds_dwordx4 v[164:165], off
	s_barrier
	s_waitcnt lgkmcnt(0)
	s_setprio 1
	s_waitcnt lgkmcnt(0)
	v_mfma_f32_16x16x128_f8f6f4 v[78:81], v[2:9], v[186:193], v[78:81]
	v_mfma_f32_16x16x128_f8f6f4 v[74:77], v[10:17], v[186:193], v[74:77]
	v_mfma_f32_16x16x128_f8f6f4 v[70:73], v[2:9], v[194:201], v[70:73]
	v_mfma_f32_16x16x128_f8f6f4 v[66:69], v[10:17], v[194:201], v[66:69]
	v_mfma_f32_16x16x128_f8f6f4 v[46:49], v[2:9], v[202:209], v[46:49]
	v_mfma_f32_16x16x128_f8f6f4 v[42:45], v[10:17], v[202:209], v[42:45]
	v_mfma_f32_16x16x128_f8f6f4 v[38:41], v[2:9], v[210:217], v[38:41]
	v_mfma_f32_16x16x128_f8f6f4 v[34:37], v[10:17], v[210:217], v[34:37]
	s_setprio 0
	s_barrier
	s_add_u32 s38, s42, 0x58000
	s_addc_u32 s39, s43, 0
	s_mov_b32 m0, s53
	v_lshl_add_u64 v[2:3], s[38:39], 0, v[146:147]
	global_load_lds_dwordx4 v[2:3], off
	v_lshl_add_u64 v[2:3], s[38:39], 0, v[148:149]
	s_mov_b32 m0, s55
	s_nop 0
	global_load_lds_dwordx4 v[2:3], off
	s_waitcnt vmcnt(6)
	s_barrier
	s_setprio 1
	v_mfma_f32_16x16x128_f8f6f4 v[62:65], v[220:227], v[186:193], v[62:65]
	v_mfma_f32_16x16x128_f8f6f4 v[58:61], v[228:235], v[186:193], v[58:61]
	v_mfma_f32_16x16x128_f8f6f4 v[54:57], v[220:227], v[194:201], v[54:57]
	v_mfma_f32_16x16x128_f8f6f4 v[50:53], v[228:235], v[194:201], v[50:53]
	v_mfma_f32_16x16x128_f8f6f4 v[30:33], v[220:227], v[202:209], v[30:33]
	v_mfma_f32_16x16x128_f8f6f4 v[26:29], v[228:235], v[202:209], v[26:29]
	v_mfma_f32_16x16x128_f8f6f4 v[22:25], v[220:227], v[210:217], v[22:25]
	v_mfma_f32_16x16x128_f8f6f4 v[18:21], v[228:235], v[210:217], v[18:21]
	s_setprio 0
	s_barrier
	ds_read_b128 v[2:5], v169
	ds_read_b128 v[6:9], v177
	ds_read_b128 v[10:13], v178
	ds_read_b128 v[14:17], v179
	s_add_u32 s38, s44, 0x58000
	s_addc_u32 s39, s45, 0
	s_mov_b32 m0, s64
	v_lshl_add_u64 v[220:221], s[38:39], 0, v[146:147]
	ds_read_b128 v[186:189], v184 offset:32768
	ds_read_b128 v[190:193], v184 offset:33792
	ds_read_b128 v[194:197], v184 offset:34816
	ds_read_b128 v[198:201], v184 offset:35840
	ds_read_b128 v[202:205], v184 offset:36864
	ds_read_b128 v[206:209], v184 offset:37888
	ds_read_b128 v[210:213], v184 offset:38912
	ds_read_b128 v[214:217], v184 offset:39936
	global_load_lds_dwordx4 v[220:221], off
	v_lshl_add_u64 v[220:221], s[38:39], 0, v[148:149]
	s_mov_b32 m0, s65
	s_nop 0
	global_load_lds_dwordx4 v[220:221], off
	s_waitcnt lgkmcnt(8)
	s_barrier
	s_waitcnt lgkmcnt(0)
	s_setprio 1
	s_waitcnt lgkmcnt(0)
	v_mfma_f32_16x16x128_f8f6f4 v[142:145], v[2:9], v[186:193], v[142:145]
	v_mfma_f32_16x16x128_f8f6f4 v[138:141], v[10:17], v[186:193], v[138:141]
	v_mfma_f32_16x16x128_f8f6f4 v[134:137], v[2:9], v[194:201], v[134:137]
	v_mfma_f32_16x16x128_f8f6f4 v[130:133], v[10:17], v[194:201], v[130:133]
	v_mfma_f32_16x16x128_f8f6f4 v[110:113], v[2:9], v[202:209], v[110:113]
	v_mfma_f32_16x16x128_f8f6f4 v[106:109], v[10:17], v[202:209], v[106:109]
	v_mfma_f32_16x16x128_f8f6f4 v[102:105], v[2:9], v[210:217], v[102:105]
	v_mfma_f32_16x16x128_f8f6f4 v[98:101], v[10:17], v[210:217], v[98:101]
	s_setprio 0
	s_barrier
	s_mov_b32 m0, s69
	v_lshl_add_u64 v[158:159], v[158:159], 0, s[28:29]
	ds_read_b128 v[220:223], v170
	ds_read_b128 v[224:227], v180
	ds_read_b128 v[228:231], v181
	ds_read_b128 v[232:235], v182
	global_load_lds_dwordx4 v[158:159], off
	v_lshl_add_u64 v[158:159], v[160:161], 0, s[28:29]
	s_mov_b32 m0, s70
	s_nop 0
	global_load_lds_dwordx4 v[158:159], off
	s_barrier
	s_waitcnt lgkmcnt(0)
	s_setprio 1
	s_waitcnt lgkmcnt(0)
	v_mfma_f32_16x16x128_f8f6f4 v[126:129], v[220:227], v[186:193], v[126:129]
	v_mfma_f32_16x16x128_f8f6f4 v[122:125], v[228:235], v[186:193], v[122:125]
	v_mfma_f32_16x16x128_f8f6f4 v[118:121], v[220:227], v[194:201], v[118:121]
	v_mfma_f32_16x16x128_f8f6f4 v[114:117], v[228:235], v[194:201], v[114:117]
	v_mfma_f32_16x16x128_f8f6f4 v[94:97], v[220:227], v[202:209], v[94:97]
	v_mfma_f32_16x16x128_f8f6f4 v[90:93], v[228:235], v[202:209], v[90:93]
	v_mfma_f32_16x16x128_f8f6f4 v[86:89], v[220:227], v[210:217], v[86:89]
	v_mfma_f32_16x16x128_f8f6f4 v[82:85], v[228:235], v[210:217], v[82:85]
	s_setprio 0
	s_mov_b32 m0, s71
	v_lshl_add_u64 v[158:159], v[162:163], 0, s[28:29]
	s_barrier
	ds_read_b128 v[186:189], v184 offset:49152
	ds_read_b128 v[190:193], v184 offset:50176
	ds_read_b128 v[194:197], v184 offset:51200
	ds_read_b128 v[198:201], v184 offset:52224
	ds_read_b128 v[202:205], v184 offset:53248
	ds_read_b128 v[206:209], v184 offset:54272
	ds_read_b128 v[210:213], v184 offset:55296
	ds_read_b128 v[214:217], v184 offset:56320
	global_load_lds_dwordx4 v[158:159], off
	v_lshl_add_u64 v[158:159], v[164:165], 0, s[28:29]
	s_mov_b32 m0, s72
	s_nop 0
	global_load_lds_dwordx4 v[158:159], off
	s_barrier
	s_waitcnt lgkmcnt(0)
	s_setprio 1
	s_waitcnt lgkmcnt(0)
	v_mfma_f32_16x16x128_f8f6f4 v[78:81], v[2:9], v[186:193], v[78:81]
	v_mfma_f32_16x16x128_f8f6f4 v[74:77], v[10:17], v[186:193], v[74:77]
	v_mfma_f32_16x16x128_f8f6f4 v[70:73], v[2:9], v[194:201], v[70:73]
	v_mfma_f32_16x16x128_f8f6f4 v[66:69], v[10:17], v[194:201], v[66:69]
	v_mfma_f32_16x16x128_f8f6f4 v[46:49], v[2:9], v[202:209], v[46:49]
	v_mfma_f32_16x16x128_f8f6f4 v[42:45], v[10:17], v[202:209], v[42:45]
	v_mfma_f32_16x16x128_f8f6f4 v[38:41], v[2:9], v[210:217], v[38:41]
	v_mfma_f32_16x16x128_f8f6f4 v[34:37], v[10:17], v[210:217], v[34:37]
	s_setprio 0
	s_barrier
	s_add_u32 s38, s42, 0x58080
	s_addc_u32 s39, s43, 0
	s_mov_b32 m0, s73
	v_lshl_add_u64 v[2:3], s[38:39], 0, v[146:147]
	global_load_lds_dwordx4 v[2:3], off
	v_lshl_add_u64 v[2:3], s[38:39], 0, v[148:149]
	s_mov_b32 m0, s74
	s_nop 0
	global_load_lds_dwordx4 v[2:3], off
	s_waitcnt vmcnt(6)
	s_barrier
	s_setprio 1
	v_mfma_f32_16x16x128_f8f6f4 v[62:65], v[220:227], v[186:193], v[62:65]
	v_mfma_f32_16x16x128_f8f6f4 v[58:61], v[228:235], v[186:193], v[58:61]
	v_mfma_f32_16x16x128_f8f6f4 v[54:57], v[220:227], v[194:201], v[54:57]
	v_mfma_f32_16x16x128_f8f6f4 v[50:53], v[228:235], v[194:201], v[50:53]
	v_mfma_f32_16x16x128_f8f6f4 v[30:33], v[220:227], v[202:209], v[30:33]
	v_mfma_f32_16x16x128_f8f6f4 v[26:29], v[228:235], v[202:209], v[26:29]
	v_mfma_f32_16x16x128_f8f6f4 v[22:25], v[220:227], v[210:217], v[22:25]
	v_mfma_f32_16x16x128_f8f6f4 v[18:21], v[228:235], v[210:217], v[18:21]
	s_setprio 0
	s_add_i32 s86, s86, 2
	s_add_u32 s84, s84, 0x100
	s_addc_u32 s85, s85, 0
	s_cmp_gt_u32 s86, 19
	s_mov_b64 s[38:39], s[40:41]
	s_barrier
	s_cbranch_scc0 .LBB0_3123
	v_bfe_u32 v160, v0, 4, 1
	v_mul_u32_u24_e32 v160, 24, v160
	v_mov_b32_e32 v161, 0
	v_lshl_add_u32 v6, s83, 8, v166
	v_ashrrev_i32_e32 v7, 31, v6
	v_or_b32_e32 v4, 16, v6
	s_nop 15
	s_nop 15
	v_lshl_add_u64 v[2:3], v[6:7], 2, s[20:21]
	v_ashrrev_i32_e32 v5, 31, v4
	global_load_dword v158, v[2:3], off
	v_lshl_add_u64 v[8:9], v[4:5], 2, s[20:21]
	global_load_dword v159, v[8:9], off
	s_ashr_i32 s0, s82, 31
	s_lshr_b32 s0, s0, 30
	s_add_i32 s0, s82, s0
	s_and_b32 s0, s0, 0xfffffc
	v_lshlrev_b64 v[4:5], 11, v[4:5]
	s_sub_i32 s0, s82, s0
	v_lshl_add_u64 v[14:15], s[18:19], 0, v[4:5]
	v_lshl_or_b32 v4, s0, 8, v183
	v_lshlrev_b64 v[10:11], 11, v[6:7]
	v_ashrrev_i32_e32 v5, 31, v4
	v_lshl_add_u64 v[10:11], s[18:19], 0, v[10:11]
	v_lshlrev_b64 v[16:17], 1, v[4:5]
	v_lshl_add_u64 v[4:5], v[10:11], 0, v[16:17]
	v_lshl_add_u64 v[10:11], v[14:15], 0, v[16:17]
	v_or_b32_e32 v8, 32, v6
	v_ashrrev_i32_e32 v9, 31, v8
	v_lshl_add_u64 v[12:13], v[8:9], 2, s[20:21]
	v_or_b32_e32 v6, 48, v6
	v_ashrrev_i32_e32 v7, 31, v6
	v_lshlrev_b64 v[8:9], 11, v[8:9]
	v_lshlrev_b64 v[6:7], 11, v[6:7]
	v_lshl_add_u64 v[8:9], s[18:19], 0, v[8:9]
	v_lshl_add_u64 v[6:7], s[18:19], 0, v[6:7]
	v_lshl_add_u64 v[8:9], v[8:9], 0, v[16:17]
	v_lshl_add_u64 v[6:7], v[6:7], 0, v[16:17]
	s_mov_b32 s83, s80
	s_mov_b64 s[40:41], s[16:17]
	s_mov_b64 s[38:39], s[14:15]
	s_mov_b32 s82, s81
	s_waitcnt vmcnt(0)
	v_mul_f32_e32 v14, 0x3b800000, v158
	v_pk_mul_f32 v[142:143], v[142:143], v[14:15] op_sel_hi:[1,0]
	v_pk_mul_f32 v[144:145], v[144:145], v[14:15] op_sel_hi:[1,0]
	v_pk_mul_f32 v[138:139], v[138:139], v[14:15] op_sel_hi:[1,0]
	v_pk_mul_f32 v[140:141], v[140:141], v[14:15] op_sel_hi:[1,0]
	v_pk_mul_f32 v[126:127], v[126:127], v[14:15] op_sel_hi:[1,0]
	v_pk_mul_f32 v[128:129], v[128:129], v[14:15] op_sel_hi:[1,0]
	v_pk_mul_f32 v[122:123], v[122:123], v[14:15] op_sel_hi:[1,0]
	v_pk_mul_f32 v[14:15], v[124:125], v[14:15] op_sel_hi:[1,0]
	v_mul_f32_e32 v124, 0x3b800000, v159
	v_cvt_pk_bf16_f32 v126, v126, v127
	v_cvt_pk_bf16_f32 v127, v128, v129
	v_cvt_pk_bf16_f32 v122, v122, v123
	v_cvt_pk_bf16_f32 v123, v14, v15
	v_pk_mul_f32 v[14:15], v[134:135], v[124:125] op_sel_hi:[1,0]
	v_pk_mul_f32 v[128:129], v[136:137], v[124:125] op_sel_hi:[1,0]
	v_cvt_pk_bf16_f32 v142, v142, v143
	v_cvt_pk_bf16_f32 v143, v144, v145
	v_pk_mul_f32 v[130:131], v[130:131], v[124:125] op_sel_hi:[1,0]
	v_pk_mul_f32 v[132:133], v[132:133], v[124:125] op_sel_hi:[1,0]
	v_pk_mul_f32 v[118:119], v[118:119], v[124:125] op_sel_hi:[1,0]
	v_pk_mul_f32 v[120:121], v[120:121], v[124:125] op_sel_hi:[1,0]
	v_pk_mul_f32 v[114:115], v[114:115], v[124:125] op_sel_hi:[1,0]
	v_pk_mul_f32 v[116:117], v[116:117], v[124:125] op_sel_hi:[1,0]
	v_cvt_pk_bf16_f32 v14, v14, v15
	v_cvt_pk_bf16_f32 v15, v128, v129
	v_cvt_pk_bf16_f32 v138, v138, v139
	v_cvt_pk_bf16_f32 v139, v140, v141
	v_mov_b32_e32 v192, v142
	v_mov_b32_e32 v193, v143
	v_mov_b32_e32 v194, v138
	v_mov_b32_e32 v195, v139
	v_lshl_add_u64 v[162:163], v[4:5], 0, v[160:161]
	s_nop 0
	v_permlane16_swap_b32 v192, v194
	v_permlane16_swap_b32 v193, v195
	global_store_dwordx4 v[162:163], v[192:195], off
	v_mov_b32_e32 v196, v126
	v_mov_b32_e32 v197, v127
	v_mov_b32_e32 v198, v122
	v_mov_b32_e32 v199, v123
	v_lshl_add_u64 v[162:163], v[4:5], 0, v[160:161]
	s_nop 0
	v_permlane16_swap_b32 v196, v198
	v_permlane16_swap_b32 v197, v199
	global_store_dwordx4 v[162:163], v[196:199], off offset:256
	v_cvt_pk_bf16_f32 v122, v130, v131
	v_cvt_pk_bf16_f32 v123, v132, v133
	v_cvt_pk_bf16_f32 v118, v118, v119
	v_cvt_pk_bf16_f32 v119, v120, v121
	v_cvt_pk_bf16_f32 v114, v114, v115
	v_cvt_pk_bf16_f32 v115, v116, v117
	v_mov_b32_e32 v200, v14
	v_mov_b32_e32 v201, v15
	v_mov_b32_e32 v202, v122
	v_mov_b32_e32 v203, v123
	v_lshl_add_u64 v[162:163], v[10:11], 0, v[160:161]
	s_nop 0
	v_permlane16_swap_b32 v200, v202
	v_permlane16_swap_b32 v201, v203
	global_store_dwordx4 v[162:163], v[200:203], off
	v_mov_b32_e32 v204, v118
	v_mov_b32_e32 v205, v119
	v_mov_b32_e32 v206, v114
	v_mov_b32_e32 v207, v115
	v_lshl_add_u64 v[162:163], v[10:11], 0, v[160:161]
	s_nop 0
	v_permlane16_swap_b32 v204, v206
	v_permlane16_swap_b32 v205, v207
	global_store_dwordx4 v[162:163], v[204:207], off offset:256
	global_load_dword v10, v[12:13], off
	s_nop 0
	global_load_dword v11, v[2:3], off offset:192
	s_waitcnt vmcnt(0)
	v_mul_f32_e32 v10, 0x3b800000, v10
	v_mul_f32_e32 v12, 0x3b800000, v11
	v_pk_mul_f32 v[14:15], v[110:111], v[10:11] op_sel_hi:[1,0]
	v_pk_mul_f32 v[16:17], v[112:113], v[10:11] op_sel_hi:[1,0]
	v_pk_mul_f32 v[106:107], v[106:107], v[10:11] op_sel_hi:[1,0]
	v_pk_mul_f32 v[108:109], v[108:109], v[10:11] op_sel_hi:[1,0]
	v_pk_mul_f32 v[94:95], v[94:95], v[10:11] op_sel_hi:[1,0]
	v_pk_mul_f32 v[96:97], v[96:97], v[10:11] op_sel_hi:[1,0]
	v_pk_mul_f32 v[90:91], v[90:91], v[10:11] op_sel_hi:[1,0]
	v_pk_mul_f32 v[10:11], v[92:93], v[10:11] op_sel_hi:[1,0]
	v_pk_mul_f32 v[92:93], v[102:103], v[12:13] op_sel_hi:[1,0]
	v_pk_mul_f32 v[102:103], v[104:105], v[12:13] op_sel_hi:[1,0]
	v_pk_mul_f32 v[98:99], v[98:99], v[12:13] op_sel_hi:[1,0]
	v_pk_mul_f32 v[100:101], v[100:101], v[12:13] op_sel_hi:[1,0]
	v_pk_mul_f32 v[86:87], v[86:87], v[12:13] op_sel_hi:[1,0]
	v_pk_mul_f32 v[88:89], v[88:89], v[12:13] op_sel_hi:[1,0]
	v_pk_mul_f32 v[82:83], v[82:83], v[12:13] op_sel_hi:[1,0]
	v_pk_mul_f32 v[12:13], v[84:85], v[12:13] op_sel_hi:[1,0]
	v_cvt_pk_bf16_f32 v14, v14, v15
	v_cvt_pk_bf16_f32 v15, v16, v17
	v_cvt_pk_bf16_f32 v16, v106, v107
	v_cvt_pk_bf16_f32 v17, v108, v109
	v_cvt_pk_bf16_f32 v84, v94, v95
	v_cvt_pk_bf16_f32 v85, v96, v97
	v_cvt_pk_bf16_f32 v90, v90, v91
	v_cvt_pk_bf16_f32 v91, v10, v11
	v_cvt_pk_bf16_f32 v10, v92, v93
	v_cvt_pk_bf16_f32 v11, v102, v103
	v_cvt_pk_bf16_f32 v92, v98, v99
	v_cvt_pk_bf16_f32 v93, v100, v101
	v_cvt_pk_bf16_f32 v86, v86, v87
	v_cvt_pk_bf16_f32 v87, v88, v89
	v_cvt_pk_bf16_f32 v82, v82, v83
	v_cvt_pk_bf16_f32 v83, v12, v13
	v_mov_b32_e32 v208, v14
	v_mov_b32_e32 v209, v15
	v_mov_b32_e32 v210, v16
	v_mov_b32_e32 v211, v17
	v_lshl_add_u64 v[162:163], v[8:9], 0, v[160:161]
	s_nop 0
	v_permlane16_swap_b32 v208, v210
	v_permlane16_swap_b32 v209, v211
	global_store_dwordx4 v[162:163], v[208:211], off
	v_mov_b32_e32 v212, v84
	v_mov_b32_e32 v213, v85
	v_mov_b32_e32 v214, v90
	v_mov_b32_e32 v215, v91
	v_lshl_add_u64 v[162:163], v[8:9], 0, v[160:161]
	s_nop 0
	v_permlane16_swap_b32 v212, v214
	v_permlane16_swap_b32 v213, v215
	global_store_dwordx4 v[162:163], v[212:215], off offset:256
	v_mov_b32_e32 v220, v10
	v_mov_b32_e32 v221, v11
	v_mov_b32_e32 v222, v92
	v_mov_b32_e32 v223, v93
	v_lshl_add_u64 v[162:163], v[6:7], 0, v[160:161]
	s_nop 0
	v_permlane16_swap_b32 v220, v222
	v_permlane16_swap_b32 v221, v223
	global_store_dwordx4 v[162:163], v[220:223], off
	v_mov_b32_e32 v224, v86
	v_mov_b32_e32 v225, v87
	v_mov_b32_e32 v226, v82
	v_mov_b32_e32 v227, v83
	v_lshl_add_u64 v[162:163], v[6:7], 0, v[160:161]
	s_nop 0
	v_permlane16_swap_b32 v224, v226
	v_permlane16_swap_b32 v225, v227
	global_store_dwordx4 v[162:163], v[224:227], off offset:256
	global_load_dword v14, v[2:3], off offset:512
	global_load_dword v15, v[2:3], off offset:576
	v_add_co_u32_e32 v8, vcc, s76, v4
	v_lshl_add_u64 v[6:7], v[4:5], 0, s[30:31]
	s_nop 0
	v_addc_co_u32_e32 v9, vcc, 0, v5, vcc
	v_add_co_u32_e32 v12, vcc, s77, v4
	v_lshl_add_u64 v[10:11], v[4:5], 0, s[34:35]
	s_nop 0
	v_addc_co_u32_e32 v13, vcc, 0, v5, vcc
	s_and_b64 vcc, exec, s[12:13]
	s_waitcnt vmcnt(0)
	v_mul_f32_e32 v14, 0x3b800000, v14
	v_mul_f32_e32 v16, 0x3b800000, v15
	v_pk_mul_f32 v[78:79], v[78:79], v[14:15] op_sel_hi:[1,0]
	v_pk_mul_f32 v[80:81], v[80:81], v[14:15] op_sel_hi:[1,0]
	v_pk_mul_f32 v[74:75], v[74:75], v[14:15] op_sel_hi:[1,0]
	v_pk_mul_f32 v[76:77], v[76:77], v[14:15] op_sel_hi:[1,0]
	v_pk_mul_f32 v[62:63], v[62:63], v[14:15] op_sel_hi:[1,0]
	v_pk_mul_f32 v[64:65], v[64:65], v[14:15] op_sel_hi:[1,0]
	v_pk_mul_f32 v[58:59], v[58:59], v[14:15] op_sel_hi:[1,0]
	v_pk_mul_f32 v[14:15], v[60:61], v[14:15] op_sel_hi:[1,0]
	v_pk_mul_f32 v[60:61], v[70:71], v[16:17] op_sel_hi:[1,0]
	v_pk_mul_f32 v[70:71], v[72:73], v[16:17] op_sel_hi:[1,0]
	v_pk_mul_f32 v[66:67], v[66:67], v[16:17] op_sel_hi:[1,0]
	v_pk_mul_f32 v[68:69], v[68:69], v[16:17] op_sel_hi:[1,0]
	v_pk_mul_f32 v[54:55], v[54:55], v[16:17] op_sel_hi:[1,0]
	v_pk_mul_f32 v[56:57], v[56:57], v[16:17] op_sel_hi:[1,0]
	v_pk_mul_f32 v[50:51], v[50:51], v[16:17] op_sel_hi:[1,0]
	v_pk_mul_f32 v[16:17], v[52:53], v[16:17] op_sel_hi:[1,0]
	v_cvt_pk_bf16_f32 v52, v78, v79
	v_cvt_pk_bf16_f32 v53, v80, v81
	v_cvt_pk_bf16_f32 v72, v74, v75
	v_cvt_pk_bf16_f32 v73, v76, v77
	v_cvt_pk_bf16_f32 v62, v62, v63
	v_cvt_pk_bf16_f32 v63, v64, v65
	v_cvt_pk_bf16_f32 v58, v58, v59
	v_cvt_pk_bf16_f32 v59, v14, v15
	v_cvt_pk_bf16_f32 v14, v60, v61
	v_cvt_pk_bf16_f32 v15, v70, v71
	v_cvt_pk_bf16_f32 v60, v66, v67
	v_cvt_pk_bf16_f32 v61, v68, v69
	v_cvt_pk_bf16_f32 v54, v54, v55
	v_cvt_pk_bf16_f32 v55, v56, v57
	v_cvt_pk_bf16_f32 v50, v50, v51
	v_cvt_pk_bf16_f32 v51, v16, v17
	global_store_dwordx2 v[8:9], v[52:53], off
	global_store_dwordx2 v[6:7], v[72:73], off offset:32
	v_mov_b32_e32 v232, v62
	v_mov_b32_e32 v233, v63
	v_mov_b32_e32 v234, v58
	v_mov_b32_e32 v235, v59
	v_lshl_add_u64 v[162:163], v[6:7], 0, v[160:161]
	s_nop 0
	v_permlane16_swap_b32 v232, v234
	v_permlane16_swap_b32 v233, v235
	global_store_dwordx4 v[162:163], v[232:235], off offset:256
	global_store_dwordx2 v[12:13], v[14:15], off
	global_store_dwordx2 v[10:11], v[60:61], off offset:32
	v_mov_b32_e32 v236, v54
	v_mov_b32_e32 v237, v55
	v_mov_b32_e32 v238, v50
	v_mov_b32_e32 v239, v51
	v_lshl_add_u64 v[162:163], v[10:11], 0, v[160:161]
	s_nop 0
	v_permlane16_swap_b32 v236, v238
	v_permlane16_swap_b32 v237, v239
	global_store_dwordx4 v[162:163], v[236:239], off offset:256
	global_load_dword v10, v[2:3], off offset:640
	s_nop 0
	global_load_dword v11, v[2:3], off offset:704
	v_add_co_u32_e64 v6, s[12:13], s78, v4
	v_lshl_add_u64 v[2:3], v[4:5], 0, s[36:37]
	s_nop 0
	v_addc_co_u32_e64 v7, s[12:13], 0, v5, s[12:13]
	v_lshl_add_u64 v[8:9], v[4:5], 0, s[26:27]
	v_add_co_u32_e64 v4, s[12:13], s79, v4
	s_waitcnt vmcnt(0)
	v_mul_f32_e32 v10, 0x3b800000, v10
	v_mul_f32_e32 v12, 0x3b800000, v11
	v_pk_mul_f32 v[14:15], v[46:47], v[10:11] op_sel_hi:[1,0]
	v_pk_mul_f32 v[16:17], v[48:49], v[10:11] op_sel_hi:[1,0]
	v_pk_mul_f32 v[42:43], v[42:43], v[10:11] op_sel_hi:[1,0]
	v_pk_mul_f32 v[44:45], v[44:45], v[10:11] op_sel_hi:[1,0]
	v_pk_mul_f32 v[30:31], v[30:31], v[10:11] op_sel_hi:[1,0]
	v_pk_mul_f32 v[32:33], v[32:33], v[10:11] op_sel_hi:[1,0]
	v_pk_mul_f32 v[26:27], v[26:27], v[10:11] op_sel_hi:[1,0]
	v_pk_mul_f32 v[10:11], v[28:29], v[10:11] op_sel_hi:[1,0]
	v_pk_mul_f32 v[28:29], v[38:39], v[12:13] op_sel_hi:[1,0]
	v_pk_mul_f32 v[38:39], v[40:41], v[12:13] op_sel_hi:[1,0]
	v_pk_mul_f32 v[34:35], v[34:35], v[12:13] op_sel_hi:[1,0]
	v_pk_mul_f32 v[36:37], v[36:37], v[12:13] op_sel_hi:[1,0]
	v_pk_mul_f32 v[22:23], v[22:23], v[12:13] op_sel_hi:[1,0]
	v_pk_mul_f32 v[24:25], v[24:25], v[12:13] op_sel_hi:[1,0]
	v_pk_mul_f32 v[18:19], v[18:19], v[12:13] op_sel_hi:[1,0]
	v_pk_mul_f32 v[12:13], v[20:21], v[12:13] op_sel_hi:[1,0]
	v_cvt_pk_bf16_f32 v14, v14, v15
	v_cvt_pk_bf16_f32 v15, v16, v17
	v_addc_co_u32_e64 v5, s[12:13], 0, v5, s[12:13]
	v_cvt_pk_bf16_f32 v16, v42, v43
	v_cvt_pk_bf16_f32 v17, v44, v45
	v_cvt_pk_bf16_f32 v20, v30, v31
	v_cvt_pk_bf16_f32 v21, v32, v33
	v_cvt_pk_bf16_f32 v26, v26, v27
	v_cvt_pk_bf16_f32 v27, v10, v11
	v_cvt_pk_bf16_f32 v10, v28, v29
	v_cvt_pk_bf16_f32 v11, v38, v39
	v_cvt_pk_bf16_f32 v28, v34, v35
	v_cvt_pk_bf16_f32 v29, v36, v37
	v_cvt_pk_bf16_f32 v22, v22, v23
	v_cvt_pk_bf16_f32 v23, v24, v25
	v_cvt_pk_bf16_f32 v18, v18, v19
	v_cvt_pk_bf16_f32 v19, v12, v13
	global_store_dwordx2 v[6:7], v[14:15], off
	global_store_dwordx2 v[2:3], v[16:17], off offset:32
	v_mov_b32_e32 v240, v20
	v_mov_b32_e32 v241, v21
	v_mov_b32_e32 v242, v26
	v_mov_b32_e32 v243, v27
	v_lshl_add_u64 v[162:163], v[2:3], 0, v[160:161]
	s_nop 0
	v_permlane16_swap_b32 v240, v242
	v_permlane16_swap_b32 v241, v243
	global_store_dwordx4 v[162:163], v[240:243], off offset:256
	global_store_dwordx2 v[4:5], v[10:11], off
	global_store_dwordx2 v[8:9], v[28:29], off offset:32
	v_mov_b32_e32 v192, v22
	v_mov_b32_e32 v193, v23
	v_mov_b32_e32 v194, v18
	v_mov_b32_e32 v195, v19
	v_lshl_add_u64 v[162:163], v[8:9], 0, v[160:161]
	s_nop 0
	v_permlane16_swap_b32 v192, v194
	v_permlane16_swap_b32 v193, v195
	global_store_dwordx4 v[162:163], v[192:195], off offset:256
	s_cbranch_vccz .LBB0_3112
	s_waitcnt vmcnt(0)
	s_cmpk_gt_u32 s3, 0xff
	s_cbranch_scc1 .LBB0_3127
	s_barrier

.LBB0_3420:
	ds_read_b128 v[2:5], v167
	ds_read_b128 v[6:9], v171
	ds_read_b128 v[10:13], v172
	ds_read_b128 v[14:17], v173
	s_add_u32 s0, s36, 0xfffe0080
	s_addc_u32 s1, s37, -1
	s_cmp_eq_u32 s76, 4
	s_cselect_b32 s41, s27, s1
	s_cselect_b32 s40, s72, s0
	s_cselect_b32 s39, s25, s75
	s_cselect_b32 s38, s73, s74
	v_lshl_add_u64 v[158:159], s[36:37], 0, v[152:153]
	s_add_i32 m0, s35, 0xc000
	ds_read_b128 v[186:189], v184
	ds_read_b128 v[190:193], v184 offset:1024
	ds_read_b128 v[194:197], v184 offset:2048
	ds_read_b128 v[198:201], v184 offset:3072
	ds_read_b128 v[202:205], v184 offset:4096
	ds_read_b128 v[206:209], v184 offset:5120
	ds_read_b128 v[210:213], v184 offset:6144
	ds_read_b128 v[214:217], v184 offset:7168
	global_load_lds_dwordx4 v[158:159], off
	v_lshl_add_u64 v[158:159], s[36:37], 0, v[150:151]
	s_add_i32 m0, s35, 0xe000
	s_nop 0
	global_load_lds_dwordx4 v[158:159], off
	s_waitcnt lgkmcnt(8)
	s_barrier
	s_waitcnt lgkmcnt(0)
	s_setprio 1
	s_waitcnt lgkmcnt(0)
	v_mfma_f32_16x16x128_f8f6f4 v[142:145], v[2:9], v[186:193], v[142:145]
	v_mfma_f32_16x16x128_f8f6f4 v[138:141], v[10:17], v[186:193], v[138:141]
	v_mfma_f32_16x16x128_f8f6f4 v[134:137], v[2:9], v[194:201], v[134:137]
	v_mfma_f32_16x16x128_f8f6f4 v[126:129], v[10:17], v[194:201], v[126:129]
	v_mfma_f32_16x16x128_f8f6f4 v[118:121], v[2:9], v[202:209], v[118:121]
	v_mfma_f32_16x16x128_f8f6f4 v[110:113], v[10:17], v[202:209], v[110:113]
	v_mfma_f32_16x16x128_f8f6f4 v[102:105], v[2:9], v[210:217], v[102:105]
	v_mfma_f32_16x16x128_f8f6f4 v[94:97], v[10:17], v[210:217], v[94:97]
	s_setprio 0
	s_barrier
	s_mov_b32 m0, s43
	v_lshl_add_u64 v[158:159], s[38:39], 0, v[148:149]
	ds_read_b128 v[220:223], v168
	ds_read_b128 v[224:227], v174
	ds_read_b128 v[228:231], v175
	ds_read_b128 v[232:235], v176
	global_load_lds_dwordx4 v[158:159], off
	v_lshl_add_u64 v[160:161], s[38:39], 0, v[146:147]
	s_mov_b32 m0, s44
	s_nop 0
	global_load_lds_dwordx4 v[160:161], off
	s_barrier
	s_waitcnt lgkmcnt(0)
	s_setprio 1
	s_waitcnt lgkmcnt(0)
	v_mfma_f32_16x16x128_f8f6f4 v[130:133], v[220:227], v[186:193], v[130:133]
	v_mfma_f32_16x16x128_f8f6f4 v[122:125], v[228:235], v[186:193], v[122:125]
	v_mfma_f32_16x16x128_f8f6f4 v[114:117], v[220:227], v[194:201], v[114:117]
	v_mfma_f32_16x16x128_f8f6f4 v[106:109], v[228:235], v[194:201], v[106:109]
	v_mfma_f32_16x16x128_f8f6f4 v[98:101], v[220:227], v[202:209], v[98:101]
	v_mfma_f32_16x16x128_f8f6f4 v[90:93], v[228:235], v[202:209], v[90:93]
	v_mfma_f32_16x16x128_f8f6f4 v[86:89], v[220:227], v[210:217], v[86:89]
	v_mfma_f32_16x16x128_f8f6f4 v[82:85], v[228:235], v[210:217], v[82:85]
	s_setprio 0
	s_mov_b32 m0, s35
	v_lshl_add_u64 v[162:163], s[40:41], 0, v[148:149]
	s_barrier
	ds_read_b128 v[186:189], v184 offset:16384
	ds_read_b128 v[190:193], v184 offset:17408
	ds_read_b128 v[194:197], v184 offset:18432
	ds_read_b128 v[198:201], v184 offset:19456
	ds_read_b128 v[202:205], v184 offset:20480
	ds_read_b128 v[206:209], v184 offset:21504
	ds_read_b128 v[210:213], v184 offset:22528
	ds_read_b128 v[214:217], v184 offset:23552
	global_load_lds_dwordx4 v[162:163], off
	v_lshl_add_u64 v[164:165], s[40:41], 0, v[146:147]
	s_mov_b32 m0, s45
	s_nop 0
	global_load_lds_dwordx4 v[164:165], off
	s_barrier
	s_waitcnt lgkmcnt(0)
	s_setprio 1
	s_waitcnt lgkmcnt(0)
	v_mfma_f32_16x16x128_f8f6f4 v[78:81], v[2:9], v[186:193], v[78:81]
	v_mfma_f32_16x16x128_f8f6f4 v[74:77], v[10:17], v[186:193], v[74:77]
	v_mfma_f32_16x16x128_f8f6f4 v[70:73], v[2:9], v[194:201], v[70:73]
	v_mfma_f32_16x16x128_f8f6f4 v[62:65], v[10:17], v[194:201], v[62:65]
	v_mfma_f32_16x16x128_f8f6f4 v[54:57], v[2:9], v[202:209], v[54:57]
	v_mfma_f32_16x16x128_f8f6f4 v[46:49], v[10:17], v[202:209], v[46:49]
	v_mfma_f32_16x16x128_f8f6f4 v[38:41], v[2:9], v[210:217], v[38:41]
	v_mfma_f32_16x16x128_f8f6f4 v[30:33], v[10:17], v[210:217], v[30:33]
	s_setprio 0
	s_barrier
	s_add_u32 s78, s38, 0x20000
	s_addc_u32 s79, s39, 0
	s_mov_b32 m0, s46
	v_lshl_add_u64 v[2:3], s[78:79], 0, v[148:149]
	global_load_lds_dwordx4 v[2:3], off
	v_lshl_add_u64 v[2:3], s[78:79], 0, v[146:147]
	s_mov_b32 m0, s47
	s_nop 0
	global_load_lds_dwordx4 v[2:3], off
	s_waitcnt vmcnt(6)
	s_barrier
	s_setprio 1
	v_mfma_f32_16x16x128_f8f6f4 v[66:69], v[220:227], v[186:193], v[66:69]
	v_mfma_f32_16x16x128_f8f6f4 v[58:61], v[228:235], v[186:193], v[58:61]
	v_mfma_f32_16x16x128_f8f6f4 v[50:53], v[220:227], v[194:201], v[50:53]
	v_mfma_f32_16x16x128_f8f6f4 v[42:45], v[228:235], v[194:201], v[42:45]
	v_mfma_f32_16x16x128_f8f6f4 v[34:37], v[220:227], v[202:209], v[34:37]
	v_mfma_f32_16x16x128_f8f6f4 v[26:29], v[228:235], v[202:209], v[26:29]
	v_mfma_f32_16x16x128_f8f6f4 v[22:25], v[220:227], v[210:217], v[22:25]
	v_mfma_f32_16x16x128_f8f6f4 v[18:21], v[228:235], v[210:217], v[18:21]
	s_setprio 0
	s_barrier
	ds_read_b128 v[2:5], v169
	ds_read_b128 v[6:9], v177
	ds_read_b128 v[10:13], v178
	ds_read_b128 v[14:17], v179
	s_add_u32 s40, s40, 0x20000
	s_addc_u32 s41, s41, 0
	s_mov_b32 m0, s48
	v_lshl_add_u64 v[220:221], s[40:41], 0, v[148:149]
	ds_read_b128 v[186:189], v184 offset:32768
	ds_read_b128 v[190:193], v184 offset:33792
	ds_read_b128 v[194:197], v184 offset:34816
	ds_read_b128 v[198:201], v184 offset:35840
	ds_read_b128 v[202:205], v184 offset:36864
	ds_read_b128 v[206:209], v184 offset:37888
	ds_read_b128 v[210:213], v184 offset:38912
	ds_read_b128 v[214:217], v184 offset:39936
	global_load_lds_dwordx4 v[220:221], off
	v_lshl_add_u64 v[220:221], s[40:41], 0, v[146:147]
	s_mov_b32 m0, s49
	s_nop 0
	global_load_lds_dwordx4 v[220:221], off
	s_waitcnt lgkmcnt(8)
	s_barrier
	s_waitcnt lgkmcnt(0)
	s_setprio 1
	s_waitcnt lgkmcnt(0)
	v_mfma_f32_16x16x128_f8f6f4 v[142:145], v[2:9], v[186:193], v[142:145]
	v_mfma_f32_16x16x128_f8f6f4 v[138:141], v[10:17], v[186:193], v[138:141]
	v_mfma_f32_16x16x128_f8f6f4 v[134:137], v[2:9], v[194:201], v[134:137]
	v_mfma_f32_16x16x128_f8f6f4 v[126:129], v[10:17], v[194:201], v[126:129]
	v_mfma_f32_16x16x128_f8f6f4 v[118:121], v[2:9], v[202:209], v[118:121]
	v_mfma_f32_16x16x128_f8f6f4 v[110:113], v[10:17], v[202:209], v[110:113]
	v_mfma_f32_16x16x128_f8f6f4 v[102:105], v[2:9], v[210:217], v[102:105]
	v_mfma_f32_16x16x128_f8f6f4 v[94:97], v[10:17], v[210:217], v[94:97]
	s_setprio 0
	s_barrier
	s_mov_b32 m0, s55
	v_lshl_add_u64 v[158:159], v[158:159], 0, s[20:21]
	ds_read_b128 v[220:223], v170
	ds_read_b128 v[224:227], v180
	ds_read_b128 v[228:231], v181
	ds_read_b128 v[232:235], v182
	global_load_lds_dwordx4 v[158:159], off
	v_lshl_add_u64 v[158:159], v[160:161], 0, s[20:21]
	s_mov_b32 m0, s64
	s_nop 0
	global_load_lds_dwordx4 v[158:159], off
	s_barrier
	s_waitcnt lgkmcnt(0)
	s_setprio 1
	s_waitcnt lgkmcnt(0)
	v_mfma_f32_16x16x128_f8f6f4 v[130:133], v[220:227], v[186:193], v[130:133]
	v_mfma_f32_16x16x128_f8f6f4 v[122:125], v[228:235], v[186:193], v[122:125]
	v_mfma_f32_16x16x128_f8f6f4 v[114:117], v[220:227], v[194:201], v[114:117]
	v_mfma_f32_16x16x128_f8f6f4 v[106:109], v[228:235], v[194:201], v[106:109]
	v_mfma_f32_16x16x128_f8f6f4 v[98:101], v[220:227], v[202:209], v[98:101]
	v_mfma_f32_16x16x128_f8f6f4 v[90:93], v[228:235], v[202:209], v[90:93]
	v_mfma_f32_16x16x128_f8f6f4 v[86:89], v[220:227], v[210:217], v[86:89]
	v_mfma_f32_16x16x128_f8f6f4 v[82:85], v[228:235], v[210:217], v[82:85]
	s_setprio 0
	s_mov_b32 m0, s65
	v_lshl_add_u64 v[158:159], v[162:163], 0, s[20:21]
	s_barrier
	ds_read_b128 v[186:189], v184 offset:49152
	ds_read_b128 v[190:193], v184 offset:50176
	ds_read_b128 v[194:197], v184 offset:51200
	ds_read_b128 v[198:201], v184 offset:52224
	ds_read_b128 v[202:205], v184 offset:53248
	ds_read_b128 v[206:209], v184 offset:54272
	ds_read_b128 v[210:213], v184 offset:55296
	ds_read_b128 v[214:217], v184 offset:56320
	global_load_lds_dwordx4 v[158:159], off
	v_lshl_add_u64 v[158:159], v[164:165], 0, s[20:21]
	s_mov_b32 m0, s66
	s_nop 0
	global_load_lds_dwordx4 v[158:159], off
	s_barrier
	s_waitcnt lgkmcnt(0)
	s_setprio 1
	s_waitcnt lgkmcnt(0)
	v_mfma_f32_16x16x128_f8f6f4 v[78:81], v[2:9], v[186:193], v[78:81]
	v_mfma_f32_16x16x128_f8f6f4 v[74:77], v[10:17], v[186:193], v[74:77]
	v_mfma_f32_16x16x128_f8f6f4 v[70:73], v[2:9], v[194:201], v[70:73]
	v_mfma_f32_16x16x128_f8f6f4 v[62:65], v[10:17], v[194:201], v[62:65]
	v_mfma_f32_16x16x128_f8f6f4 v[54:57], v[2:9], v[202:209], v[54:57]
	v_mfma_f32_16x16x128_f8f6f4 v[46:49], v[10:17], v[202:209], v[46:49]
	v_mfma_f32_16x16x128_f8f6f4 v[38:41], v[2:9], v[210:217], v[38:41]
	v_mfma_f32_16x16x128_f8f6f4 v[30:33], v[10:17], v[210:217], v[30:33]
	s_setprio 0
	s_barrier
	s_add_u32 s38, s38, 0x20080
	s_addc_u32 s39, s39, 0
	s_mov_b32 m0, s67
	v_lshl_add_u64 v[2:3], s[38:39], 0, v[148:149]
	global_load_lds_dwordx4 v[2:3], off
	v_lshl_add_u64 v[2:3], s[38:39], 0, v[146:147]
	s_mov_b32 m0, s68
	s_nop 0
	global_load_lds_dwordx4 v[2:3], off
	s_waitcnt vmcnt(6)
	s_barrier
	s_setprio 1
	v_mfma_f32_16x16x128_f8f6f4 v[66:69], v[220:227], v[186:193], v[66:69]
	v_mfma_f32_16x16x128_f8f6f4 v[58:61], v[228:235], v[186:193], v[58:61]
	v_mfma_f32_16x16x128_f8f6f4 v[50:53], v[220:227], v[194:201], v[50:53]
	v_mfma_f32_16x16x128_f8f6f4 v[42:45], v[228:235], v[194:201], v[42:45]
	v_mfma_f32_16x16x128_f8f6f4 v[34:37], v[220:227], v[202:209], v[34:37]
	v_mfma_f32_16x16x128_f8f6f4 v[26:29], v[228:235], v[202:209], v[26:29]
	v_mfma_f32_16x16x128_f8f6f4 v[22:25], v[220:227], v[210:217], v[22:25]
	v_mfma_f32_16x16x128_f8f6f4 v[18:21], v[228:235], v[210:217], v[18:21]
	s_setprio 0
	s_add_i32 s76, s76, 2
	s_add_u32 s74, s74, 0x100
	s_addc_u32 s75, s75, 0
	s_add_u32 s36, s36, 0x100
	s_addc_u32 s37, s37, 0
	s_cmp_gt_u32 s76, 5
	s_barrier
	s_cbranch_scc0 .LBB0_3420
	v_bfe_u32 v160, v0, 4, 1
	v_mul_u32_u24_e32 v160, 24, v160
	v_mov_b32_e32 v161, 0
	v_lshl_or_b32 v4, s71, 8, v183
	v_pk_mul_f32 v[2:3], v[144:145], s[22:23] op_sel_hi:[1,0]
	v_pk_mul_f32 v[6:7], v[142:143], s[22:23] op_sel_hi:[1,0]
	v_lshl_add_u32 v12, s34, 8, v166
	v_cvt_pk_bf16_f32 v6, v6, v7
	v_cvt_pk_bf16_f32 v7, v2, v3
	v_mov_b64_e32 v[2:3], s[16:17]
	v_ashrrev_i32_e32 v5, 31, v4
	v_mad_i64_i32 v[8:9], s[36:37], v12, s70, v[2:3]
	v_lshlrev_b64 v[4:5], 1, v[4:5]
	v_lshl_add_u64 v[8:9], v[8:9], 0, v[4:5]
	s_nop 15
	s_nop 15
	v_mov_b32_e32 v192, v6
	v_mov_b32_e32 v193, v7
	v_pk_mul_f32 v[6:7], v[140:141], s[22:23] op_sel_hi:[1,0]
	v_pk_mul_f32 v[10:11], v[138:139], s[22:23] op_sel_hi:[1,0]
	s_and_b64 vcc, exec, s[12:13]
	v_cvt_pk_bf16_f32 v10, v10, v11
	v_cvt_pk_bf16_f32 v11, v6, v7
	v_mov_b32_e32 v194, v10
	v_mov_b32_e32 v195, v11
	v_lshl_add_u64 v[162:163], v[8:9], 0, v[160:161]
	s_nop 0
	v_permlane16_swap_b32 v192, v194
	v_permlane16_swap_b32 v193, v195
	global_store_dwordx4 v[162:163], v[192:195], off
	v_pk_mul_f32 v[6:7], v[132:133], s[22:23] op_sel_hi:[1,0]
	v_pk_mul_f32 v[10:11], v[130:131], s[22:23] op_sel_hi:[1,0]
	s_mov_b32 s71, s24
	v_cvt_pk_bf16_f32 v10, v10, v11
	v_cvt_pk_bf16_f32 v11, v6, v7
	v_mov_b32_e32 v196, v10
	v_mov_b32_e32 v197, v11
	v_pk_mul_f32 v[6:7], v[124:125], s[22:23] op_sel_hi:[1,0]
	v_pk_mul_f32 v[10:11], v[122:123], s[22:23] op_sel_hi:[1,0]
	s_mov_b32 s34, s26
	v_cvt_pk_bf16_f32 v10, v10, v11
	v_cvt_pk_bf16_f32 v11, v6, v7
	v_mov_b32_e32 v198, v10
	v_mov_b32_e32 v199, v11
	v_lshl_add_u64 v[162:163], v[8:9], 0, v[160:161]
	s_nop 0
	v_permlane16_swap_b32 v196, v198
	v_permlane16_swap_b32 v197, v199
	global_store_dwordx4 v[162:163], v[196:199], off offset:256
	v_or_b32_e32 v10, 16, v12
	v_pk_mul_f32 v[6:7], v[136:137], s[22:23] op_sel_hi:[1,0]
	v_pk_mul_f32 v[8:9], v[134:135], s[22:23] op_sel_hi:[1,0]
	s_mov_b64 s[38:39], s[28:29]
	v_cvt_pk_bf16_f32 v8, v8, v9
	v_cvt_pk_bf16_f32 v9, v6, v7
	v_mad_i64_i32 v[6:7], s[36:37], v10, s70, v[2:3]
	v_lshl_add_u64 v[6:7], v[6:7], 0, v[4:5]
	v_mov_b32_e32 v200, v8
	v_mov_b32_e32 v201, v9
	v_pk_mul_f32 v[8:9], v[128:129], s[22:23] op_sel_hi:[1,0]
	v_pk_mul_f32 v[10:11], v[126:127], s[22:23] op_sel_hi:[1,0]
	s_nop 0
	v_cvt_pk_bf16_f32 v10, v10, v11
	v_cvt_pk_bf16_f32 v11, v8, v9
	v_mov_b32_e32 v202, v10
	v_mov_b32_e32 v203, v11
	v_lshl_add_u64 v[162:163], v[6:7], 0, v[160:161]
	s_nop 0
	v_permlane16_swap_b32 v200, v202
	v_permlane16_swap_b32 v201, v203
	global_store_dwordx4 v[162:163], v[200:203], off
	v_pk_mul_f32 v[8:9], v[116:117], s[22:23] op_sel_hi:[1,0]
	v_pk_mul_f32 v[10:11], v[114:115], s[22:23] op_sel_hi:[1,0]
	s_nop 0
	v_cvt_pk_bf16_f32 v10, v10, v11
	v_cvt_pk_bf16_f32 v11, v8, v9
	v_mov_b32_e32 v204, v10
	v_mov_b32_e32 v205, v11
	v_pk_mul_f32 v[8:9], v[108:109], s[22:23] op_sel_hi:[1,0]
	v_pk_mul_f32 v[10:11], v[106:107], s[22:23] op_sel_hi:[1,0]
	s_nop 0
	v_cvt_pk_bf16_f32 v10, v10, v11
	v_cvt_pk_bf16_f32 v11, v8, v9
	v_mov_b32_e32 v206, v10
	v_mov_b32_e32 v207, v11
	v_lshl_add_u64 v[162:163], v[6:7], 0, v[160:161]
	s_nop 0
	v_permlane16_swap_b32 v204, v206
	v_permlane16_swap_b32 v205, v207
	global_store_dwordx4 v[162:163], v[204:207], off offset:256
	v_or_b32_e32 v10, 32, v12
	v_pk_mul_f32 v[6:7], v[120:121], s[22:23] op_sel_hi:[1,0]
	v_pk_mul_f32 v[8:9], v[118:119], s[22:23] op_sel_hi:[1,0]
	s_nop 0
	v_cvt_pk_bf16_f32 v8, v8, v9
	v_cvt_pk_bf16_f32 v9, v6, v7
	v_mad_i64_i32 v[6:7], s[36:37], v10, s70, v[2:3]
	v_lshl_add_u64 v[6:7], v[6:7], 0, v[4:5]
	v_mov_b32_e32 v208, v8
	v_mov_b32_e32 v209, v9
	v_pk_mul_f32 v[8:9], v[112:113], s[22:23] op_sel_hi:[1,0]
	v_pk_mul_f32 v[10:11], v[110:111], s[22:23] op_sel_hi:[1,0]
	s_nop 0
	v_cvt_pk_bf16_f32 v10, v10, v11
	v_cvt_pk_bf16_f32 v11, v8, v9
	v_mov_b32_e32 v210, v10
	v_mov_b32_e32 v211, v11
	v_lshl_add_u64 v[162:163], v[6:7], 0, v[160:161]
	s_nop 0
	v_permlane16_swap_b32 v208, v210
	v_permlane16_swap_b32 v209, v211
	global_store_dwordx4 v[162:163], v[208:211], off
	v_pk_mul_f32 v[8:9], v[100:101], s[22:23] op_sel_hi:[1,0]
	v_pk_mul_f32 v[10:11], v[98:99], s[22:23] op_sel_hi:[1,0]
	s_nop 0
	v_cvt_pk_bf16_f32 v10, v10, v11
	v_cvt_pk_bf16_f32 v11, v8, v9
	v_mov_b32_e32 v212, v10
	v_mov_b32_e32 v213, v11
	v_pk_mul_f32 v[8:9], v[92:93], s[22:23] op_sel_hi:[1,0]
	v_pk_mul_f32 v[10:11], v[90:91], s[22:23] op_sel_hi:[1,0]
	s_nop 0
	v_cvt_pk_bf16_f32 v10, v10, v11
	v_cvt_pk_bf16_f32 v11, v8, v9
	v_mov_b32_e32 v214, v10
	v_mov_b32_e32 v215, v11
	v_lshl_add_u64 v[162:163], v[6:7], 0, v[160:161]
	s_nop 0
	v_permlane16_swap_b32 v212, v214
	v_permlane16_swap_b32 v213, v215
	global_store_dwordx4 v[162:163], v[212:215], off offset:256
	v_or_b32_e32 v10, 48, v12
	v_pk_mul_f32 v[6:7], v[104:105], s[22:23] op_sel_hi:[1,0]
	v_pk_mul_f32 v[8:9], v[102:103], s[22:23] op_sel_hi:[1,0]
	s_nop 0
	v_cvt_pk_bf16_f32 v8, v8, v9
	v_cvt_pk_bf16_f32 v9, v6, v7
	v_mad_i64_i32 v[6:7], s[36:37], v10, s70, v[2:3]
	v_lshl_add_u64 v[6:7], v[6:7], 0, v[4:5]
	v_mov_b32_e32 v220, v8
	v_mov_b32_e32 v221, v9
	v_pk_mul_f32 v[8:9], v[96:97], s[22:23] op_sel_hi:[1,0]
	v_pk_mul_f32 v[10:11], v[94:95], s[22:23] op_sel_hi:[1,0]
	s_nop 0
	v_cvt_pk_bf16_f32 v10, v10, v11
	v_cvt_pk_bf16_f32 v11, v8, v9
	v_mov_b32_e32 v222, v10
	v_mov_b32_e32 v223, v11
	v_lshl_add_u64 v[162:163], v[6:7], 0, v[160:161]
	s_nop 0
	v_permlane16_swap_b32 v220, v222
	v_permlane16_swap_b32 v221, v223
	global_store_dwordx4 v[162:163], v[220:223], off
	v_pk_mul_f32 v[8:9], v[88:89], s[22:23] op_sel_hi:[1,0]
	v_pk_mul_f32 v[10:11], v[86:87], s[22:23] op_sel_hi:[1,0]
	s_nop 0
	v_cvt_pk_bf16_f32 v10, v10, v11
	v_cvt_pk_bf16_f32 v11, v8, v9
	v_mov_b32_e32 v224, v10
	v_mov_b32_e32 v225, v11
	v_pk_mul_f32 v[8:9], v[84:85], s[22:23] op_sel_hi:[1,0]
	v_pk_mul_f32 v[10:11], v[82:83], s[22:23] op_sel_hi:[1,0]
	s_nop 0
	v_cvt_pk_bf16_f32 v10, v10, v11
	v_cvt_pk_bf16_f32 v11, v8, v9
	v_mov_b32_e32 v226, v10
	v_mov_b32_e32 v227, v11
	v_lshl_add_u64 v[162:163], v[6:7], 0, v[160:161]
	s_nop 0
	v_permlane16_swap_b32 v224, v226
	v_permlane16_swap_b32 v225, v227
	global_store_dwordx4 v[162:163], v[224:227], off offset:256
	v_add_u32_e32 v10, 0x80, v12
	v_pk_mul_f32 v[6:7], v[80:81], s[22:23] op_sel_hi:[1,0]
	v_pk_mul_f32 v[8:9], v[78:79], s[22:23] op_sel_hi:[1,0]
	s_nop 0
	v_cvt_pk_bf16_f32 v8, v8, v9
	v_cvt_pk_bf16_f32 v9, v6, v7
	v_mad_i64_i32 v[6:7], s[36:37], v10, s70, v[2:3]
	v_lshl_add_u64 v[6:7], v[6:7], 0, v[4:5]
	v_mov_b32_e32 v228, v8
	v_mov_b32_e32 v229, v9
	v_pk_mul_f32 v[8:9], v[76:77], s[22:23] op_sel_hi:[1,0]
	v_pk_mul_f32 v[10:11], v[74:75], s[22:23] op_sel_hi:[1,0]
	s_nop 0
	v_cvt_pk_bf16_f32 v10, v10, v11
	v_cvt_pk_bf16_f32 v11, v8, v9
	v_mov_b32_e32 v230, v10
	v_mov_b32_e32 v231, v11
	v_lshl_add_u64 v[162:163], v[6:7], 0, v[160:161]
	s_nop 0
	v_permlane16_swap_b32 v228, v230
	v_permlane16_swap_b32 v229, v231
	global_store_dwordx4 v[162:163], v[228:231], off
	v_pk_mul_f32 v[8:9], v[68:69], s[22:23] op_sel_hi:[1,0]
	v_pk_mul_f32 v[10:11], v[66:67], s[22:23] op_sel_hi:[1,0]
	s_nop 0
	v_cvt_pk_bf16_f32 v10, v10, v11
	v_cvt_pk_bf16_f32 v11, v8, v9
	v_mov_b32_e32 v232, v10
	v_mov_b32_e32 v233, v11
	v_pk_mul_f32 v[8:9], v[60:61], s[22:23] op_sel_hi:[1,0]
	v_pk_mul_f32 v[10:11], v[58:59], s[22:23] op_sel_hi:[1,0]
	s_nop 0
	v_cvt_pk_bf16_f32 v10, v10, v11
	v_cvt_pk_bf16_f32 v11, v8, v9
	v_mov_b32_e32 v234, v10
	v_mov_b32_e32 v235, v11
	v_lshl_add_u64 v[162:163], v[6:7], 0, v[160:161]
	s_nop 0
	v_permlane16_swap_b32 v232, v234
	v_permlane16_swap_b32 v233, v235
	global_store_dwordx4 v[162:163], v[232:235], off offset:256
	v_add_u32_e32 v10, 0x90, v12
	v_pk_mul_f32 v[6:7], v[72:73], s[22:23] op_sel_hi:[1,0]
	v_pk_mul_f32 v[8:9], v[70:71], s[22:23] op_sel_hi:[1,0]
	s_nop 0
	v_cvt_pk_bf16_f32 v8, v8, v9
	v_cvt_pk_bf16_f32 v9, v6, v7
	v_mad_i64_i32 v[6:7], s[36:37], v10, s70, v[2:3]
	v_lshl_add_u64 v[6:7], v[6:7], 0, v[4:5]
	v_mov_b32_e32 v236, v8
	v_mov_b32_e32 v237, v9
	v_pk_mul_f32 v[8:9], v[64:65], s[22:23] op_sel_hi:[1,0]
	v_pk_mul_f32 v[10:11], v[62:63], s[22:23] op_sel_hi:[1,0]
	s_nop 0
	v_cvt_pk_bf16_f32 v10, v10, v11
	v_cvt_pk_bf16_f32 v11, v8, v9
	v_mov_b32_e32 v238, v10
	v_mov_b32_e32 v239, v11
	v_lshl_add_u64 v[162:163], v[6:7], 0, v[160:161]
	s_nop 0
	v_permlane16_swap_b32 v236, v238
	v_permlane16_swap_b32 v237, v239
	global_store_dwordx4 v[162:163], v[236:239], off
	v_pk_mul_f32 v[8:9], v[52:53], s[22:23] op_sel_hi:[1,0]
	v_pk_mul_f32 v[10:11], v[50:51], s[22:23] op_sel_hi:[1,0]
	s_nop 0
	v_cvt_pk_bf16_f32 v10, v10, v11
	v_cvt_pk_bf16_f32 v11, v8, v9
	v_mov_b32_e32 v192, v10
	v_mov_b32_e32 v193, v11
	v_pk_mul_f32 v[8:9], v[44:45], s[22:23] op_sel_hi:[1,0]
	v_pk_mul_f32 v[10:11], v[42:43], s[22:23] op_sel_hi:[1,0]
	s_nop 0
	v_cvt_pk_bf16_f32 v10, v10, v11
	v_cvt_pk_bf16_f32 v11, v8, v9
	v_mov_b32_e32 v194, v10
	v_mov_b32_e32 v195, v11
	v_lshl_add_u64 v[162:163], v[6:7], 0, v[160:161]
	s_nop 0
	v_permlane16_swap_b32 v192, v194
	v_permlane16_swap_b32 v193, v195
	global_store_dwordx4 v[162:163], v[192:195], off offset:256
	v_add_u32_e32 v10, 0xa0, v12
	v_pk_mul_f32 v[6:7], v[56:57], s[22:23] op_sel_hi:[1,0]
	v_pk_mul_f32 v[8:9], v[54:55], s[22:23] op_sel_hi:[1,0]
	s_nop 0
	v_cvt_pk_bf16_f32 v8, v8, v9
	v_cvt_pk_bf16_f32 v9, v6, v7
	v_mad_i64_i32 v[6:7], s[36:37], v10, s70, v[2:3]
	v_lshl_add_u64 v[6:7], v[6:7], 0, v[4:5]
	v_mov_b32_e32 v196, v8
	v_mov_b32_e32 v197, v9
	v_pk_mul_f32 v[8:9], v[48:49], s[22:23] op_sel_hi:[1,0]
	v_pk_mul_f32 v[10:11], v[46:47], s[22:23] op_sel_hi:[1,0]
	s_nop 0
	v_cvt_pk_bf16_f32 v10, v10, v11
	v_cvt_pk_bf16_f32 v11, v8, v9
	v_mov_b32_e32 v198, v10
	v_mov_b32_e32 v199, v11
	v_lshl_add_u64 v[162:163], v[6:7], 0, v[160:161]
	s_nop 0
	v_permlane16_swap_b32 v196, v198
	v_permlane16_swap_b32 v197, v199
	global_store_dwordx4 v[162:163], v[196:199], off
	v_pk_mul_f32 v[8:9], v[36:37], s[22:23] op_sel_hi:[1,0]
	v_pk_mul_f32 v[10:11], v[34:35], s[22:23] op_sel_hi:[1,0]
	s_nop 0
	v_cvt_pk_bf16_f32 v10, v10, v11
	v_cvt_pk_bf16_f32 v11, v8, v9
	v_mov_b32_e32 v200, v10
	v_mov_b32_e32 v201, v11
	v_pk_mul_f32 v[8:9], v[28:29], s[22:23] op_sel_hi:[1,0]
	v_pk_mul_f32 v[10:11], v[26:27], s[22:23] op_sel_hi:[1,0]
	s_nop 0
	v_cvt_pk_bf16_f32 v10, v10, v11
	v_cvt_pk_bf16_f32 v11, v8, v9
	v_mov_b32_e32 v202, v10
	v_mov_b32_e32 v203, v11
	v_lshl_add_u64 v[162:163], v[6:7], 0, v[160:161]
	s_nop 0
	v_permlane16_swap_b32 v200, v202
	v_permlane16_swap_b32 v201, v203
	global_store_dwordx4 v[162:163], v[200:203], off offset:256
	v_add_u32_e32 v10, 0xb0, v12
	v_pk_mul_f32 v[6:7], v[40:41], s[22:23] op_sel_hi:[1,0]
	v_pk_mul_f32 v[8:9], v[38:39], s[22:23] op_sel_hi:[1,0]
	v_mad_i64_i32 v[2:3], s[36:37], v10, s70, v[2:3]
	v_cvt_pk_bf16_f32 v8, v8, v9
	v_cvt_pk_bf16_f32 v9, v6, v7
	v_lshl_add_u64 v[2:3], v[2:3], 0, v[4:5]
	v_pk_mul_f32 v[4:5], v[32:33], s[22:23] op_sel_hi:[1,0]
	v_pk_mul_f32 v[6:7], v[30:31], s[22:23] op_sel_hi:[1,0]
	s_mov_b64 s[36:37], s[30:31]
	v_cvt_pk_bf16_f32 v6, v6, v7
	v_cvt_pk_bf16_f32 v7, v4, v5
	v_mov_b32_e32 v206, v6
	v_mov_b32_e32 v207, v7
	v_pk_mul_f32 v[4:5], v[24:25], s[22:23] op_sel_hi:[1,0]
	v_pk_mul_f32 v[6:7], v[22:23], s[22:23] op_sel_hi:[1,0]
	v_mov_b32_e32 v204, v8
	v_mov_b32_e32 v205, v9
	v_lshl_add_u64 v[162:163], v[2:3], 0, v[160:161]
	s_nop 0
	v_permlane16_swap_b32 v204, v206
	v_permlane16_swap_b32 v205, v207
	global_store_dwordx4 v[162:163], v[204:207], off
	v_cvt_pk_bf16_f32 v6, v6, v7
	v_cvt_pk_bf16_f32 v7, v4, v5
	v_mov_b32_e32 v208, v6
	v_mov_b32_e32 v209, v7
	v_pk_mul_f32 v[4:5], v[20:21], s[22:23] op_sel_hi:[1,0]
	v_pk_mul_f32 v[6:7], v[18:19], s[22:23] op_sel_hi:[1,0]
	s_nop 0
	v_cvt_pk_bf16_f32 v6, v6, v7
	v_cvt_pk_bf16_f32 v7, v4, v5
	v_mov_b32_e32 v210, v6
	v_mov_b32_e32 v211, v7
	v_lshl_add_u64 v[162:163], v[2:3], 0, v[160:161]
	s_nop 0
	v_permlane16_swap_b32 v208, v210
	v_permlane16_swap_b32 v209, v211
	global_store_dwordx4 v[162:163], v[208:211], off offset:256
	s_cbranch_vccz .LBB0_3417
	s_waitcnt vmcnt(0)
	s_cmpk_gt_u32 s3, 0xff
	v_readlane_b32 s4, v252, 8
	s_cbranch_scc1 .LBB0_3424
	s_barrier

.LBB0_4318:
	ds_read_b128 v[2:5], v167
	ds_read_b128 v[6:9], v171
	ds_read_b128 v[10:13], v172
	ds_read_b128 v[14:17], v173
	s_add_u32 s0, s30, 0xfffe0080
	s_addc_u32 s1, s31, -1
	s_cmp_eq_u32 s73, 4
	s_cselect_b32 s37, s23, s1
	s_cselect_b32 s36, s69, s0
	s_cselect_b32 s35, s21, s72
	s_cselect_b32 s34, s70, s71
	v_lshl_add_u64 v[158:159], s[30:31], 0, v[152:153]
	s_add_i32 m0, s29, 0xc000
	ds_read_b128 v[186:189], v184
	ds_read_b128 v[190:193], v184 offset:1024
	ds_read_b128 v[194:197], v184 offset:2048
	ds_read_b128 v[198:201], v184 offset:3072
	ds_read_b128 v[202:205], v184 offset:4096
	ds_read_b128 v[206:209], v184 offset:5120
	ds_read_b128 v[210:213], v184 offset:6144
	ds_read_b128 v[214:217], v184 offset:7168
	global_load_lds_dwordx4 v[158:159], off
	v_lshl_add_u64 v[158:159], s[30:31], 0, v[150:151]
	s_add_i32 m0, s29, 0xe000
	s_nop 0
	global_load_lds_dwordx4 v[158:159], off
	s_waitcnt lgkmcnt(8)
	s_barrier
	s_waitcnt lgkmcnt(0)
	s_setprio 1
	s_waitcnt lgkmcnt(0)
	v_mfma_f32_16x16x128_f8f6f4 v[142:145], v[2:9], v[186:193], v[142:145]
	v_mfma_f32_16x16x128_f8f6f4 v[138:141], v[10:17], v[186:193], v[138:141]
	v_mfma_f32_16x16x128_f8f6f4 v[126:129], v[2:9], v[194:201], v[126:129]
	v_mfma_f32_16x16x128_f8f6f4 v[122:125], v[10:17], v[194:201], v[122:125]
	v_mfma_f32_16x16x128_f8f6f4 v[110:113], v[2:9], v[202:209], v[110:113]
	v_mfma_f32_16x16x128_f8f6f4 v[106:109], v[10:17], v[202:209], v[106:109]
	v_mfma_f32_16x16x128_f8f6f4 v[94:97], v[2:9], v[210:217], v[94:97]
	v_mfma_f32_16x16x128_f8f6f4 v[90:93], v[10:17], v[210:217], v[90:93]
	s_setprio 0
	s_barrier
	s_mov_b32 m0, s43
	v_lshl_add_u64 v[158:159], s[34:35], 0, v[148:149]
	ds_read_b128 v[220:223], v168
	ds_read_b128 v[224:227], v174
	ds_read_b128 v[228:231], v175
	ds_read_b128 v[232:235], v176
	global_load_lds_dwordx4 v[158:159], off
	v_lshl_add_u64 v[160:161], s[34:35], 0, v[146:147]
	s_mov_b32 m0, s44
	s_nop 0
	global_load_lds_dwordx4 v[160:161], off
	s_barrier
	s_waitcnt lgkmcnt(0)
	s_setprio 1
	s_waitcnt lgkmcnt(0)
	v_mfma_f32_16x16x128_f8f6f4 v[134:137], v[220:227], v[186:193], v[134:137]
	v_mfma_f32_16x16x128_f8f6f4 v[130:133], v[228:235], v[186:193], v[130:133]
	v_mfma_f32_16x16x128_f8f6f4 v[118:121], v[220:227], v[194:201], v[118:121]
	v_mfma_f32_16x16x128_f8f6f4 v[114:117], v[228:235], v[194:201], v[114:117]
	v_mfma_f32_16x16x128_f8f6f4 v[102:105], v[220:227], v[202:209], v[102:105]
	v_mfma_f32_16x16x128_f8f6f4 v[98:101], v[228:235], v[202:209], v[98:101]
	v_mfma_f32_16x16x128_f8f6f4 v[86:89], v[220:227], v[210:217], v[86:89]
	v_mfma_f32_16x16x128_f8f6f4 v[82:85], v[228:235], v[210:217], v[82:85]
	s_setprio 0
	s_mov_b32 m0, s29
	v_lshl_add_u64 v[162:163], s[36:37], 0, v[148:149]
	s_barrier
	ds_read_b128 v[186:189], v184 offset:16384
	ds_read_b128 v[190:193], v184 offset:17408
	ds_read_b128 v[194:197], v184 offset:18432
	ds_read_b128 v[198:201], v184 offset:19456
	ds_read_b128 v[202:205], v184 offset:20480
	ds_read_b128 v[206:209], v184 offset:21504
	ds_read_b128 v[210:213], v184 offset:22528
	ds_read_b128 v[214:217], v184 offset:23552
	global_load_lds_dwordx4 v[162:163], off
	v_lshl_add_u64 v[164:165], s[36:37], 0, v[146:147]
	s_mov_b32 m0, s45
	s_nop 0
	global_load_lds_dwordx4 v[164:165], off
	s_barrier
	s_waitcnt lgkmcnt(0)
	s_setprio 1
	s_waitcnt lgkmcnt(0)
	v_mfma_f32_16x16x128_f8f6f4 v[78:81], v[2:9], v[186:193], v[78:81]
	v_mfma_f32_16x16x128_f8f6f4 v[74:77], v[10:17], v[186:193], v[74:77]
	v_mfma_f32_16x16x128_f8f6f4 v[62:65], v[2:9], v[194:201], v[62:65]
	v_mfma_f32_16x16x128_f8f6f4 v[58:61], v[10:17], v[194:201], v[58:61]
	v_mfma_f32_16x16x128_f8f6f4 v[46:49], v[2:9], v[202:209], v[46:49]
	v_mfma_f32_16x16x128_f8f6f4 v[42:45], v[10:17], v[202:209], v[42:45]
	v_mfma_f32_16x16x128_f8f6f4 v[30:33], v[2:9], v[210:217], v[30:33]
	v_mfma_f32_16x16x128_f8f6f4 v[26:29], v[10:17], v[210:217], v[26:29]
	s_setprio 0
	s_barrier
	s_add_u32 s74, s34, 0x20000
	s_addc_u32 s75, s35, 0
	s_mov_b32 m0, s46
	v_lshl_add_u64 v[2:3], s[74:75], 0, v[148:149]
	global_load_lds_dwordx4 v[2:3], off
	v_lshl_add_u64 v[2:3], s[74:75], 0, v[146:147]
	s_mov_b32 m0, s47
	s_nop 0
	global_load_lds_dwordx4 v[2:3], off
	s_waitcnt vmcnt(6)
	s_barrier
	s_setprio 1
	v_mfma_f32_16x16x128_f8f6f4 v[70:73], v[220:227], v[186:193], v[70:73]
	v_mfma_f32_16x16x128_f8f6f4 v[66:69], v[228:235], v[186:193], v[66:69]
	v_mfma_f32_16x16x128_f8f6f4 v[54:57], v[220:227], v[194:201], v[54:57]
	v_mfma_f32_16x16x128_f8f6f4 v[50:53], v[228:235], v[194:201], v[50:53]
	v_mfma_f32_16x16x128_f8f6f4 v[38:41], v[220:227], v[202:209], v[38:41]
	v_mfma_f32_16x16x128_f8f6f4 v[34:37], v[228:235], v[202:209], v[34:37]
	v_mfma_f32_16x16x128_f8f6f4 v[22:25], v[220:227], v[210:217], v[22:25]
	v_mfma_f32_16x16x128_f8f6f4 v[18:21], v[228:235], v[210:217], v[18:21]
	s_setprio 0
	s_barrier
	ds_read_b128 v[2:5], v169
	ds_read_b128 v[6:9], v177
	ds_read_b128 v[10:13], v178
	ds_read_b128 v[14:17], v179
	s_add_u32 s36, s36, 0x20000
	s_addc_u32 s37, s37, 0
	s_mov_b32 m0, s48
	v_lshl_add_u64 v[220:221], s[36:37], 0, v[148:149]
	ds_read_b128 v[186:189], v184 offset:32768
	ds_read_b128 v[190:193], v184 offset:33792
	ds_read_b128 v[194:197], v184 offset:34816
	ds_read_b128 v[198:201], v184 offset:35840
	ds_read_b128 v[202:205], v184 offset:36864
	ds_read_b128 v[206:209], v184 offset:37888
	ds_read_b128 v[210:213], v184 offset:38912
	ds_read_b128 v[214:217], v184 offset:39936
	global_load_lds_dwordx4 v[220:221], off
	v_lshl_add_u64 v[220:221], s[36:37], 0, v[146:147]
	s_mov_b32 m0, s49
	s_nop 0
	global_load_lds_dwordx4 v[220:221], off
	s_waitcnt lgkmcnt(8)
	s_barrier
	s_waitcnt lgkmcnt(0)
	s_setprio 1
	s_waitcnt lgkmcnt(0)
	v_mfma_f32_16x16x128_f8f6f4 v[142:145], v[2:9], v[186:193], v[142:145]
	v_mfma_f32_16x16x128_f8f6f4 v[138:141], v[10:17], v[186:193], v[138:141]
	v_mfma_f32_16x16x128_f8f6f4 v[126:129], v[2:9], v[194:201], v[126:129]
	v_mfma_f32_16x16x128_f8f6f4 v[122:125], v[10:17], v[194:201], v[122:125]
	v_mfma_f32_16x16x128_f8f6f4 v[110:113], v[2:9], v[202:209], v[110:113]
	v_mfma_f32_16x16x128_f8f6f4 v[106:109], v[10:17], v[202:209], v[106:109]
	v_mfma_f32_16x16x128_f8f6f4 v[94:97], v[2:9], v[210:217], v[94:97]
	v_mfma_f32_16x16x128_f8f6f4 v[90:93], v[10:17], v[210:217], v[90:93]
	s_setprio 0
	s_barrier
	s_mov_b32 m0, s53
	v_lshl_add_u64 v[158:159], v[158:159], 0, s[16:17]
	ds_read_b128 v[220:223], v170
	ds_read_b128 v[224:227], v180
	ds_read_b128 v[228:231], v181
	ds_read_b128 v[232:235], v182
	global_load_lds_dwordx4 v[158:159], off
	v_lshl_add_u64 v[158:159], v[160:161], 0, s[16:17]
	s_mov_b32 m0, s55
	s_nop 0
	global_load_lds_dwordx4 v[158:159], off
	s_barrier
	s_waitcnt lgkmcnt(0)
	s_setprio 1
	s_waitcnt lgkmcnt(0)
	v_mfma_f32_16x16x128_f8f6f4 v[134:137], v[220:227], v[186:193], v[134:137]
	v_mfma_f32_16x16x128_f8f6f4 v[130:133], v[228:235], v[186:193], v[130:133]
	v_mfma_f32_16x16x128_f8f6f4 v[118:121], v[220:227], v[194:201], v[118:121]
	v_mfma_f32_16x16x128_f8f6f4 v[114:117], v[228:235], v[194:201], v[114:117]
	v_mfma_f32_16x16x128_f8f6f4 v[102:105], v[220:227], v[202:209], v[102:105]
	v_mfma_f32_16x16x128_f8f6f4 v[98:101], v[228:235], v[202:209], v[98:101]
	v_mfma_f32_16x16x128_f8f6f4 v[86:89], v[220:227], v[210:217], v[86:89]
	v_mfma_f32_16x16x128_f8f6f4 v[82:85], v[228:235], v[210:217], v[82:85]
	s_setprio 0
	s_mov_b32 m0, s62
	v_lshl_add_u64 v[158:159], v[162:163], 0, s[16:17]
	s_barrier
	ds_read_b128 v[186:189], v184 offset:49152
	ds_read_b128 v[190:193], v184 offset:50176
	ds_read_b128 v[194:197], v184 offset:51200
	ds_read_b128 v[198:201], v184 offset:52224
	ds_read_b128 v[202:205], v184 offset:53248
	ds_read_b128 v[206:209], v184 offset:54272
	ds_read_b128 v[210:213], v184 offset:55296
	ds_read_b128 v[214:217], v184 offset:56320
	global_load_lds_dwordx4 v[158:159], off
	v_lshl_add_u64 v[158:159], v[164:165], 0, s[16:17]
	s_mov_b32 m0, s63
	s_nop 0
	global_load_lds_dwordx4 v[158:159], off
	s_barrier
	s_waitcnt lgkmcnt(0)
	s_setprio 1
	s_waitcnt lgkmcnt(0)
	v_mfma_f32_16x16x128_f8f6f4 v[78:81], v[2:9], v[186:193], v[78:81]
	v_mfma_f32_16x16x128_f8f6f4 v[74:77], v[10:17], v[186:193], v[74:77]
	v_mfma_f32_16x16x128_f8f6f4 v[62:65], v[2:9], v[194:201], v[62:65]
	v_mfma_f32_16x16x128_f8f6f4 v[58:61], v[10:17], v[194:201], v[58:61]
	v_mfma_f32_16x16x128_f8f6f4 v[46:49], v[2:9], v[202:209], v[46:49]
	v_mfma_f32_16x16x128_f8f6f4 v[42:45], v[10:17], v[202:209], v[42:45]
	v_mfma_f32_16x16x128_f8f6f4 v[30:33], v[2:9], v[210:217], v[30:33]
	v_mfma_f32_16x16x128_f8f6f4 v[26:29], v[10:17], v[210:217], v[26:29]
	s_setprio 0
	s_barrier
	s_add_u32 s34, s34, 0x20080
	s_addc_u32 s35, s35, 0
	s_mov_b32 m0, s64
	v_lshl_add_u64 v[2:3], s[34:35], 0, v[148:149]
	global_load_lds_dwordx4 v[2:3], off
	v_lshl_add_u64 v[2:3], s[34:35], 0, v[146:147]
	s_mov_b32 m0, s65
	s_nop 0
	global_load_lds_dwordx4 v[2:3], off
	s_waitcnt vmcnt(6)
	s_barrier
	s_setprio 1
	v_mfma_f32_16x16x128_f8f6f4 v[70:73], v[220:227], v[186:193], v[70:73]
	v_mfma_f32_16x16x128_f8f6f4 v[66:69], v[228:235], v[186:193], v[66:69]
	v_mfma_f32_16x16x128_f8f6f4 v[54:57], v[220:227], v[194:201], v[54:57]
	v_mfma_f32_16x16x128_f8f6f4 v[50:53], v[228:235], v[194:201], v[50:53]
	v_mfma_f32_16x16x128_f8f6f4 v[38:41], v[220:227], v[202:209], v[38:41]
	v_mfma_f32_16x16x128_f8f6f4 v[34:37], v[228:235], v[202:209], v[34:37]
	v_mfma_f32_16x16x128_f8f6f4 v[22:25], v[220:227], v[210:217], v[22:25]
	v_mfma_f32_16x16x128_f8f6f4 v[18:21], v[228:235], v[210:217], v[18:21]
	s_setprio 0
	s_add_i32 s73, s73, 2
	s_add_u32 s71, s71, 0x100
	s_addc_u32 s72, s72, 0
	s_add_u32 s30, s30, 0x100
	s_addc_u32 s31, s31, 0
	s_cmp_gt_u32 s73, 5
	s_barrier
	s_cbranch_scc0 .LBB0_4318
	v_bfe_u32 v196, v0, 4, 1
	v_mul_u32_u24_e32 v196, 24, v196
	v_mov_b32_e32 v197, 0
	v_lshl_or_b32 v10, s68, 8, v183
	v_or_b32_e32 v2, 0x80, v10
	v_ashrrev_i32_e32 v3, 31, v2
	v_lshl_add_u64 v[14:15], v[2:3], 2, s[14:15]
	v_or_b32_e32 v2, 16, v10
	v_ashrrev_i32_e32 v11, 31, v10
	v_ashrrev_i32_e32 v3, 31, v2
	s_nop 15
	s_nop 15
	v_lshl_add_u64 v[16:17], v[10:11], 2, s[14:15]
	v_lshl_add_u64 v[158:159], v[2:3], 2, s[14:15]
	global_load_dwordx4 v[186:189], v[16:17], off
	global_load_dwordx4 v[190:193], v[158:159], off
	global_load_dwordx4 v[6:9], v[14:15], off
	v_or_b32_e32 v2, 0x90, v10
	v_ashrrev_i32_e32 v3, 31, v2
	v_lshl_add_u64 v[160:161], v[2:3], 2, s[14:15]
	global_load_dwordx4 v[2:5], v[160:161], off
	v_lshl_add_u32 v162, s28, 8, v166
	v_mov_b64_e32 v[12:13], s[12:13]
	v_mad_i64_i32 v[164:165], s[30:31], v162, s67, v[12:13]
	v_lshlrev_b64 v[10:11], 1, v[10:11]
	v_lshl_add_u64 v[164:165], v[164:165], 0, v[10:11]
	s_and_b64 vcc, exec, s[8:9]
	s_mov_b32 s68, s20
	s_mov_b32 s28, s22
	s_mov_b64 s[34:35], s[24:25]
	s_waitcnt vmcnt(0)
	v_pk_fma_f32 v[142:143], v[142:143], s[18:19], v[186:187] op_sel_hi:[1,0,1]
	v_pk_fma_f32 v[136:137], v[136:137], s[18:19], v[8:9] op_sel_hi:[1,0,1]
	v_pk_fma_f32 v[134:135], v[134:135], s[18:19], v[6:7] op_sel_hi:[1,0,1]
	v_mul_f32_e32 v142, 0xbfb8aa3b, v142
	v_mul_f32_e32 v143, 0xbfb8aa3b, v143
	v_mul_f32_e32 v134, 0xbfb8aa3b, v134
	v_mul_f32_e32 v135, 0xbfb8aa3b, v135
	v_mul_f32_e32 v136, 0xbfb8aa3b, v136
	v_mul_f32_e32 v137, 0xbfb8aa3b, v137
	v_pk_fma_f32 v[144:145], v[144:145], s[18:19], v[188:189] op_sel_hi:[1,0,1]
	v_exp_f32_e32 v142, v142
	v_exp_f32_e32 v143, v143
	v_exp_f32_e32 v134, v134
	v_exp_f32_e32 v135, v135
	v_exp_f32_e32 v136, v136
	v_exp_f32_e32 v137, v137
	v_mul_f32_e32 v144, 0xbfb8aa3b, v144
	v_mul_f32_e32 v145, 0xbfb8aa3b, v145
	v_pk_fma_f32 v[140:141], v[140:141], s[18:19], v[192:193] op_sel_hi:[1,0,1]
	v_pk_fma_f32 v[138:139], v[138:139], s[18:19], v[190:191] op_sel_hi:[1,0,1]
	v_pk_fma_f32 v[132:133], v[132:133], s[18:19], v[4:5] op_sel_hi:[1,0,1]
	v_pk_fma_f32 v[130:131], v[130:131], s[18:19], v[2:3] op_sel_hi:[1,0,1]
	v_exp_f32_e32 v144, v144
	v_exp_f32_e32 v145, v145
	v_mul_f32_e32 v138, 0xbfb8aa3b, v138
	v_mul_f32_e32 v139, 0xbfb8aa3b, v139
	v_mul_f32_e32 v140, 0xbfb8aa3b, v140
	v_mul_f32_e32 v141, 0xbfb8aa3b, v141
	v_mul_f32_e32 v130, 0xbfb8aa3b, v130
	v_mul_f32_e32 v132, 0xbfb8aa3b, v132
	v_mul_f32_e32 v133, 0xbfb8aa3b, v133
	v_exp_f32_e32 v138, v138
	v_exp_f32_e32 v139, v139
	v_exp_f32_e32 v140, v140
	v_exp_f32_e32 v141, v141
	v_exp_f32_e32 v130, v130
	v_exp_f32_e32 v163, v132
	v_exp_f32_e32 v133, v133
	v_add_f32_e32 v132, 1.0, v142
	v_add_f32_e32 v142, 1.0, v143
	v_add_f32_e32 v134, 1.0, v134
	v_add_f32_e32 v135, 1.0, v135
	v_add_f32_e32 v136, 1.0, v136
	v_add_f32_e32 v137, 1.0, v137
	v_rcp_f32_e32 v132, v132
	v_rcp_f32_e32 v142, v142
	v_rcp_f32_e32 v134, v134
	v_rcp_f32_e32 v135, v135
	v_rcp_f32_e32 v136, v136
	v_rcp_f32_e32 v137, v137
	v_mul_f32_e32 v131, 0xbfb8aa3b, v131
	v_add_f32_e32 v143, 1.0, v144
	v_add_f32_e32 v144, 1.0, v145
	v_exp_f32_e32 v131, v131
	v_rcp_f32_e32 v143, v143
	v_rcp_f32_e32 v144, v144
	v_add_f32_e32 v138, 1.0, v138
	v_add_f32_e32 v139, 1.0, v139
	v_add_f32_e32 v140, 1.0, v140
	v_add_f32_e32 v141, 1.0, v141
	v_add_f32_e32 v130, 1.0, v130
	v_rcp_f32_e32 v138, v138
	v_rcp_f32_e32 v139, v139
	v_rcp_f32_e32 v140, v140
	v_rcp_f32_e32 v141, v141
	v_add_f32_e32 v133, 1.0, v133
	v_pk_fma_f32 v[126:127], v[126:127], s[18:19], v[186:187] op_sel_hi:[1,0,1]
	v_pk_fma_f32 v[6:7], v[118:119], s[18:19], v[6:7] op_sel_hi:[1,0,1]
	v_rcp_f32_e32 v185, v130
	v_cvt_pk_bf16_f32 v130, v132, v142
	v_cvt_pk_bf16_f32 v132, v134, v135
	v_rcp_f32_e32 v134, v133
	v_cvt_pk_bf16_f32 v133, v136, v137
	v_mul_f32_e32 v126, 0xbfb8aa3b, v126
	v_mul_f32_e32 v6, 0xbfb8aa3b, v6
	v_mov_b32_e32 v200, v132
	v_mov_b32_e32 v201, v133
	v_exp_f32_e32 v132, v126
	v_mul_f32_e32 v126, 0xbfb8aa3b, v127
	v_exp_f32_e32 v118, v6
	v_mul_f32_e32 v6, 0xbfb8aa3b, v7
	v_add_f32_e32 v145, 1.0, v131
	v_cvt_pk_bf16_f32 v131, v143, v144
	v_exp_f32_e32 v133, v126
	v_exp_f32_e32 v119, v6
	v_mov_b32_e32 v204, v130
	v_mov_b32_e32 v205, v131
	v_cvt_pk_bf16_f32 v130, v138, v139
	v_cvt_pk_bf16_f32 v131, v140, v141
	v_pk_fma_f32 v[126:127], v[128:129], s[18:19], v[188:189] op_sel_hi:[1,0,1]
	v_mov_b32_e32 v206, v130
	v_mov_b32_e32 v207, v131
	v_lshl_add_u64 v[198:199], v[164:165], 0, v[196:197]
	s_nop 0
	v_permlane16_swap_b32 v204, v206
	v_permlane16_swap_b32 v205, v207
	global_store_dwordx4 v[198:199], v[204:207], off
	v_add_f32_e32 v131, 1.0, v163
	v_mul_f32_e32 v126, 0xbfb8aa3b, v126
	v_rcp_f32_e32 v130, v145
	v_rcp_f32_e32 v131, v131
	v_exp_f32_e32 v126, v126
	v_mul_f32_e32 v127, 0xbfb8aa3b, v127
	v_add_f32_e32 v128, 1.0, v132
	v_add_f32_e32 v129, 1.0, v133
	v_exp_f32_e32 v127, v127
	v_pk_fma_f32 v[6:7], v[120:121], s[18:19], v[8:9] op_sel_hi:[1,0,1]
	v_add_f32_e32 v8, 1.0, v118
	v_add_f32_e32 v9, 1.0, v119
	v_rcp_f32_e32 v128, v128
	v_rcp_f32_e32 v129, v129
	v_rcp_f32_e32 v8, v8
	v_rcp_f32_e32 v9, v9
	v_cvt_pk_bf16_f32 v130, v185, v130
	v_cvt_pk_bf16_f32 v131, v131, v134
	v_add_f32_e32 v126, 1.0, v126
	v_pk_fma_f32 v[122:123], v[122:123], s[18:19], v[190:191] op_sel_hi:[1,0,1]
	v_mul_f32_e32 v6, 0xbfb8aa3b, v6
	v_pk_fma_f32 v[2:3], v[114:115], s[18:19], v[2:3] op_sel_hi:[1,0,1]
	v_rcp_f32_e32 v132, v126
	v_add_f32_e32 v126, 1.0, v127
	v_mov_b32_e32 v202, v130
	v_mov_b32_e32 v203, v131
	v_lshl_add_u64 v[198:199], v[164:165], 0, v[196:197]
	s_nop 0
	v_permlane16_swap_b32 v200, v202
	v_permlane16_swap_b32 v201, v203
	global_store_dwordx4 v[198:199], v[200:203], off offset:256
	v_or_b32_e32 v130, 16, v162
	v_mul_f32_e32 v122, 0xbfb8aa3b, v122
	v_exp_f32_e32 v118, v6
	v_mul_f32_e32 v6, 0xbfb8aa3b, v7
	v_mul_f32_e32 v2, 0xbfb8aa3b, v2
	v_rcp_f32_e32 v127, v126
	v_cvt_pk_bf16_f32 v126, v128, v129
	v_mad_i64_i32 v[128:129], s[30:31], v130, s67, v[12:13]
	v_exp_f32_e32 v130, v122
	v_mul_f32_e32 v122, 0xbfb8aa3b, v123
	v_exp_f32_e32 v7, v6
	v_cvt_pk_bf16_f32 v6, v8, v9
	v_exp_f32_e32 v9, v2
	v_mul_f32_e32 v2, 0xbfb8aa3b, v3
	v_exp_f32_e32 v131, v122
	v_pk_fma_f32 v[122:123], v[124:125], s[18:19], v[192:193] op_sel_hi:[1,0,1]
	v_exp_f32_e32 v114, v2
	v_pk_fma_f32 v[2:3], v[116:117], s[18:19], v[4:5] op_sel_hi:[1,0,1]
	v_mul_f32_e32 v122, 0xbfb8aa3b, v122
	v_mul_f32_e32 v2, 0xbfb8aa3b, v2
	v_exp_f32_e32 v122, v122
	v_mul_f32_e32 v123, 0xbfb8aa3b, v123
	v_exp_f32_e32 v2, v2
	v_mul_f32_e32 v3, 0xbfb8aa3b, v3
	v_exp_f32_e32 v123, v123
	v_exp_f32_e32 v3, v3
	v_add_f32_e32 v122, 1.0, v122
	v_add_f32_e32 v2, 1.0, v2
	v_add_f32_e32 v124, 1.0, v130
	v_add_f32_e32 v125, 1.0, v131
	v_rcp_f32_e32 v130, v122
	v_add_f32_e32 v122, 1.0, v123
	v_add_f32_e32 v8, 1.0, v118
	v_add_f32_e32 v7, 1.0, v7
	v_add_f32_e32 v4, 1.0, v9
	v_add_f32_e32 v5, 1.0, v114
	v_rcp_f32_e32 v9, v2
	v_add_f32_e32 v2, 1.0, v3
	v_rcp_f32_e32 v124, v124
	v_rcp_f32_e32 v125, v125
	v_rcp_f32_e32 v131, v122
	v_rcp_f32_e32 v8, v8
	v_rcp_f32_e32 v7, v7
	v_rcp_f32_e32 v4, v4
	v_rcp_f32_e32 v5, v5
	v_rcp_f32_e32 v3, v2
	v_cvt_pk_bf16_f32 v127, v132, v127
	v_lshl_add_u64 v[122:123], v[128:129], 0, v[10:11]
	v_cvt_pk_bf16_f32 v124, v124, v125
	v_cvt_pk_bf16_f32 v125, v130, v131
	v_cvt_pk_bf16_f32 v7, v8, v7
	v_cvt_pk_bf16_f32 v2, v4, v5
	v_cvt_pk_bf16_f32 v3, v9, v3
	v_mov_b32_e32 v208, v126
	v_mov_b32_e32 v209, v127
	v_mov_b32_e32 v210, v124
	v_mov_b32_e32 v211, v125
	v_lshl_add_u64 v[198:199], v[122:123], 0, v[196:197]
	s_nop 0
	v_permlane16_swap_b32 v208, v210
	v_permlane16_swap_b32 v209, v211
	global_store_dwordx4 v[198:199], v[208:211], off
	v_mov_b32_e32 v212, v6
	v_mov_b32_e32 v213, v7
	v_mov_b32_e32 v214, v2
	v_mov_b32_e32 v215, v3
	v_lshl_add_u64 v[198:199], v[122:123], 0, v[196:197]
	s_nop 0
	v_permlane16_swap_b32 v212, v214
	v_permlane16_swap_b32 v213, v215
	global_store_dwordx4 v[198:199], v[212:215], off offset:256
	global_load_dwordx4 v[6:9], v[16:17], off
	s_nop 0
	global_load_dwordx4 v[114:117], v[158:159], off
	global_load_dwordx4 v[118:121], v[14:15], off
	global_load_dwordx4 v[2:5], v[160:161], off
	s_waitcnt vmcnt(0)
	v_pk_fma_f32 v[110:111], v[110:111], s[18:19], v[6:7] op_sel_hi:[1,0,1]
	s_nop 0
	v_mul_f32_e32 v110, 0xbfb8aa3b, v110
	v_exp_f32_e32 v122, v110
	v_mul_f32_e32 v110, 0xbfb8aa3b, v111
	v_exp_f32_e32 v123, v110
	v_pk_fma_f32 v[110:111], v[112:113], s[18:19], v[8:9] op_sel_hi:[1,0,1]
	v_pk_fma_f32 v[6:7], v[94:95], s[18:19], v[6:7] op_sel_hi:[1,0,1]
	v_mul_f32_e32 v110, 0xbfb8aa3b, v110
	v_exp_f32_e32 v110, v110
	v_mul_f32_e32 v111, 0xbfb8aa3b, v111
	v_exp_f32_e32 v111, v111
	v_mul_f32_e32 v6, 0xbfb8aa3b, v6
	v_add_f32_e32 v110, 1.0, v110
	v_exp_f32_e32 v94, v6
	v_mul_f32_e32 v6, 0xbfb8aa3b, v7
	v_add_f32_e32 v112, 1.0, v122
	v_rcp_f32_e32 v122, v110
	v_add_f32_e32 v110, 1.0, v111
	v_exp_f32_e32 v95, v6
	v_pk_fma_f32 v[6:7], v[96:97], s[18:19], v[8:9] op_sel_hi:[1,0,1]
	v_add_f32_e32 v113, 1.0, v123
	v_rcp_f32_e32 v111, v110
	v_mul_f32_e32 v6, 0xbfb8aa3b, v6
	v_rcp_f32_e32 v112, v112
	v_rcp_f32_e32 v113, v113
	v_exp_f32_e32 v6, v6
	v_mul_f32_e32 v7, 0xbfb8aa3b, v7
	v_pk_fma_f32 v[106:107], v[106:107], s[18:19], v[114:115] op_sel_hi:[1,0,1]
	v_exp_f32_e32 v7, v7
	v_mul_f32_e32 v106, 0xbfb8aa3b, v106
	v_or_b32_e32 v123, 32, v162
	v_cvt_pk_bf16_f32 v111, v122, v111
	v_exp_f32_e32 v122, v106
	v_mul_f32_e32 v106, 0xbfb8aa3b, v107
	v_cvt_pk_bf16_f32 v110, v112, v113
	v_mad_i64_i32 v[112:113], s[30:31], v123, s67, v[12:13]
	v_exp_f32_e32 v123, v106
	v_pk_fma_f32 v[106:107], v[108:109], s[18:19], v[116:117] op_sel_hi:[1,0,1]
	v_add_f32_e32 v6, 1.0, v6
	v_mul_f32_e32 v106, 0xbfb8aa3b, v106
	v_add_f32_e32 v8, 1.0, v94
	v_rcp_f32_e32 v94, v6
	v_add_f32_e32 v6, 1.0, v7
	v_exp_f32_e32 v106, v106
	v_mul_f32_e32 v107, 0xbfb8aa3b, v107
	v_add_f32_e32 v9, 1.0, v95
	v_rcp_f32_e32 v7, v6
	v_exp_f32_e32 v107, v107
	v_rcp_f32_e32 v8, v8
	v_rcp_f32_e32 v9, v9
	v_pk_fma_f32 v[90:91], v[90:91], s[18:19], v[114:115] op_sel_hi:[1,0,1]
	v_add_f32_e32 v106, 1.0, v106
	v_mul_f32_e32 v90, 0xbfb8aa3b, v90
	v_or_b32_e32 v95, 48, v162
	v_cvt_pk_bf16_f32 v7, v94, v7
	v_exp_f32_e32 v94, v90
	v_mul_f32_e32 v90, 0xbfb8aa3b, v91
	v_add_f32_e32 v108, 1.0, v122
	v_add_f32_e32 v109, 1.0, v123
	v_rcp_f32_e32 v122, v106
	v_add_f32_e32 v106, 1.0, v107
	v_cvt_pk_bf16_f32 v6, v8, v9
	v_mad_i64_i32 v[8:9], s[30:31], v95, s67, v[12:13]
	v_exp_f32_e32 v95, v90
	v_pk_fma_f32 v[90:91], v[92:93], s[18:19], v[116:117] op_sel_hi:[1,0,1]
	v_rcp_f32_e32 v108, v108
	v_rcp_f32_e32 v109, v109
	v_rcp_f32_e32 v123, v106
	v_mul_f32_e32 v90, 0xbfb8aa3b, v90
	v_mul_f32_e32 v91, 0xbfb8aa3b, v91
	v_exp_f32_e32 v90, v90
	v_exp_f32_e32 v91, v91
	v_pk_fma_f32 v[102:103], v[102:103], s[18:19], v[118:119] op_sel_hi:[1,0,1]
	v_lshl_add_u64 v[106:107], v[112:113], 0, v[10:11]
	v_cvt_pk_bf16_f32 v108, v108, v109
	v_cvt_pk_bf16_f32 v109, v122, v123
	v_mul_f32_e32 v102, 0xbfb8aa3b, v102
	v_mov_b32_e32 v222, v108
	v_mov_b32_e32 v223, v109
	v_exp_f32_e32 v108, v102
	v_mul_f32_e32 v102, 0xbfb8aa3b, v103
	v_add_f32_e32 v92, 1.0, v94
	v_add_f32_e32 v93, 1.0, v95
	v_add_f32_e32 v90, 1.0, v90
	v_add_f32_e32 v91, 1.0, v91
	v_exp_f32_e32 v109, v102
	v_rcp_f32_e32 v92, v92
	v_rcp_f32_e32 v93, v93
	v_rcp_f32_e32 v90, v90
	v_rcp_f32_e32 v91, v91
	v_lshl_add_u64 v[8:9], v[8:9], 0, v[10:11]
	v_pk_fma_f32 v[102:103], v[104:105], s[18:19], v[120:121] op_sel_hi:[1,0,1]
	v_add_f32_e32 v104, 1.0, v108
	v_add_f32_e32 v105, 1.0, v109
	v_mov_b32_e32 v224, v6
	v_mov_b32_e32 v225, v7
	v_cvt_pk_bf16_f32 v6, v92, v93
	v_cvt_pk_bf16_f32 v7, v90, v91
	v_rcp_f32_e32 v104, v104
	v_rcp_f32_e32 v105, v105
	v_mul_f32_e32 v102, 0xbfb8aa3b, v102
	v_mov_b32_e32 v226, v6
	v_mov_b32_e32 v227, v7
	v_lshl_add_u64 v[198:199], v[8:9], 0, v[196:197]
	s_nop 0
	v_permlane16_swap_b32 v224, v226
	v_permlane16_swap_b32 v225, v227
	global_store_dwordx4 v[198:199], v[224:227], off
	v_pk_fma_f32 v[6:7], v[86:87], s[18:19], v[118:119] op_sel_hi:[1,0,1]
	v_exp_f32_e32 v108, v102
	v_mul_f32_e32 v6, 0xbfb8aa3b, v6
	v_pk_fma_f32 v[98:99], v[98:99], s[18:19], v[2:3] op_sel_hi:[1,0,1]
	v_exp_f32_e32 v86, v6
	v_mul_f32_e32 v6, 0xbfb8aa3b, v7
	v_pk_fma_f32 v[2:3], v[82:83], s[18:19], v[2:3] op_sel_hi:[1,0,1]
	v_mul_f32_e32 v102, 0xbfb8aa3b, v103
	v_mul_f32_e32 v98, 0xbfb8aa3b, v98
	v_exp_f32_e32 v87, v6
	v_mul_f32_e32 v2, 0xbfb8aa3b, v2
	v_exp_f32_e32 v103, v102
	v_cvt_pk_bf16_f32 v102, v104, v105
	v_exp_f32_e32 v105, v98
	v_mul_f32_e32 v98, 0xbfb8aa3b, v99
	v_exp_f32_e32 v82, v2
	v_mul_f32_e32 v2, 0xbfb8aa3b, v3
	v_add_f32_e32 v104, 1.0, v108
	v_exp_f32_e32 v108, v98
	v_pk_fma_f32 v[98:99], v[100:101], s[18:19], v[4:5] op_sel_hi:[1,0,1]
	v_pk_fma_f32 v[6:7], v[88:89], s[18:19], v[120:121] op_sel_hi:[1,0,1]
	v_exp_f32_e32 v83, v2
	v_pk_fma_f32 v[2:3], v[84:85], s[18:19], v[4:5] op_sel_hi:[1,0,1]
	v_mul_f32_e32 v98, 0xbfb8aa3b, v98
	v_mul_f32_e32 v6, 0xbfb8aa3b, v6
	v_mul_f32_e32 v2, 0xbfb8aa3b, v2
	v_exp_f32_e32 v98, v98
	v_mul_f32_e32 v99, 0xbfb8aa3b, v99
	v_add_f32_e32 v86, 1.0, v86
	v_add_f32_e32 v87, 1.0, v87
	v_exp_f32_e32 v88, v6
	v_mul_f32_e32 v6, 0xbfb8aa3b, v7
	v_exp_f32_e32 v2, v2
	v_mul_f32_e32 v3, 0xbfb8aa3b, v3
	v_exp_f32_e32 v99, v99
	v_rcp_f32_e32 v86, v86
	v_rcp_f32_e32 v87, v87
	v_exp_f32_e32 v7, v6
	v_exp_f32_e32 v3, v3
	v_add_f32_e32 v98, 1.0, v98
	v_add_f32_e32 v2, 1.0, v2
	v_add_f32_e32 v103, 1.0, v103
	v_add_f32_e32 v100, 1.0, v105
	v_add_f32_e32 v101, 1.0, v108
	v_rcp_f32_e32 v105, v98
	v_add_f32_e32 v98, 1.0, v99
	v_cvt_pk_bf16_f32 v6, v86, v87
	v_add_f32_e32 v86, 1.0, v88
	v_add_f32_e32 v7, 1.0, v7
	v_add_f32_e32 v4, 1.0, v82
	v_add_f32_e32 v5, 1.0, v83
	v_rcp_f32_e32 v82, v2
	v_add_f32_e32 v2, 1.0, v3
	v_rcp_f32_e32 v104, v104
	v_rcp_f32_e32 v103, v103
	v_rcp_f32_e32 v100, v100
	v_rcp_f32_e32 v101, v101
	v_rcp_f32_e32 v99, v98
	v_rcp_f32_e32 v86, v86
	v_rcp_f32_e32 v7, v7
	v_rcp_f32_e32 v4, v4
	v_rcp_f32_e32 v5, v5
	v_rcp_f32_e32 v3, v2
	v_cvt_pk_bf16_f32 v103, v104, v103
	v_cvt_pk_bf16_f32 v98, v100, v101
	v_cvt_pk_bf16_f32 v99, v105, v99
	v_cvt_pk_bf16_f32 v7, v86, v7
	v_cvt_pk_bf16_f32 v2, v4, v5
	v_cvt_pk_bf16_f32 v3, v82, v3
	v_mov_b32_e32 v220, v110
	v_mov_b32_e32 v221, v111
	v_lshl_add_u64 v[198:199], v[106:107], 0, v[196:197]
	s_nop 0
	v_permlane16_swap_b32 v220, v222
	v_permlane16_swap_b32 v221, v223
	global_store_dwordx4 v[198:199], v[220:223], off
	v_mov_b32_e32 v228, v102
	v_mov_b32_e32 v229, v103
	v_mov_b32_e32 v230, v98
	v_mov_b32_e32 v231, v99
	v_lshl_add_u64 v[198:199], v[106:107], 0, v[196:197]
	s_nop 0
	v_permlane16_swap_b32 v228, v230
	v_permlane16_swap_b32 v229, v231
	global_store_dwordx4 v[198:199], v[228:231], off offset:256
	v_mov_b32_e32 v232, v6
	v_mov_b32_e32 v233, v7
	v_mov_b32_e32 v234, v2
	v_mov_b32_e32 v235, v3
	v_lshl_add_u64 v[198:199], v[8:9], 0, v[196:197]
	s_nop 0
	v_permlane16_swap_b32 v232, v234
	v_permlane16_swap_b32 v233, v235
	global_store_dwordx4 v[198:199], v[232:235], off offset:256
	global_load_dwordx4 v[6:9], v[16:17], off
	s_nop 0
	global_load_dwordx4 v[82:85], v[158:159], off
	global_load_dwordx4 v[86:89], v[14:15], off
	global_load_dwordx4 v[2:5], v[160:161], off
	s_waitcnt vmcnt(0)
	v_pk_fma_f32 v[78:79], v[78:79], s[18:19], v[6:7] op_sel_hi:[1,0,1]
	s_nop 0
	v_mul_f32_e32 v78, 0xbfb8aa3b, v78
	v_exp_f32_e32 v90, v78
	v_mul_f32_e32 v78, 0xbfb8aa3b, v79
	v_exp_f32_e32 v91, v78
	v_pk_fma_f32 v[78:79], v[80:81], s[18:19], v[8:9] op_sel_hi:[1,0,1]
	v_pk_fma_f32 v[6:7], v[62:63], s[18:19], v[6:7] op_sel_hi:[1,0,1]
	v_mul_f32_e32 v78, 0xbfb8aa3b, v78
	v_exp_f32_e32 v78, v78
	v_mul_f32_e32 v79, 0xbfb8aa3b, v79
	v_exp_f32_e32 v79, v79
	v_mul_f32_e32 v6, 0xbfb8aa3b, v6
	v_add_f32_e32 v78, 1.0, v78
	v_exp_f32_e32 v62, v6
	v_mul_f32_e32 v6, 0xbfb8aa3b, v7
	v_add_f32_e32 v80, 1.0, v90
	v_rcp_f32_e32 v90, v78
	v_add_f32_e32 v78, 1.0, v79
	v_exp_f32_e32 v63, v6
	v_pk_fma_f32 v[6:7], v[64:65], s[18:19], v[8:9] op_sel_hi:[1,0,1]
	v_add_f32_e32 v81, 1.0, v91
	v_rcp_f32_e32 v79, v78
	v_mul_f32_e32 v6, 0xbfb8aa3b, v6
	v_rcp_f32_e32 v80, v80
	v_rcp_f32_e32 v81, v81
	v_exp_f32_e32 v6, v6
	v_mul_f32_e32 v7, 0xbfb8aa3b, v7
	v_pk_fma_f32 v[74:75], v[74:75], s[18:19], v[82:83] op_sel_hi:[1,0,1]
	v_exp_f32_e32 v7, v7
	v_mul_f32_e32 v74, 0xbfb8aa3b, v74
	v_add_u32_e32 v91, 0x80, v162
	v_cvt_pk_bf16_f32 v79, v90, v79
	v_exp_f32_e32 v90, v74
	v_mul_f32_e32 v74, 0xbfb8aa3b, v75
	v_cvt_pk_bf16_f32 v78, v80, v81
	v_mad_i64_i32 v[80:81], s[30:31], v91, s67, v[12:13]
	v_exp_f32_e32 v91, v74
	v_pk_fma_f32 v[74:75], v[76:77], s[18:19], v[84:85] op_sel_hi:[1,0,1]
	v_add_f32_e32 v6, 1.0, v6
	v_mul_f32_e32 v74, 0xbfb8aa3b, v74
	v_add_f32_e32 v8, 1.0, v62
	v_rcp_f32_e32 v62, v6
	v_add_f32_e32 v6, 1.0, v7
	v_exp_f32_e32 v74, v74
	v_mul_f32_e32 v75, 0xbfb8aa3b, v75
	v_add_f32_e32 v9, 1.0, v63
	v_rcp_f32_e32 v7, v6
	v_exp_f32_e32 v75, v75
	v_rcp_f32_e32 v8, v8
	v_rcp_f32_e32 v9, v9
	v_pk_fma_f32 v[58:59], v[58:59], s[18:19], v[82:83] op_sel_hi:[1,0,1]
	v_add_f32_e32 v74, 1.0, v74
	v_mul_f32_e32 v58, 0xbfb8aa3b, v58
	v_add_u32_e32 v63, 0x90, v162
	v_cvt_pk_bf16_f32 v7, v62, v7
	v_exp_f32_e32 v62, v58
	v_mul_f32_e32 v58, 0xbfb8aa3b, v59
	v_add_f32_e32 v76, 1.0, v90
	v_add_f32_e32 v77, 1.0, v91
	v_rcp_f32_e32 v90, v74
	v_add_f32_e32 v74, 1.0, v75
	v_cvt_pk_bf16_f32 v6, v8, v9
	v_mad_i64_i32 v[8:9], s[30:31], v63, s67, v[12:13]
	v_exp_f32_e32 v63, v58
	v_pk_fma_f32 v[58:59], v[60:61], s[18:19], v[84:85] op_sel_hi:[1,0,1]
	v_rcp_f32_e32 v76, v76
	v_rcp_f32_e32 v77, v77
	v_rcp_f32_e32 v91, v74
	v_mul_f32_e32 v58, 0xbfb8aa3b, v58
	v_mul_f32_e32 v59, 0xbfb8aa3b, v59
	v_exp_f32_e32 v58, v58
	v_exp_f32_e32 v59, v59
	v_pk_fma_f32 v[70:71], v[70:71], s[18:19], v[86:87] op_sel_hi:[1,0,1]
	v_lshl_add_u64 v[74:75], v[80:81], 0, v[10:11]
	v_cvt_pk_bf16_f32 v76, v76, v77
	v_cvt_pk_bf16_f32 v77, v90, v91
	v_mul_f32_e32 v70, 0xbfb8aa3b, v70
	v_mov_b32_e32 v238, v76
	v_mov_b32_e32 v239, v77
	v_exp_f32_e32 v76, v70
	v_mul_f32_e32 v70, 0xbfb8aa3b, v71
	v_add_f32_e32 v60, 1.0, v62
	v_add_f32_e32 v61, 1.0, v63
	v_add_f32_e32 v58, 1.0, v58
	v_add_f32_e32 v59, 1.0, v59
	v_exp_f32_e32 v77, v70
	v_rcp_f32_e32 v60, v60
	v_rcp_f32_e32 v61, v61
	v_rcp_f32_e32 v58, v58
	v_rcp_f32_e32 v59, v59
	v_lshl_add_u64 v[8:9], v[8:9], 0, v[10:11]
	v_pk_fma_f32 v[70:71], v[72:73], s[18:19], v[88:89] op_sel_hi:[1,0,1]
	v_add_f32_e32 v72, 1.0, v76
	v_add_f32_e32 v73, 1.0, v77
	v_mov_b32_e32 v240, v6
	v_mov_b32_e32 v241, v7
	v_cvt_pk_bf16_f32 v6, v60, v61
	v_cvt_pk_bf16_f32 v7, v58, v59
	v_rcp_f32_e32 v72, v72
	v_rcp_f32_e32 v73, v73
	v_mul_f32_e32 v70, 0xbfb8aa3b, v70
	v_mov_b32_e32 v242, v6
	v_mov_b32_e32 v243, v7
	v_lshl_add_u64 v[198:199], v[8:9], 0, v[196:197]
	s_nop 0
	v_permlane16_swap_b32 v240, v242
	v_permlane16_swap_b32 v241, v243
	global_store_dwordx4 v[198:199], v[240:243], off
	v_pk_fma_f32 v[6:7], v[54:55], s[18:19], v[86:87] op_sel_hi:[1,0,1]
	v_exp_f32_e32 v76, v70
	v_mul_f32_e32 v6, 0xbfb8aa3b, v6
	v_pk_fma_f32 v[66:67], v[66:67], s[18:19], v[2:3] op_sel_hi:[1,0,1]
	v_exp_f32_e32 v54, v6
	v_mul_f32_e32 v6, 0xbfb8aa3b, v7
	v_pk_fma_f32 v[2:3], v[50:51], s[18:19], v[2:3] op_sel_hi:[1,0,1]
	v_mul_f32_e32 v70, 0xbfb8aa3b, v71
	v_mul_f32_e32 v66, 0xbfb8aa3b, v66
	v_exp_f32_e32 v55, v6
	v_mul_f32_e32 v2, 0xbfb8aa3b, v2
	v_exp_f32_e32 v71, v70
	v_cvt_pk_bf16_f32 v70, v72, v73
	v_exp_f32_e32 v73, v66
	v_mul_f32_e32 v66, 0xbfb8aa3b, v67
	v_exp_f32_e32 v50, v2
	v_mul_f32_e32 v2, 0xbfb8aa3b, v3
	v_add_f32_e32 v72, 1.0, v76
	v_exp_f32_e32 v76, v66
	v_pk_fma_f32 v[66:67], v[68:69], s[18:19], v[4:5] op_sel_hi:[1,0,1]
	v_pk_fma_f32 v[6:7], v[56:57], s[18:19], v[88:89] op_sel_hi:[1,0,1]
	v_exp_f32_e32 v51, v2
	v_pk_fma_f32 v[2:3], v[52:53], s[18:19], v[4:5] op_sel_hi:[1,0,1]
	v_mul_f32_e32 v66, 0xbfb8aa3b, v66
	v_mul_f32_e32 v6, 0xbfb8aa3b, v6
	v_mul_f32_e32 v2, 0xbfb8aa3b, v2
	v_exp_f32_e32 v66, v66
	v_mul_f32_e32 v67, 0xbfb8aa3b, v67
	v_add_f32_e32 v54, 1.0, v54
	v_add_f32_e32 v55, 1.0, v55
	v_exp_f32_e32 v56, v6
	v_mul_f32_e32 v6, 0xbfb8aa3b, v7
	v_exp_f32_e32 v2, v2
	v_mul_f32_e32 v3, 0xbfb8aa3b, v3
	v_exp_f32_e32 v67, v67
	v_rcp_f32_e32 v54, v54
	v_rcp_f32_e32 v55, v55
	v_exp_f32_e32 v7, v6
	v_exp_f32_e32 v3, v3
	v_add_f32_e32 v66, 1.0, v66
	v_add_f32_e32 v2, 1.0, v2
	v_add_f32_e32 v71, 1.0, v71
	v_add_f32_e32 v68, 1.0, v73
	v_add_f32_e32 v69, 1.0, v76
	v_rcp_f32_e32 v73, v66
	v_add_f32_e32 v66, 1.0, v67
	v_cvt_pk_bf16_f32 v6, v54, v55
	v_add_f32_e32 v54, 1.0, v56
	v_add_f32_e32 v7, 1.0, v7
	v_add_f32_e32 v4, 1.0, v50
	v_add_f32_e32 v5, 1.0, v51
	v_rcp_f32_e32 v50, v2
	v_add_f32_e32 v2, 1.0, v3
	v_rcp_f32_e32 v72, v72
	v_rcp_f32_e32 v71, v71
	v_rcp_f32_e32 v68, v68
	v_rcp_f32_e32 v69, v69
	v_rcp_f32_e32 v67, v66
	v_rcp_f32_e32 v54, v54
	v_rcp_f32_e32 v7, v7
	v_rcp_f32_e32 v4, v4
	v_rcp_f32_e32 v5, v5
	v_rcp_f32_e32 v3, v2
	v_cvt_pk_bf16_f32 v71, v72, v71
	v_cvt_pk_bf16_f32 v66, v68, v69
	v_cvt_pk_bf16_f32 v67, v73, v67
	v_cvt_pk_bf16_f32 v7, v54, v7
	v_cvt_pk_bf16_f32 v2, v4, v5
	v_cvt_pk_bf16_f32 v3, v50, v3
	v_mov_b32_e32 v236, v78
	v_mov_b32_e32 v237, v79
	v_lshl_add_u64 v[198:199], v[74:75], 0, v[196:197]
	s_nop 0
	v_permlane16_swap_b32 v236, v238
	v_permlane16_swap_b32 v237, v239
	global_store_dwordx4 v[198:199], v[236:239], off
	v_mov_b32_e32 v244, v70
	v_mov_b32_e32 v245, v71
	v_mov_b32_e32 v246, v66
	v_mov_b32_e32 v247, v67
	v_lshl_add_u64 v[198:199], v[74:75], 0, v[196:197]
	s_nop 0
	v_permlane16_swap_b32 v244, v246
	v_permlane16_swap_b32 v245, v247
	global_store_dwordx4 v[198:199], v[244:247], off offset:256
	v_mov_b32_e32 v200, v6
	v_mov_b32_e32 v201, v7
	v_mov_b32_e32 v202, v2
	v_mov_b32_e32 v203, v3
	v_lshl_add_u64 v[198:199], v[8:9], 0, v[196:197]
	s_nop 0
	v_permlane16_swap_b32 v200, v202
	v_permlane16_swap_b32 v201, v203
	global_store_dwordx4 v[198:199], v[200:203], off offset:256
	global_load_dwordx4 v[6:9], v[16:17], off
	s_nop 0
	global_load_dwordx4 v[50:53], v[158:159], off
	s_nop 0
	global_load_dwordx4 v[14:17], v[14:15], off
	s_nop 0
	global_load_dwordx4 v[2:5], v[160:161], off
	s_waitcnt vmcnt(0)
	v_pk_fma_f32 v[46:47], v[46:47], s[18:19], v[6:7] op_sel_hi:[1,0,1]
	v_pk_fma_f32 v[6:7], v[30:31], s[18:19], v[6:7] op_sel_hi:[1,0,1]
	v_mul_f32_e32 v46, 0xbfb8aa3b, v46
	v_mul_f32_e32 v6, 0xbfb8aa3b, v6
	v_exp_f32_e32 v54, v46
	v_mul_f32_e32 v46, 0xbfb8aa3b, v47
	v_exp_f32_e32 v30, v6
	v_mul_f32_e32 v6, 0xbfb8aa3b, v7
	v_exp_f32_e32 v55, v46
	v_pk_fma_f32 v[46:47], v[48:49], s[18:19], v[8:9] op_sel_hi:[1,0,1]
	v_exp_f32_e32 v31, v6
	v_mul_f32_e32 v46, 0xbfb8aa3b, v46
	v_pk_fma_f32 v[6:7], v[32:33], s[18:19], v[8:9] op_sel_hi:[1,0,1]
	v_exp_f32_e32 v46, v46
	v_mul_f32_e32 v47, 0xbfb8aa3b, v47
	v_mul_f32_e32 v6, 0xbfb8aa3b, v6
	v_exp_f32_e32 v47, v47
	v_exp_f32_e32 v6, v6
	v_mul_f32_e32 v7, 0xbfb8aa3b, v7
	v_add_f32_e32 v48, 1.0, v54
	v_add_f32_e32 v49, 1.0, v55
	v_add_f32_e32 v8, 1.0, v30
	v_add_f32_e32 v9, 1.0, v31
	v_exp_f32_e32 v7, v7
	v_rcp_f32_e32 v48, v48
	v_rcp_f32_e32 v49, v49
	v_rcp_f32_e32 v8, v8
	v_rcp_f32_e32 v9, v9
	v_add_f32_e32 v46, 1.0, v46
	v_rcp_f32_e32 v54, v46
	v_add_f32_e32 v46, 1.0, v47
	v_add_f32_e32 v6, 1.0, v6
	v_rcp_f32_e32 v47, v46
	v_add_u32_e32 v55, 0xa0, v162
	v_rcp_f32_e32 v30, v6
	v_add_f32_e32 v6, 1.0, v7
	v_add_u32_e32 v31, 0xb0, v162
	v_cvt_pk_bf16_f32 v46, v48, v49
	v_mad_i64_i32 v[48:49], s[30:31], v55, s67, v[12:13]
	v_rcp_f32_e32 v7, v6
	v_cvt_pk_bf16_f32 v6, v8, v9
	v_mad_i64_i32 v[8:9], s[30:31], v31, s67, v[12:13]
	v_pk_fma_f32 v[12:13], v[26:27], s[18:19], v[50:51] op_sel_hi:[1,0,1]
	v_pk_fma_f32 v[42:43], v[42:43], s[18:19], v[50:51] op_sel_hi:[1,0,1]
	v_mul_f32_e32 v12, 0xbfb8aa3b, v12
	v_mul_f32_e32 v42, 0xbfb8aa3b, v42
	v_exp_f32_e32 v26, v12
	v_mul_f32_e32 v12, 0xbfb8aa3b, v13
	v_cvt_pk_bf16_f32 v47, v54, v47
	v_exp_f32_e32 v54, v42
	v_mul_f32_e32 v42, 0xbfb8aa3b, v43
	v_exp_f32_e32 v27, v12
	v_pk_fma_f32 v[12:13], v[28:29], s[18:19], v[52:53] op_sel_hi:[1,0,1]
	v_exp_f32_e32 v55, v42
	v_pk_fma_f32 v[42:43], v[44:45], s[18:19], v[52:53] op_sel_hi:[1,0,1]
	v_mul_f32_e32 v12, 0xbfb8aa3b, v12
	v_mul_f32_e32 v13, 0xbfb8aa3b, v13
	v_mul_f32_e32 v42, 0xbfb8aa3b, v42
	v_exp_f32_e32 v12, v12
	v_exp_f32_e32 v13, v13
	v_exp_f32_e32 v42, v42
	v_mul_f32_e32 v43, 0xbfb8aa3b, v43
	v_exp_f32_e32 v43, v43
	v_add_f32_e32 v26, 1.0, v26
	v_add_f32_e32 v27, 1.0, v27
	v_add_f32_e32 v12, 1.0, v12
	v_add_f32_e32 v13, 1.0, v13
	v_add_f32_e32 v42, 1.0, v42
	v_rcp_f32_e32 v26, v26
	v_rcp_f32_e32 v27, v27
	v_rcp_f32_e32 v12, v12
	v_rcp_f32_e32 v13, v13
	v_add_f32_e32 v44, 1.0, v54
	v_add_f32_e32 v45, 1.0, v55
	v_rcp_f32_e32 v54, v42
	v_add_f32_e32 v42, 1.0, v43
	v_rcp_f32_e32 v44, v44
	v_rcp_f32_e32 v45, v45
	v_rcp_f32_e32 v55, v42
	v_cvt_pk_bf16_f32 v7, v30, v7
	v_lshl_add_u64 v[8:9], v[8:9], 0, v[10:11]
	v_mov_b32_e32 v204, v6
	v_mov_b32_e32 v205, v7
	v_cvt_pk_bf16_f32 v6, v26, v27
	v_cvt_pk_bf16_f32 v7, v12, v13
	v_pk_fma_f32 v[38:39], v[38:39], s[18:19], v[14:15] op_sel_hi:[1,0,1]
	v_mov_b32_e32 v206, v6
	v_mov_b32_e32 v207, v7
	v_lshl_add_u64 v[198:199], v[8:9], 0, v[196:197]
	s_nop 0
	v_permlane16_swap_b32 v204, v206
	v_permlane16_swap_b32 v205, v207
	global_store_dwordx4 v[198:199], v[204:207], off
	v_pk_fma_f32 v[6:7], v[22:23], s[18:19], v[14:15] op_sel_hi:[1,0,1]
	v_lshl_add_u64 v[42:43], v[48:49], 0, v[10:11]
	v_cvt_pk_bf16_f32 v44, v44, v45
	v_cvt_pk_bf16_f32 v45, v54, v55
	v_mul_f32_e32 v38, 0xbfb8aa3b, v38
	v_mul_f32_e32 v6, 0xbfb8aa3b, v6
	v_mov_b32_e32 v210, v44
	v_mov_b32_e32 v211, v45
	v_exp_f32_e32 v44, v38
	v_mul_f32_e32 v38, 0xbfb8aa3b, v39
	v_exp_f32_e32 v10, v6
	v_mul_f32_e32 v6, 0xbfb8aa3b, v7
	v_exp_f32_e32 v45, v38
	v_exp_f32_e32 v11, v6
	v_pk_fma_f32 v[38:39], v[40:41], s[18:19], v[16:17] op_sel_hi:[1,0,1]
	v_add_f32_e32 v40, 1.0, v44
	v_add_f32_e32 v41, 1.0, v45
	v_pk_fma_f32 v[6:7], v[24:25], s[18:19], v[16:17] op_sel_hi:[1,0,1]
	v_add_f32_e32 v10, 1.0, v10
	v_add_f32_e32 v11, 1.0, v11
	v_rcp_f32_e32 v40, v40
	v_rcp_f32_e32 v41, v41
	v_mul_f32_e32 v38, 0xbfb8aa3b, v38
	v_rcp_f32_e32 v10, v10
	v_rcp_f32_e32 v11, v11
	v_mul_f32_e32 v6, 0xbfb8aa3b, v6
	v_exp_f32_e32 v44, v38
	v_exp_f32_e32 v12, v6
	v_pk_fma_f32 v[34:35], v[34:35], s[18:19], v[2:3] op_sel_hi:[1,0,1]
	v_pk_fma_f32 v[2:3], v[18:19], s[18:19], v[2:3] op_sel_hi:[1,0,1]
	v_mul_f32_e32 v38, 0xbfb8aa3b, v39
	v_mul_f32_e32 v34, 0xbfb8aa3b, v34
	v_mul_f32_e32 v6, 0xbfb8aa3b, v7
	v_mul_f32_e32 v2, 0xbfb8aa3b, v2
	v_exp_f32_e32 v39, v38
	v_cvt_pk_bf16_f32 v38, v40, v41
	v_exp_f32_e32 v41, v34
	v_mul_f32_e32 v34, 0xbfb8aa3b, v35
	v_exp_f32_e32 v7, v6
	v_cvt_pk_bf16_f32 v6, v10, v11
	v_exp_f32_e32 v11, v2
	v_mul_f32_e32 v2, 0xbfb8aa3b, v3
	v_add_f32_e32 v40, 1.0, v44
	v_exp_f32_e32 v44, v34
	v_pk_fma_f32 v[34:35], v[36:37], s[18:19], v[4:5] op_sel_hi:[1,0,1]
	v_add_f32_e32 v10, 1.0, v12
	v_exp_f32_e32 v12, v2
	v_pk_fma_f32 v[2:3], v[20:21], s[18:19], v[4:5] op_sel_hi:[1,0,1]
	v_mul_f32_e32 v34, 0xbfb8aa3b, v34
	v_mul_f32_e32 v2, 0xbfb8aa3b, v2
	v_exp_f32_e32 v34, v34
	v_mul_f32_e32 v35, 0xbfb8aa3b, v35
	v_exp_f32_e32 v2, v2
	v_mul_f32_e32 v3, 0xbfb8aa3b, v3
	v_exp_f32_e32 v35, v35
	v_exp_f32_e32 v3, v3
	v_add_f32_e32 v34, 1.0, v34
	v_add_f32_e32 v2, 1.0, v2
	v_add_f32_e32 v39, 1.0, v39
	v_add_f32_e32 v36, 1.0, v41
	v_add_f32_e32 v37, 1.0, v44
	v_rcp_f32_e32 v41, v34
	v_add_f32_e32 v34, 1.0, v35
	v_add_f32_e32 v7, 1.0, v7
	v_add_f32_e32 v4, 1.0, v11
	v_add_f32_e32 v5, 1.0, v12
	v_rcp_f32_e32 v11, v2
	v_add_f32_e32 v2, 1.0, v3
	v_rcp_f32_e32 v40, v40
	v_rcp_f32_e32 v39, v39
	v_rcp_f32_e32 v36, v36
	v_rcp_f32_e32 v37, v37
	v_rcp_f32_e32 v35, v34
	v_rcp_f32_e32 v10, v10
	v_rcp_f32_e32 v7, v7
	v_rcp_f32_e32 v4, v4
	v_rcp_f32_e32 v5, v5
	v_rcp_f32_e32 v3, v2
	v_cvt_pk_bf16_f32 v39, v40, v39
	v_cvt_pk_bf16_f32 v34, v36, v37
	v_cvt_pk_bf16_f32 v35, v41, v35
	v_cvt_pk_bf16_f32 v7, v10, v7
	v_cvt_pk_bf16_f32 v2, v4, v5
	v_cvt_pk_bf16_f32 v3, v11, v3
	s_mov_b64 s[30:31], s[26:27]
	v_mov_b32_e32 v208, v46
	v_mov_b32_e32 v209, v47
	v_lshl_add_u64 v[198:199], v[42:43], 0, v[196:197]
	s_nop 0
	v_permlane16_swap_b32 v208, v210
	v_permlane16_swap_b32 v209, v211
	global_store_dwordx4 v[198:199], v[208:211], off
	v_mov_b32_e32 v212, v38
	v_mov_b32_e32 v213, v39
	v_mov_b32_e32 v214, v34
	v_mov_b32_e32 v215, v35
	v_lshl_add_u64 v[198:199], v[42:43], 0, v[196:197]
	s_nop 0
	v_permlane16_swap_b32 v212, v214
	v_permlane16_swap_b32 v213, v215
	global_store_dwordx4 v[198:199], v[212:215], off offset:256
	v_mov_b32_e32 v220, v6
	v_mov_b32_e32 v221, v7
	v_mov_b32_e32 v222, v2
	v_mov_b32_e32 v223, v3
	v_lshl_add_u64 v[198:199], v[8:9], 0, v[196:197]
	s_nop 0
	v_permlane16_swap_b32 v220, v222
	v_permlane16_swap_b32 v221, v223
	global_store_dwordx4 v[198:199], v[220:223], off offset:256
	s_cbranch_vccz .LBB0_4315
	s_waitcnt vmcnt(0)
	s_cmpk_gt_u32 s3, 0xff
	s_cbranch_scc1 .LBB0_4322
	s_barrier

.LBB0_5692:
	ds_read_b128 v[2:5], v167
	ds_read_b128 v[6:9], v171
	ds_read_b128 v[10:13], v172
	ds_read_b128 v[14:17], v173
	s_add_u32 s28, s26, 0x100
	s_addc_u32 s29, s27, 0
	s_cmp_eq_u32 s70, 18
	s_cselect_b32 s35, s9, s29
	s_cselect_b32 s34, s8, s28
	s_cselect_b32 s31, s11, s69
	s_cselect_b32 s30, s10, s68
	v_lshl_add_u64 v[158:159], s[26:27], 0, v[152:153]
	s_add_i32 m0, s41, 0xc000
	ds_read_b128 v[186:189], v184
	ds_read_b128 v[190:193], v184 offset:1024
	ds_read_b128 v[194:197], v184 offset:2048
	ds_read_b128 v[198:201], v184 offset:3072
	ds_read_b128 v[202:205], v184 offset:4096
	ds_read_b128 v[206:209], v184 offset:5120
	ds_read_b128 v[210:213], v184 offset:6144
	ds_read_b128 v[214:217], v184 offset:7168
	global_load_lds_dwordx4 v[158:159], off
	v_lshl_add_u64 v[158:159], s[26:27], 0, v[150:151]
	s_add_i32 m0, s41, 0xe000
	s_nop 0
	global_load_lds_dwordx4 v[158:159], off
	s_waitcnt lgkmcnt(8)
	s_barrier
	s_waitcnt lgkmcnt(0)
	s_setprio 1
	s_waitcnt lgkmcnt(0)
	v_mfma_f32_16x16x128_f8f6f4 v[142:145], v[2:9], v[186:193], v[142:145]
	v_mfma_f32_16x16x128_f8f6f4 v[138:141], v[10:17], v[186:193], v[138:141]
	v_mfma_f32_16x16x128_f8f6f4 v[134:137], v[2:9], v[194:201], v[134:137]
	v_mfma_f32_16x16x128_f8f6f4 v[130:133], v[10:17], v[194:201], v[130:133]
	v_mfma_f32_16x16x128_f8f6f4 v[110:113], v[2:9], v[202:209], v[110:113]
	v_mfma_f32_16x16x128_f8f6f4 v[106:109], v[10:17], v[202:209], v[106:109]
	v_mfma_f32_16x16x128_f8f6f4 v[102:105], v[2:9], v[210:217], v[102:105]
	v_mfma_f32_16x16x128_f8f6f4 v[98:101], v[10:17], v[210:217], v[98:101]
	s_setprio 0
	s_barrier
	s_mov_b32 m0, s42
	v_lshl_add_u64 v[158:159], s[30:31], 0, v[146:147]
	ds_read_b128 v[220:223], v168
	ds_read_b128 v[224:227], v174
	ds_read_b128 v[228:231], v175
	ds_read_b128 v[232:235], v176
	global_load_lds_dwordx4 v[158:159], off
	v_lshl_add_u64 v[160:161], s[30:31], 0, v[148:149]
	s_mov_b32 m0, s43
	s_nop 0
	global_load_lds_dwordx4 v[160:161], off
	s_barrier
	s_waitcnt lgkmcnt(0)
	s_setprio 1
	s_waitcnt lgkmcnt(0)
	v_mfma_f32_16x16x128_f8f6f4 v[126:129], v[220:227], v[186:193], v[126:129]
	v_mfma_f32_16x16x128_f8f6f4 v[122:125], v[228:235], v[186:193], v[122:125]
	v_mfma_f32_16x16x128_f8f6f4 v[118:121], v[220:227], v[194:201], v[118:121]
	v_mfma_f32_16x16x128_f8f6f4 v[114:117], v[228:235], v[194:201], v[114:117]
	v_mfma_f32_16x16x128_f8f6f4 v[94:97], v[220:227], v[202:209], v[94:97]
	v_mfma_f32_16x16x128_f8f6f4 v[90:93], v[228:235], v[202:209], v[90:93]
	v_mfma_f32_16x16x128_f8f6f4 v[86:89], v[220:227], v[210:217], v[86:89]
	v_mfma_f32_16x16x128_f8f6f4 v[82:85], v[228:235], v[210:217], v[82:85]
	s_setprio 0
	s_mov_b32 m0, s41
	v_lshl_add_u64 v[162:163], s[34:35], 0, v[146:147]
	s_barrier
	ds_read_b128 v[186:189], v184 offset:16384
	ds_read_b128 v[190:193], v184 offset:17408
	ds_read_b128 v[194:197], v184 offset:18432
	ds_read_b128 v[198:201], v184 offset:19456
	ds_read_b128 v[202:205], v184 offset:20480
	ds_read_b128 v[206:209], v184 offset:21504
	ds_read_b128 v[210:213], v184 offset:22528
	ds_read_b128 v[214:217], v184 offset:23552
	global_load_lds_dwordx4 v[162:163], off
	v_lshl_add_u64 v[164:165], s[34:35], 0, v[148:149]
	s_mov_b32 m0, s44
	s_nop 0
	global_load_lds_dwordx4 v[164:165], off
	s_barrier
	s_waitcnt lgkmcnt(0)
	s_setprio 1
	s_waitcnt lgkmcnt(0)
	v_mfma_f32_16x16x128_f8f6f4 v[78:81], v[2:9], v[186:193], v[78:81]
	v_mfma_f32_16x16x128_f8f6f4 v[74:77], v[10:17], v[186:193], v[74:77]
	v_mfma_f32_16x16x128_f8f6f4 v[70:73], v[2:9], v[194:201], v[70:73]
	v_mfma_f32_16x16x128_f8f6f4 v[66:69], v[10:17], v[194:201], v[66:69]
	v_mfma_f32_16x16x128_f8f6f4 v[46:49], v[2:9], v[202:209], v[46:49]
	v_mfma_f32_16x16x128_f8f6f4 v[42:45], v[10:17], v[202:209], v[42:45]
	v_mfma_f32_16x16x128_f8f6f4 v[38:41], v[2:9], v[210:217], v[38:41]
	v_mfma_f32_16x16x128_f8f6f4 v[34:37], v[10:17], v[210:217], v[34:37]
	s_setprio 0
	s_barrier
	s_add_u32 s26, s30, 0x58000
	s_addc_u32 s27, s31, 0
	s_mov_b32 m0, s45
	v_lshl_add_u64 v[2:3], s[26:27], 0, v[146:147]
	global_load_lds_dwordx4 v[2:3], off
	v_lshl_add_u64 v[2:3], s[26:27], 0, v[148:149]
	s_mov_b32 m0, s46
	s_nop 0
	global_load_lds_dwordx4 v[2:3], off
	s_waitcnt vmcnt(6)
	s_barrier
	s_setprio 1
	v_mfma_f32_16x16x128_f8f6f4 v[62:65], v[220:227], v[186:193], v[62:65]
	v_mfma_f32_16x16x128_f8f6f4 v[58:61], v[228:235], v[186:193], v[58:61]
	v_mfma_f32_16x16x128_f8f6f4 v[54:57], v[220:227], v[194:201], v[54:57]
	v_mfma_f32_16x16x128_f8f6f4 v[50:53], v[228:235], v[194:201], v[50:53]
	v_mfma_f32_16x16x128_f8f6f4 v[30:33], v[220:227], v[202:209], v[30:33]
	v_mfma_f32_16x16x128_f8f6f4 v[26:29], v[228:235], v[202:209], v[26:29]
	v_mfma_f32_16x16x128_f8f6f4 v[22:25], v[220:227], v[210:217], v[22:25]
	v_mfma_f32_16x16x128_f8f6f4 v[18:21], v[228:235], v[210:217], v[18:21]
	s_setprio 0
	s_barrier
	ds_read_b128 v[2:5], v169
	ds_read_b128 v[6:9], v177
	ds_read_b128 v[10:13], v178
	ds_read_b128 v[14:17], v179
	s_add_u32 s26, s34, 0x58000
	s_addc_u32 s27, s35, 0
	s_mov_b32 m0, s47
	v_lshl_add_u64 v[220:221], s[26:27], 0, v[146:147]
	ds_read_b128 v[186:189], v184 offset:32768
	ds_read_b128 v[190:193], v184 offset:33792
	ds_read_b128 v[194:197], v184 offset:34816
	ds_read_b128 v[198:201], v184 offset:35840
	ds_read_b128 v[202:205], v184 offset:36864
	ds_read_b128 v[206:209], v184 offset:37888
	ds_read_b128 v[210:213], v184 offset:38912
	ds_read_b128 v[214:217], v184 offset:39936
	global_load_lds_dwordx4 v[220:221], off
	v_lshl_add_u64 v[220:221], s[26:27], 0, v[148:149]
	s_mov_b32 m0, s48
	s_nop 0
	global_load_lds_dwordx4 v[220:221], off
	s_waitcnt lgkmcnt(8)
	s_barrier
	s_waitcnt lgkmcnt(0)
	s_setprio 1
	s_waitcnt lgkmcnt(0)
	v_mfma_f32_16x16x128_f8f6f4 v[142:145], v[2:9], v[186:193], v[142:145]
	v_mfma_f32_16x16x128_f8f6f4 v[138:141], v[10:17], v[186:193], v[138:141]
	v_mfma_f32_16x16x128_f8f6f4 v[134:137], v[2:9], v[194:201], v[134:137]
	v_mfma_f32_16x16x128_f8f6f4 v[130:133], v[10:17], v[194:201], v[130:133]
	v_mfma_f32_16x16x128_f8f6f4 v[110:113], v[2:9], v[202:209], v[110:113]
	v_mfma_f32_16x16x128_f8f6f4 v[106:109], v[10:17], v[202:209], v[106:109]
	v_mfma_f32_16x16x128_f8f6f4 v[102:105], v[2:9], v[210:217], v[102:105]
	v_mfma_f32_16x16x128_f8f6f4 v[98:101], v[10:17], v[210:217], v[98:101]
	s_setprio 0
	s_barrier
	s_mov_b32 m0, s50
	v_lshl_add_u64 v[158:159], v[158:159], 0, s[18:19]
	ds_read_b128 v[220:223], v170
	ds_read_b128 v[224:227], v180
	ds_read_b128 v[228:231], v181
	ds_read_b128 v[232:235], v182
	global_load_lds_dwordx4 v[158:159], off
	v_lshl_add_u64 v[158:159], v[160:161], 0, s[18:19]
	s_mov_b32 m0, s51
	s_nop 0
	global_load_lds_dwordx4 v[158:159], off
	s_barrier
	s_waitcnt lgkmcnt(0)
	s_setprio 1
	s_waitcnt lgkmcnt(0)
	v_mfma_f32_16x16x128_f8f6f4 v[126:129], v[220:227], v[186:193], v[126:129]
	v_mfma_f32_16x16x128_f8f6f4 v[122:125], v[228:235], v[186:193], v[122:125]
	v_mfma_f32_16x16x128_f8f6f4 v[118:121], v[220:227], v[194:201], v[118:121]
	v_mfma_f32_16x16x128_f8f6f4 v[114:117], v[228:235], v[194:201], v[114:117]
	v_mfma_f32_16x16x128_f8f6f4 v[94:97], v[220:227], v[202:209], v[94:97]
	v_mfma_f32_16x16x128_f8f6f4 v[90:93], v[228:235], v[202:209], v[90:93]
	v_mfma_f32_16x16x128_f8f6f4 v[86:89], v[220:227], v[210:217], v[86:89]
	v_mfma_f32_16x16x128_f8f6f4 v[82:85], v[228:235], v[210:217], v[82:85]
	s_setprio 0
	s_mov_b32 m0, s52
	v_lshl_add_u64 v[158:159], v[162:163], 0, s[18:19]
	s_barrier
	ds_read_b128 v[186:189], v184 offset:49152
	ds_read_b128 v[190:193], v184 offset:50176
	ds_read_b128 v[194:197], v184 offset:51200
	ds_read_b128 v[198:201], v184 offset:52224
	ds_read_b128 v[202:205], v184 offset:53248
	ds_read_b128 v[206:209], v184 offset:54272
	ds_read_b128 v[210:213], v184 offset:55296
	ds_read_b128 v[214:217], v184 offset:56320
	global_load_lds_dwordx4 v[158:159], off
	v_lshl_add_u64 v[158:159], v[164:165], 0, s[18:19]
	s_mov_b32 m0, s53
	s_nop 0
	global_load_lds_dwordx4 v[158:159], off
	s_barrier
	s_waitcnt lgkmcnt(0)
	s_setprio 1
	s_waitcnt lgkmcnt(0)
	v_mfma_f32_16x16x128_f8f6f4 v[78:81], v[2:9], v[186:193], v[78:81]
	v_mfma_f32_16x16x128_f8f6f4 v[74:77], v[10:17], v[186:193], v[74:77]
	v_mfma_f32_16x16x128_f8f6f4 v[70:73], v[2:9], v[194:201], v[70:73]
	v_mfma_f32_16x16x128_f8f6f4 v[66:69], v[10:17], v[194:201], v[66:69]
	v_mfma_f32_16x16x128_f8f6f4 v[46:49], v[2:9], v[202:209], v[46:49]
	v_mfma_f32_16x16x128_f8f6f4 v[42:45], v[10:17], v[202:209], v[42:45]
	v_mfma_f32_16x16x128_f8f6f4 v[38:41], v[2:9], v[210:217], v[38:41]
	v_mfma_f32_16x16x128_f8f6f4 v[34:37], v[10:17], v[210:217], v[34:37]
	s_setprio 0
	s_barrier
	s_add_u32 s26, s30, 0x58080
	s_addc_u32 s27, s31, 0
	s_mov_b32 m0, s55
	v_lshl_add_u64 v[2:3], s[26:27], 0, v[146:147]
	global_load_lds_dwordx4 v[2:3], off
	v_lshl_add_u64 v[2:3], s[26:27], 0, v[148:149]
	s_mov_b32 m0, s58
	s_nop 0
	global_load_lds_dwordx4 v[2:3], off
	s_waitcnt vmcnt(6)
	s_barrier
	s_setprio 1
	v_mfma_f32_16x16x128_f8f6f4 v[62:65], v[220:227], v[186:193], v[62:65]
	v_mfma_f32_16x16x128_f8f6f4 v[58:61], v[228:235], v[186:193], v[58:61]
	v_mfma_f32_16x16x128_f8f6f4 v[54:57], v[220:227], v[194:201], v[54:57]
	v_mfma_f32_16x16x128_f8f6f4 v[50:53], v[228:235], v[194:201], v[50:53]
	v_mfma_f32_16x16x128_f8f6f4 v[30:33], v[220:227], v[202:209], v[30:33]
	v_mfma_f32_16x16x128_f8f6f4 v[26:29], v[228:235], v[202:209], v[26:29]
	v_mfma_f32_16x16x128_f8f6f4 v[22:25], v[220:227], v[210:217], v[22:25]
	v_mfma_f32_16x16x128_f8f6f4 v[18:21], v[228:235], v[210:217], v[18:21]
	s_setprio 0
	s_add_i32 s70, s70, 2
	s_add_u32 s68, s68, 0x100
	s_addc_u32 s69, s69, 0
	s_cmp_gt_u32 s70, 19
	s_mov_b64 s[26:27], s[28:29]
	s_barrier
	s_cbranch_scc0 .LBB0_5692
	v_bfe_u32 v160, v0, 4, 1
	v_mul_u32_u24_e32 v160, 24, v160
	v_mov_b32_e32 v161, 0
	v_lshl_add_u32 v6, s67, 8, v166
	v_ashrrev_i32_e32 v7, 31, v6
	v_or_b32_e32 v4, 16, v6
	s_nop 15
	s_nop 15
	v_lshl_add_u64 v[2:3], v[6:7], 2, s[16:17]
	v_ashrrev_i32_e32 v5, 31, v4
	global_load_dword v158, v[2:3], off
	v_lshl_add_u64 v[8:9], v[4:5], 2, s[16:17]
	global_load_dword v159, v[8:9], off
	s_ashr_i32 s0, s66, 31
	s_lshr_b32 s0, s0, 30
	s_add_i32 s0, s66, s0
	s_and_b32 s0, s0, 0xfffffc
	v_lshlrev_b64 v[4:5], 11, v[4:5]
	s_sub_i32 s0, s66, s0
	v_lshl_add_u64 v[14:15], s[14:15], 0, v[4:5]
	v_lshl_or_b32 v4, s0, 8, v183
	v_lshlrev_b64 v[10:11], 11, v[6:7]
	v_ashrrev_i32_e32 v5, 31, v4
	v_lshl_add_u64 v[10:11], s[14:15], 0, v[10:11]
	v_lshlrev_b64 v[16:17], 1, v[4:5]
	v_lshl_add_u64 v[4:5], v[10:11], 0, v[16:17]
	v_lshl_add_u64 v[10:11], v[14:15], 0, v[16:17]
	v_or_b32_e32 v8, 32, v6
	v_ashrrev_i32_e32 v9, 31, v8
	v_lshl_add_u64 v[12:13], v[8:9], 2, s[16:17]
	v_or_b32_e32 v6, 48, v6
	v_ashrrev_i32_e32 v7, 31, v6
	v_lshlrev_b64 v[8:9], 11, v[8:9]
	v_lshlrev_b64 v[6:7], 11, v[6:7]
	v_lshl_add_u64 v[8:9], s[14:15], 0, v[8:9]
	v_lshl_add_u64 v[6:7], s[14:15], 0, v[6:7]
	v_lshl_add_u64 v[8:9], v[8:9], 0, v[16:17]
	v_lshl_add_u64 v[6:7], v[6:7], 0, v[16:17]
	s_mov_b32 s67, s64
	s_mov_b64 s[28:29], s[10:11]
	s_mov_b64 s[26:27], s[8:9]
	s_mov_b32 s66, s65
	s_waitcnt vmcnt(0)
	v_mul_f32_e32 v14, 0x3b800000, v158
	v_pk_mul_f32 v[142:143], v[142:143], v[14:15] op_sel_hi:[1,0]
	v_pk_mul_f32 v[144:145], v[144:145], v[14:15] op_sel_hi:[1,0]
	v_pk_mul_f32 v[138:139], v[138:139], v[14:15] op_sel_hi:[1,0]
	v_pk_mul_f32 v[140:141], v[140:141], v[14:15] op_sel_hi:[1,0]
	v_pk_mul_f32 v[126:127], v[126:127], v[14:15] op_sel_hi:[1,0]
	v_pk_mul_f32 v[128:129], v[128:129], v[14:15] op_sel_hi:[1,0]
	v_pk_mul_f32 v[122:123], v[122:123], v[14:15] op_sel_hi:[1,0]
	v_pk_mul_f32 v[14:15], v[124:125], v[14:15] op_sel_hi:[1,0]
	v_mul_f32_e32 v124, 0x3b800000, v159
	v_cvt_pk_bf16_f32 v126, v126, v127
	v_cvt_pk_bf16_f32 v127, v128, v129
	v_cvt_pk_bf16_f32 v122, v122, v123
	v_cvt_pk_bf16_f32 v123, v14, v15
	v_pk_mul_f32 v[14:15], v[134:135], v[124:125] op_sel_hi:[1,0]
	v_pk_mul_f32 v[128:129], v[136:137], v[124:125] op_sel_hi:[1,0]
	v_cvt_pk_bf16_f32 v142, v142, v143
	v_cvt_pk_bf16_f32 v143, v144, v145
	v_pk_mul_f32 v[130:131], v[130:131], v[124:125] op_sel_hi:[1,0]
	v_pk_mul_f32 v[132:133], v[132:133], v[124:125] op_sel_hi:[1,0]
	v_pk_mul_f32 v[118:119], v[118:119], v[124:125] op_sel_hi:[1,0]
	v_pk_mul_f32 v[120:121], v[120:121], v[124:125] op_sel_hi:[1,0]
	v_pk_mul_f32 v[114:115], v[114:115], v[124:125] op_sel_hi:[1,0]
	v_pk_mul_f32 v[116:117], v[116:117], v[124:125] op_sel_hi:[1,0]
	v_cvt_pk_bf16_f32 v14, v14, v15
	v_cvt_pk_bf16_f32 v15, v128, v129
	v_cvt_pk_bf16_f32 v138, v138, v139
	v_cvt_pk_bf16_f32 v139, v140, v141
	v_mov_b32_e32 v188, v142
	v_mov_b32_e32 v189, v143
	v_mov_b32_e32 v190, v138
	v_mov_b32_e32 v191, v139
	v_lshl_add_u64 v[162:163], v[4:5], 0, v[160:161]
	s_nop 0
	v_permlane16_swap_b32 v188, v190
	v_permlane16_swap_b32 v189, v191
	global_store_dwordx4 v[162:163], v[188:191], off
	v_mov_b32_e32 v192, v126
	v_mov_b32_e32 v193, v127
	v_mov_b32_e32 v194, v122
	v_mov_b32_e32 v195, v123
	v_lshl_add_u64 v[162:163], v[4:5], 0, v[160:161]
	s_nop 0
	v_permlane16_swap_b32 v192, v194
	v_permlane16_swap_b32 v193, v195
	global_store_dwordx4 v[162:163], v[192:195], off offset:256
	v_cvt_pk_bf16_f32 v122, v130, v131
	v_cvt_pk_bf16_f32 v123, v132, v133
	v_cvt_pk_bf16_f32 v118, v118, v119
	v_cvt_pk_bf16_f32 v119, v120, v121
	v_cvt_pk_bf16_f32 v114, v114, v115
	v_cvt_pk_bf16_f32 v115, v116, v117
	v_mov_b32_e32 v196, v14
	v_mov_b32_e32 v197, v15
	v_mov_b32_e32 v198, v122
	v_mov_b32_e32 v199, v123
	v_lshl_add_u64 v[162:163], v[10:11], 0, v[160:161]
	s_nop 0
	v_permlane16_swap_b32 v196, v198
	v_permlane16_swap_b32 v197, v199
	global_store_dwordx4 v[162:163], v[196:199], off
	v_mov_b32_e32 v200, v118
	v_mov_b32_e32 v201, v119
	v_mov_b32_e32 v202, v114
	v_mov_b32_e32 v203, v115
	v_lshl_add_u64 v[162:163], v[10:11], 0, v[160:161]
	s_nop 0
	v_permlane16_swap_b32 v200, v202
	v_permlane16_swap_b32 v201, v203
	global_store_dwordx4 v[162:163], v[200:203], off offset:256
	global_load_dword v10, v[12:13], off
	s_nop 0
	global_load_dword v11, v[2:3], off offset:192
	s_waitcnt vmcnt(0)
	v_mul_f32_e32 v10, 0x3b800000, v10
	v_mul_f32_e32 v12, 0x3b800000, v11
	v_pk_mul_f32 v[14:15], v[110:111], v[10:11] op_sel_hi:[1,0]
	v_pk_mul_f32 v[16:17], v[112:113], v[10:11] op_sel_hi:[1,0]
	v_pk_mul_f32 v[106:107], v[106:107], v[10:11] op_sel_hi:[1,0]
	v_pk_mul_f32 v[108:109], v[108:109], v[10:11] op_sel_hi:[1,0]
	v_pk_mul_f32 v[94:95], v[94:95], v[10:11] op_sel_hi:[1,0]
	v_pk_mul_f32 v[96:97], v[96:97], v[10:11] op_sel_hi:[1,0]
	v_pk_mul_f32 v[90:91], v[90:91], v[10:11] op_sel_hi:[1,0]
	v_pk_mul_f32 v[10:11], v[92:93], v[10:11] op_sel_hi:[1,0]
	v_pk_mul_f32 v[92:93], v[102:103], v[12:13] op_sel_hi:[1,0]
	v_pk_mul_f32 v[102:103], v[104:105], v[12:13] op_sel_hi:[1,0]
	v_pk_mul_f32 v[98:99], v[98:99], v[12:13] op_sel_hi:[1,0]
	v_pk_mul_f32 v[100:101], v[100:101], v[12:13] op_sel_hi:[1,0]
	v_pk_mul_f32 v[86:87], v[86:87], v[12:13] op_sel_hi:[1,0]
	v_pk_mul_f32 v[88:89], v[88:89], v[12:13] op_sel_hi:[1,0]
	v_pk_mul_f32 v[82:83], v[82:83], v[12:13] op_sel_hi:[1,0]
	v_pk_mul_f32 v[12:13], v[84:85], v[12:13] op_sel_hi:[1,0]
	v_cvt_pk_bf16_f32 v14, v14, v15
	v_cvt_pk_bf16_f32 v15, v16, v17
	v_cvt_pk_bf16_f32 v16, v106, v107
	v_cvt_pk_bf16_f32 v17, v108, v109
	v_cvt_pk_bf16_f32 v84, v94, v95
	v_cvt_pk_bf16_f32 v85, v96, v97
	v_cvt_pk_bf16_f32 v90, v90, v91
	v_cvt_pk_bf16_f32 v91, v10, v11
	v_cvt_pk_bf16_f32 v10, v92, v93
	v_cvt_pk_bf16_f32 v11, v102, v103
	v_cvt_pk_bf16_f32 v92, v98, v99
	v_cvt_pk_bf16_f32 v93, v100, v101
	v_cvt_pk_bf16_f32 v86, v86, v87
	v_cvt_pk_bf16_f32 v87, v88, v89
	v_cvt_pk_bf16_f32 v82, v82, v83
	v_cvt_pk_bf16_f32 v83, v12, v13
	v_mov_b32_e32 v204, v14
	v_mov_b32_e32 v205, v15
	v_mov_b32_e32 v206, v16
	v_mov_b32_e32 v207, v17
	v_lshl_add_u64 v[162:163], v[8:9], 0, v[160:161]
	s_nop 0
	v_permlane16_swap_b32 v204, v206
	v_permlane16_swap_b32 v205, v207
	global_store_dwordx4 v[162:163], v[204:207], off
	v_mov_b32_e32 v208, v84
	v_mov_b32_e32 v209, v85
	v_mov_b32_e32 v210, v90
	v_mov_b32_e32 v211, v91
	v_lshl_add_u64 v[162:163], v[8:9], 0, v[160:161]
	s_nop 0
	v_permlane16_swap_b32 v208, v210
	v_permlane16_swap_b32 v209, v211
	global_store_dwordx4 v[162:163], v[208:211], off offset:256
	v_mov_b32_e32 v212, v10
	v_mov_b32_e32 v213, v11
	v_mov_b32_e32 v214, v92
	v_mov_b32_e32 v215, v93
	v_lshl_add_u64 v[162:163], v[6:7], 0, v[160:161]
	s_nop 0
	v_permlane16_swap_b32 v212, v214
	v_permlane16_swap_b32 v213, v215
	global_store_dwordx4 v[162:163], v[212:215], off
	v_mov_b32_e32 v220, v86
	v_mov_b32_e32 v221, v87
	v_mov_b32_e32 v222, v82
	v_mov_b32_e32 v223, v83
	v_lshl_add_u64 v[162:163], v[6:7], 0, v[160:161]
	s_nop 0
	v_permlane16_swap_b32 v220, v222
	v_permlane16_swap_b32 v221, v223
	global_store_dwordx4 v[162:163], v[220:223], off offset:256
	global_load_dword v14, v[2:3], off offset:512
	global_load_dword v15, v[2:3], off offset:576
	v_add_co_u32_e32 v8, vcc, s60, v4
	v_lshl_add_u64 v[6:7], v[4:5], 0, s[20:21]
	s_nop 0
	v_addc_co_u32_e32 v9, vcc, 0, v5, vcc
	v_add_co_u32_e32 v12, vcc, s61, v4
	v_lshl_add_u64 v[10:11], v[4:5], 0, s[22:23]
	s_nop 0
	v_addc_co_u32_e32 v13, vcc, 0, v5, vcc
	s_and_b64 vcc, exec, s[6:7]
	s_waitcnt vmcnt(0)
	v_mul_f32_e32 v14, 0x3b800000, v14
	v_mul_f32_e32 v16, 0x3b800000, v15
	v_pk_mul_f32 v[78:79], v[78:79], v[14:15] op_sel_hi:[1,0]
	v_pk_mul_f32 v[80:81], v[80:81], v[14:15] op_sel_hi:[1,0]
	v_pk_mul_f32 v[74:75], v[74:75], v[14:15] op_sel_hi:[1,0]
	v_pk_mul_f32 v[76:77], v[76:77], v[14:15] op_sel_hi:[1,0]
	v_pk_mul_f32 v[62:63], v[62:63], v[14:15] op_sel_hi:[1,0]
	v_pk_mul_f32 v[64:65], v[64:65], v[14:15] op_sel_hi:[1,0]
	v_pk_mul_f32 v[58:59], v[58:59], v[14:15] op_sel_hi:[1,0]
	v_pk_mul_f32 v[14:15], v[60:61], v[14:15] op_sel_hi:[1,0]
	v_pk_mul_f32 v[60:61], v[70:71], v[16:17] op_sel_hi:[1,0]
	v_pk_mul_f32 v[70:71], v[72:73], v[16:17] op_sel_hi:[1,0]
	v_pk_mul_f32 v[66:67], v[66:67], v[16:17] op_sel_hi:[1,0]
	v_pk_mul_f32 v[68:69], v[68:69], v[16:17] op_sel_hi:[1,0]
	v_pk_mul_f32 v[54:55], v[54:55], v[16:17] op_sel_hi:[1,0]
	v_pk_mul_f32 v[56:57], v[56:57], v[16:17] op_sel_hi:[1,0]
	v_pk_mul_f32 v[50:51], v[50:51], v[16:17] op_sel_hi:[1,0]
	v_pk_mul_f32 v[16:17], v[52:53], v[16:17] op_sel_hi:[1,0]
	v_cvt_pk_bf16_f32 v52, v78, v79
	v_cvt_pk_bf16_f32 v53, v80, v81
	v_cvt_pk_bf16_f32 v72, v74, v75
	v_cvt_pk_bf16_f32 v73, v76, v77
	v_cvt_pk_bf16_f32 v62, v62, v63
	v_cvt_pk_bf16_f32 v63, v64, v65
	v_cvt_pk_bf16_f32 v58, v58, v59
	v_cvt_pk_bf16_f32 v59, v14, v15
	v_cvt_pk_bf16_f32 v14, v60, v61
	v_cvt_pk_bf16_f32 v15, v70, v71
	v_cvt_pk_bf16_f32 v60, v66, v67
	v_cvt_pk_bf16_f32 v61, v68, v69
	v_cvt_pk_bf16_f32 v54, v54, v55
	v_cvt_pk_bf16_f32 v55, v56, v57
	v_cvt_pk_bf16_f32 v50, v50, v51
	v_cvt_pk_bf16_f32 v51, v16, v17
	global_store_dwordx2 v[8:9], v[52:53], off
	global_store_dwordx2 v[6:7], v[72:73], off offset:32
	v_mov_b32_e32 v224, v62
	v_mov_b32_e32 v225, v63
	v_mov_b32_e32 v226, v58
	v_mov_b32_e32 v227, v59
	v_lshl_add_u64 v[162:163], v[6:7], 0, v[160:161]
	s_nop 0
	v_permlane16_swap_b32 v224, v226
	v_permlane16_swap_b32 v225, v227
	global_store_dwordx4 v[162:163], v[224:227], off offset:256
	global_store_dwordx2 v[12:13], v[14:15], off
	global_store_dwordx2 v[10:11], v[60:61], off offset:32
	v_mov_b32_e32 v228, v54
	v_mov_b32_e32 v229, v55
	v_mov_b32_e32 v230, v50
	v_mov_b32_e32 v231, v51
	v_lshl_add_u64 v[162:163], v[10:11], 0, v[160:161]
	s_nop 0
	v_permlane16_swap_b32 v228, v230
	v_permlane16_swap_b32 v229, v231
	global_store_dwordx4 v[162:163], v[228:231], off offset:256
	global_load_dword v10, v[2:3], off offset:640
	s_nop 0
	global_load_dword v11, v[2:3], off offset:704
	v_add_co_u32_e64 v6, s[6:7], s62, v4
	v_lshl_add_u64 v[2:3], v[4:5], 0, s[24:25]
	s_nop 0
	v_addc_co_u32_e64 v7, s[6:7], 0, v5, s[6:7]
	v_lshl_add_u64 v[8:9], v[4:5], 0, s[12:13]
	v_add_co_u32_e64 v4, s[6:7], s63, v4
	s_waitcnt vmcnt(0)
	v_mul_f32_e32 v10, 0x3b800000, v10
	v_mul_f32_e32 v12, 0x3b800000, v11
	v_pk_mul_f32 v[14:15], v[46:47], v[10:11] op_sel_hi:[1,0]
	v_pk_mul_f32 v[16:17], v[48:49], v[10:11] op_sel_hi:[1,0]
	v_pk_mul_f32 v[42:43], v[42:43], v[10:11] op_sel_hi:[1,0]
	v_pk_mul_f32 v[44:45], v[44:45], v[10:11] op_sel_hi:[1,0]
	v_pk_mul_f32 v[30:31], v[30:31], v[10:11] op_sel_hi:[1,0]
	v_pk_mul_f32 v[32:33], v[32:33], v[10:11] op_sel_hi:[1,0]
	v_pk_mul_f32 v[26:27], v[26:27], v[10:11] op_sel_hi:[1,0]
	v_pk_mul_f32 v[10:11], v[28:29], v[10:11] op_sel_hi:[1,0]
	v_pk_mul_f32 v[28:29], v[38:39], v[12:13] op_sel_hi:[1,0]
	v_pk_mul_f32 v[38:39], v[40:41], v[12:13] op_sel_hi:[1,0]
	v_pk_mul_f32 v[34:35], v[34:35], v[12:13] op_sel_hi:[1,0]
	v_pk_mul_f32 v[36:37], v[36:37], v[12:13] op_sel_hi:[1,0]
	v_pk_mul_f32 v[22:23], v[22:23], v[12:13] op_sel_hi:[1,0]
	v_pk_mul_f32 v[24:25], v[24:25], v[12:13] op_sel_hi:[1,0]
	v_pk_mul_f32 v[18:19], v[18:19], v[12:13] op_sel_hi:[1,0]
	v_pk_mul_f32 v[12:13], v[20:21], v[12:13] op_sel_hi:[1,0]
	v_cvt_pk_bf16_f32 v14, v14, v15
	v_cvt_pk_bf16_f32 v15, v16, v17
	v_addc_co_u32_e64 v5, s[6:7], 0, v5, s[6:7]
	v_cvt_pk_bf16_f32 v16, v42, v43
	v_cvt_pk_bf16_f32 v17, v44, v45
	v_cvt_pk_bf16_f32 v20, v30, v31
	v_cvt_pk_bf16_f32 v21, v32, v33
	v_cvt_pk_bf16_f32 v26, v26, v27
	v_cvt_pk_bf16_f32 v27, v10, v11
	v_cvt_pk_bf16_f32 v10, v28, v29
	v_cvt_pk_bf16_f32 v11, v38, v39
	v_cvt_pk_bf16_f32 v28, v34, v35
	v_cvt_pk_bf16_f32 v29, v36, v37
	v_cvt_pk_bf16_f32 v22, v22, v23
	v_cvt_pk_bf16_f32 v23, v24, v25
	v_cvt_pk_bf16_f32 v18, v18, v19
	v_cvt_pk_bf16_f32 v19, v12, v13
	global_store_dwordx2 v[6:7], v[14:15], off
	global_store_dwordx2 v[2:3], v[16:17], off offset:32
	v_mov_b32_e32 v232, v20
	v_mov_b32_e32 v233, v21
	v_mov_b32_e32 v234, v26
	v_mov_b32_e32 v235, v27
	v_lshl_add_u64 v[162:163], v[2:3], 0, v[160:161]
	s_nop 0
	v_permlane16_swap_b32 v232, v234
	v_permlane16_swap_b32 v233, v235
	global_store_dwordx4 v[162:163], v[232:235], off offset:256
	global_store_dwordx2 v[4:5], v[10:11], off
	global_store_dwordx2 v[8:9], v[28:29], off offset:32
	v_mov_b32_e32 v188, v22
	v_mov_b32_e32 v189, v23
	v_mov_b32_e32 v190, v18
	v_mov_b32_e32 v191, v19
	v_lshl_add_u64 v[162:163], v[8:9], 0, v[160:161]
	s_nop 0
	v_permlane16_swap_b32 v188, v190
	v_permlane16_swap_b32 v189, v191
	global_store_dwordx4 v[162:163], v[188:191], off offset:256
	s_cbranch_vccz .LBB0_5681
	s_waitcnt vmcnt(0)
	s_cmpk_gt_u32 s3, 0xff
	s_cbranch_scc1 .LBB0_5696
	s_barrier
